# K-loop load segments without VALU (saddr LDS-DMA with scalar bases, hoisted LDS read base) on top of the aligned MFMA blocks
# speedup vs baseline: 1.0063x; 1.0028x over previous
; #define PG8_STAGEA(bufoff, gbase, voff) PG8_STAGE_X(bufoff, gbase, voff, AUXA)
; #define PG8_STR(x) PG8_STR2(x)
;     ...
;         const bool has_next = S.next(ui + 1, nxt);
;         const char* nA = has_next ? (const char*)g.A + (size_t)nxt.pm * tstepA : cA; const char* nB = has_next ? (const char*)g.Bt + (size_t)nxt.pn * tstepB : cB;
;         int t0 = 0;
;         if constexpr (SP2 && GEMM_RELAX == 1) { if (ui > 0) {
;             const char* a1 = cA + kstepA; const char* a2 = cA + 2 * kstepA; const char* b2 = cB + 2 * kstepB; const char* a3 = a2 + kstepA; const char* b3 = b2 + kstepB;
;             PG8_LDB(B0, 0, 0); PG8_LDB(B1, 0, 1); PG8_SCHED; PG8_LDA(At, 0, 0); PG8_STAGEA(PG8_SA(1, 1), a1 + hstepA, voffA);
;             PG8_WAIT_V(24); PG8_WAIT_L(0); PG8_BAR; PG8_MMA(0, 0, At, B0); PG8_MMA(0, 1, At, B1); PG8_BAR; PG8_SCHED;
;             PG8_LDA(At, 0, 1); PG8_STAGEB(PG8_SB(0, 0), b2, voffB); PG8_STAGEB(PG8_SB(0, 1), b2 + hstepB, voffB); PG8_STAGEA(PG8_SA(0, 0), a2, voffA);
;             PG8_WAIT_V(24); PG8_WAIT_L(0); PG8_BAR; PG8_MMA(1, 0, At, B0); PG8_MMA(1, 1, At, B1); PG8_BAR; PG8_SCHED;
;             PG8_LDB(B0, 1, 0); PG8_LDB(B1, 1, 1); PG8_SCHED; PG8_LDA(At, 1, 0); PG8_STAGEA(PG8_SA(0, 1), a2 + hstepA, voffA);
;             PG8_WAIT_V(8); PG8_WAIT_L(0); PG8_BAR; PG8_MMA(0, 0, At, B0); PG8_MMA(0, 1, At, B1); PG8_BAR; PG8_SCHED;
;             PG8_LDA(At, 1, 1); PG8_STAGEB(PG8_SB(1, 0), b3, voffB); PG8_STAGEB(PG8_SB(1, 1), b3 + hstepB, voffB); PG8_STAGEA(PG8_SA(1, 0), a3, voffA);
;             PG8_WAIT_V(8); PG8_WAIT_L(0); PG8_BAR; PG8_MMA(1, 0, At, B0); PG8_MMA(1, 1, At, B1); PG8_BAR; PG8_SCHED;
;             t0 = 2; } }
;     ...
;         asm volatile(".p2align " PG8_STR(GEMM_LOOP_ALIGN) ::: "memory");
;     ...
;         for (int t = t0; t < nt; t += 2) {
;             const bool last = (t == nt - 2);
;             const char* a1 = cA + (size_t)(t + 1) * kstepA;
;             const char* a2 = last ? nA : cA + (size_t)(t + 2) * kstepA; const char* b2 = last ? nB : cB + (size_t)(t + 2) * kstepB;
;             const char* a3 = a2 + kstepA; const char* b3 = b2 + kstepB;
;             if (last && has_next) S.a_ready(nxt);
;             if constexpr (SP2) {
;             PG8_LDB(B0, 0, 0); PG8_LDB(B1, 0, 1); PG8_SCHED; PG8_LDA(At, 0, 0); PG8_STAGEA(PG8_SA(1, 1), a1 + hstepA, voffA);
;     ...
;             const int relax = __builtin_amdgcn_readfirstlane((t == 0 && ui > 0) ? 1 : 0);
.LBB0_128:
	s_ashr_i32 s37, s36, 31
	s_lshl_b64 s[4:5], s[36:37], 21
	s_add_u32 s38, s56, s4
	s_addc_u32 s39, s57, s5
	s_and_b64 s[4:5], s[6:7], exec
	s_cselect_b32 s4, s39, s1
	s_cselect_b32 s5, s38, s0
	s_ashr_i32 s27, s26, 31
	s_lshl_b64 s[8:9], s[26:27], 21
	s_add_u32 s40, s43, s8
	s_addc_u32 s41, s50, s9
	s_and_b64 s[8:9], s[6:7], exec
	s_cselect_b32 s16, s41, s11
	s_cselect_b32 s17, s40, s10
	s_add_u32 s8, s0, 0x100080
	s_addc_u32 s9, s1, 0
	s_add_u32 s0, s10, 0x100
	s_addc_u32 s1, s11, 0
	s_mov_b32 s27, -2
	s_add_u32 s10, s8, 0xfff00080
	s_addc_u32 s11, s9, -1
	s_add_i32 s18, 0, 0x10000
	s_cmp_eq_u32 s27, 60
	s_cselect_b32 s15, s4, s11
	s_cselect_b32 s14, s5, s10
	v_add_u32_e32 v16, s18, v167
	s_cselect_b32 s11, s16, s1
	s_cselect_b32 s10, s17, s0
	s_add_i32 s20, 0, 0x14000
	s_waitcnt lgkmcnt(0)
	ds_read_b128 v[130:133], v16
	ds_read_b128 v[134:137], v16 offset:1024
	ds_read_b128 v[152:155], v16 offset:2048
	ds_read_b128 v[156:159], v16 offset:3072
	v_add_u32_e32 v16, s20, v167
	ds_read_b128 v[160:163], v16
	ds_read_b128 v[174:177], v16 offset:1024
	ds_read_b128 v[178:181], v16 offset:2048
	ds_read_b128 v[182:185], v16 offset:3072
	v_lshl_add_u64 v[164:165], s[8:9], 0, v[148:149]
	s_add_i32 m0, s51, 0xc000
	ds_read_b128 v[186:189], v172
	ds_read_b128 v[190:193], v172 offset:1024
	ds_read_b128 v[194:197], v172 offset:2048
	ds_read_b128 v[198:201], v172 offset:3072
	ds_read_b128 v[202:205], v172 offset:4096
	ds_read_b128 v[206:209], v172 offset:5120
	ds_read_b128 v[210:213], v172 offset:6144
	ds_read_b128 v[214:217], v172 offset:7168
	global_load_lds_dwordx4 v[164:165], off
	v_lshl_add_u64 v[164:165], s[8:9], 0, v[150:151]
	s_add_i32 m0, s51, 0xe000
	s_nop 0
	global_load_lds_dwordx4 v[164:165], off
	s_waitcnt vmcnt(8)
	s_waitcnt lgkmcnt(0)
	s_setprio 1
	s_barrier
	v_mfma_f32_16x16x32_bf16 v[126:129], v[130:133], v[186:189], 0
	v_mfma_f32_16x16x32_bf16 v[122:125], v[152:155], v[186:189], 0
	v_mfma_f32_16x16x32_bf16 v[110:113], v[130:133], v[194:197], 0
	v_mfma_f32_16x16x32_bf16 v[106:109], v[152:155], v[194:197], 0
	v_mfma_f32_16x16x32_bf16 v[94:97], v[130:133], v[202:205], 0
	v_mfma_f32_16x16x32_bf16 v[90:93], v[152:155], v[202:205], 0
	v_mfma_f32_16x16x32_bf16 v[78:81], v[130:133], v[210:213], 0
	v_mfma_f32_16x16x32_bf16 v[74:77], v[152:155], v[210:213], 0
	v_mfma_f32_16x16x32_bf16 v[126:129], v[134:137], v[190:193], v[126:129]
	v_mfma_f32_16x16x32_bf16 v[122:125], v[156:159], v[190:193], v[122:125]
	v_mfma_f32_16x16x32_bf16 v[110:113], v[134:137], v[198:201], v[110:113]
	v_mfma_f32_16x16x32_bf16 v[106:109], v[156:159], v[198:201], v[106:109]
	v_mfma_f32_16x16x32_bf16 v[94:97], v[134:137], v[206:209], v[94:97]
	v_mfma_f32_16x16x32_bf16 v[90:93], v[156:159], v[206:209], v[90:93]
	v_mfma_f32_16x16x32_bf16 v[78:81], v[134:137], v[214:217], v[78:81]
	v_mfma_f32_16x16x32_bf16 v[74:77], v[156:159], v[214:217], v[74:77]
	v_mfma_f32_16x16x32_bf16 v[118:121], v[160:163], v[186:189], 0
	v_mfma_f32_16x16x32_bf16 v[114:117], v[178:181], v[186:189], 0
	v_mfma_f32_16x16x32_bf16 v[102:105], v[160:163], v[194:197], 0
	v_mfma_f32_16x16x32_bf16 v[98:101], v[178:181], v[194:197], 0
	v_mfma_f32_16x16x32_bf16 v[86:89], v[160:163], v[202:205], 0
	v_mfma_f32_16x16x32_bf16 v[82:85], v[178:181], v[202:205], 0
	v_mfma_f32_16x16x32_bf16 v[70:73], v[160:163], v[210:213], 0
	v_mfma_f32_16x16x32_bf16 v[66:69], v[178:181], v[210:213], 0
	v_mfma_f32_16x16x32_bf16 v[118:121], v[174:177], v[190:193], v[118:121]
	v_mfma_f32_16x16x32_bf16 v[114:117], v[182:185], v[190:193], v[114:117]
	v_mfma_f32_16x16x32_bf16 v[102:105], v[174:177], v[198:201], v[102:105]
	v_mfma_f32_16x16x32_bf16 v[98:101], v[182:185], v[198:201], v[98:101]
	v_mfma_f32_16x16x32_bf16 v[86:89], v[174:177], v[206:209], v[86:89]
	v_mfma_f32_16x16x32_bf16 v[82:85], v[182:185], v[206:209], v[82:85]
	v_mfma_f32_16x16x32_bf16 v[70:73], v[174:177], v[214:217], v[70:73]
	v_mfma_f32_16x16x32_bf16 v[66:69], v[182:185], v[214:217], v[66:69]
	s_barrier
	s_setprio 0
	s_add_i32 s18, s18, s42
	v_lshl_add_u64 v[164:165], s[10:11], 0, v[142:143]
	s_mov_b32 m0, s18
	ds_read_b128 v[186:189], v172 offset:16384
	ds_read_b128 v[190:193], v172 offset:17408
	ds_read_b128 v[194:197], v172 offset:18432
	ds_read_b128 v[198:201], v172 offset:19456
	ds_read_b128 v[202:205], v172 offset:20480
	ds_read_b128 v[206:209], v172 offset:21504
	ds_read_b128 v[210:213], v172 offset:22528
	ds_read_b128 v[214:217], v172 offset:23552
	global_load_lds_dwordx4 v[164:165], off
	s_add_i32 m0, s18, 0x2000
	s_add_u32 s18, s10, 0x100000
	v_lshl_add_u64 v[218:219], s[10:11], 0, v[138:139]
	s_addc_u32 s19, s11, 0
	s_add_i32 s20, s20, s42
	global_load_lds_dwordx4 v[218:219], off
	v_lshl_add_u64 v[220:221], s[18:19], 0, v[142:143]
	s_mov_b32 m0, s20
	v_lshl_add_u64 v[222:223], s[14:15], 0, v[140:141]
	global_load_lds_dwordx4 v[220:221], off
	v_lshl_add_u64 v[220:221], s[18:19], 0, v[138:139]
	s_add_i32 m0, s20, 0x2000
	s_nop 0
	global_load_lds_dwordx4 v[220:221], off
	v_lshl_add_u64 v[220:221], s[14:15], 0, v[144:145]
	s_mov_b32 m0, s51
	s_nop 0
	global_load_lds_dwordx4 v[220:221], off
	s_mov_b32 m0, s68
	s_nop 0
	global_load_lds_dwordx4 v[222:223], off
	s_waitcnt vmcnt(8)
	s_waitcnt lgkmcnt(0)
	s_nop 0
	s_nop 0
	s_setprio 1
	s_barrier
; #define PG8_STAGEA(bufoff, gbase, voff) PG8_STAGE_X(bufoff, gbase, voff, AUXA)
; #define PG8_STAGEB(bufoff, gbase, voff) PG8_STAGE_X(bufoff, gbase, voff, AUXB)
; #define PG8_LDA(dst, b, h) do { _Pragma("unroll") for (int m = 0; m < 4; ++m) _Pragma("unroll") for (int k = 0; k < 2; ++k) dst[m][k] = *(const PG8_LAS bf16x8*)(lds + PG8_SA(b, h) + aoff + m * 2048 + k * 1024); } while (0)
; #define PG8_LDB(dst, b, h) do { _Pragma("unroll") for (int n = 0; n < 2; ++n) _Pragma("unroll") for (int k = 0; k < 2; ++k) dst[n][k] = *(const PG8_LAS bf16x8*)(lds + PG8_SB(b, h) + boff + n * 2048 + k * 1024); } while (0)
; #define PG8_MMA(ai, bj, At, Bt) do { if (GEMM_PRIO_MODE == 0) __builtin_amdgcn_s_setprio(1); PG8_MMA_LOOPS \
;         acc[ai][bj][m][n] = __builtin_amdgcn_mfma_f32_16x16x32_bf16(Bt[n][k], At[m][k], acc[ai][bj][m][n], 0, 0, 0); if (GEMM_PRIO_MODE == 0) __builtin_amdgcn_s_setprio(0); } while (0)
; #define PG8_WAIT_V(n) asm volatile("s_waitcnt vmcnt(" #n ")" ::: "memory")
; #define PG8_WAIT_VR(n, nr, flag) asm volatile("s_cmp_eq_u32 %0, 0\n\ts_cbranch_scc1 .Lpg8s%=\n\ts_waitcnt vmcnt(" #nr ")\n\ts_branch .Lpg8d%=\n.Lpg8s%=:\n\ts_waitcnt vmcnt(" #n ")\n.Lpg8d%=:" :: "s"(flag) : "memory", "scc")
; #define PG8_WAIT_L(n) asm volatile("s_waitcnt lgkmcnt(" #n ")" ::: "memory")
; #define PG8_BAR __builtin_amdgcn_s_barrier()
; #define PG8_SCHED __builtin_amdgcn_sched_barrier(0)
;     ...
;             PG8_LDA(At, 0, 1); PG8_STAGEB(PG8_SB(0, 0), b2, voffB); PG8_STAGEB(PG8_SB(0, 1), b2 + hstepB, voffB); PG8_STAGEA(PG8_SA(0, 0), a2, voffA);
;     ...
;             PG8_WAIT_VR(8, 24, relax); PG8_WAIT_L(0); PG8_BAR; PG8_MMA(1, 0, At, B0); PG8_MMA(1, 1, At, B1); PG8_BAR; PG8_SCHED;
;     ...
;             PG8_WAIT_V(8); PG8_WAIT_L(0); PG8_BAR; PG8_MMA(1, 0, At, B0); PG8_MMA(1, 1, At, B1); PG8_BAR; PG8_SCHED;
;     ...
;             PG8_LDB(B0, 1, 0); PG8_LDB(B1, 1, 1); PG8_SCHED; PG8_LDA(At, 1, 0); PG8_STAGEA(PG8_SA(0, 1), a2 + hstepA, voffA);
;             PG8_WAIT_V(8); PG8_WAIT_L(0); PG8_BAR; PG8_MMA(0, 0, At, B0); PG8_MMA(0, 1, At, B1); PG8_BAR; PG8_SCHED;
	v_mfma_f32_16x16x32_bf16 v[62:65], v[130:133], v[186:189], 0
	v_mfma_f32_16x16x32_bf16 v[58:61], v[152:155], v[186:189], 0
	v_mfma_f32_16x16x32_bf16 v[46:49], v[130:133], v[194:197], 0
	v_mfma_f32_16x16x32_bf16 v[42:45], v[152:155], v[194:197], 0
	v_mfma_f32_16x16x32_bf16 v[30:33], v[130:133], v[202:205], 0
	v_mfma_f32_16x16x32_bf16 v[26:29], v[152:155], v[202:205], 0
	v_mfma_f32_16x16x32_bf16 v[12:15], v[130:133], v[210:213], 0
	v_mfma_f32_16x16x32_bf16 v[8:11], v[152:155], v[210:213], 0
	v_mfma_f32_16x16x32_bf16 v[62:65], v[134:137], v[190:193], v[62:65]
	v_mfma_f32_16x16x32_bf16 v[58:61], v[156:159], v[190:193], v[58:61]
	v_mfma_f32_16x16x32_bf16 v[46:49], v[134:137], v[198:201], v[46:49]
	v_mfma_f32_16x16x32_bf16 v[42:45], v[156:159], v[198:201], v[42:45]
	v_mfma_f32_16x16x32_bf16 v[30:33], v[134:137], v[206:209], v[30:33]
	v_mfma_f32_16x16x32_bf16 v[26:29], v[156:159], v[206:209], v[26:29]
	v_mfma_f32_16x16x32_bf16 v[12:15], v[134:137], v[214:217], v[12:15]
	v_mfma_f32_16x16x32_bf16 v[8:11], v[156:159], v[214:217], v[8:11]
	v_mfma_f32_16x16x32_bf16 v[54:57], v[160:163], v[186:189], 0
	v_mfma_f32_16x16x32_bf16 v[50:53], v[178:181], v[186:189], 0
	v_mfma_f32_16x16x32_bf16 v[38:41], v[160:163], v[194:197], 0
	v_mfma_f32_16x16x32_bf16 v[34:37], v[178:181], v[194:197], 0
	v_mfma_f32_16x16x32_bf16 v[22:25], v[160:163], v[202:205], 0
	v_mfma_f32_16x16x32_bf16 v[18:21], v[178:181], v[202:205], 0
	v_mfma_f32_16x16x32_bf16 v[4:7], v[160:163], v[210:213], 0
	v_mfma_f32_16x16x32_bf16 v[0:3], v[178:181], v[210:213], 0
	v_mfma_f32_16x16x32_bf16 v[54:57], v[174:177], v[190:193], v[54:57]
	v_mfma_f32_16x16x32_bf16 v[50:53], v[182:185], v[190:193], v[50:53]
	v_mfma_f32_16x16x32_bf16 v[38:41], v[174:177], v[198:201], v[38:41]
	v_mfma_f32_16x16x32_bf16 v[34:37], v[182:185], v[198:201], v[34:37]
	v_mfma_f32_16x16x32_bf16 v[22:25], v[174:177], v[206:209], v[22:25]
	v_mfma_f32_16x16x32_bf16 v[18:21], v[182:185], v[206:209], v[18:21]
	v_mfma_f32_16x16x32_bf16 v[4:7], v[174:177], v[214:217], v[4:7]
	v_mfma_f32_16x16x32_bf16 v[0:3], v[182:185], v[214:217], v[0:3]
	s_barrier
	s_setprio 0
	s_add_i32 s18, 0, 0x18000
	v_add_u32_e32 v16, s18, v167
	s_add_i32 s19, 0, 0x1c000
	ds_read_b128 v[130:133], v16
	ds_read_b128 v[134:137], v16 offset:1024
	ds_read_b128 v[152:155], v16 offset:2048
	ds_read_b128 v[156:159], v16 offset:3072
	v_add_u32_e32 v16, s19, v167
	ds_read_b128 v[160:163], v16
	ds_read_b128 v[174:177], v16 offset:1024
	ds_read_b128 v[178:181], v16 offset:2048
	ds_read_b128 v[182:185], v16 offset:3072
	s_add_u32 s14, s14, 0x100000
	s_addc_u32 s15, s15, 0
	s_mov_b32 m0, s69
	v_lshl_add_u64 v[224:225], s[14:15], 0, v[144:145]
	ds_read_b128 v[186:189], v172 offset:32768
	ds_read_b128 v[190:193], v172 offset:33792
	ds_read_b128 v[194:197], v172 offset:34816
	ds_read_b128 v[198:201], v172 offset:35840
	ds_read_b128 v[202:205], v172 offset:36864
	ds_read_b128 v[206:209], v172 offset:37888
	ds_read_b128 v[210:213], v172 offset:38912
	ds_read_b128 v[214:217], v172 offset:39936
	global_load_lds_dwordx4 v[224:225], off
	v_lshl_add_u64 v[224:225], s[14:15], 0, v[140:141]
	s_mov_b32 m0, s72
	s_nop 0
	global_load_lds_dwordx4 v[224:225], off
	s_waitcnt vmcnt(8)
	s_waitcnt lgkmcnt(0)
	s_setprio 1
	s_barrier
	v_mfma_f32_16x16x32_bf16 v[126:129], v[130:133], v[186:189], v[126:129]
	v_mfma_f32_16x16x32_bf16 v[122:125], v[152:155], v[186:189], v[122:125]
	v_mfma_f32_16x16x32_bf16 v[110:113], v[130:133], v[194:197], v[110:113]
	v_mfma_f32_16x16x32_bf16 v[106:109], v[152:155], v[194:197], v[106:109]
	v_mfma_f32_16x16x32_bf16 v[94:97], v[130:133], v[202:205], v[94:97]
	v_mfma_f32_16x16x32_bf16 v[90:93], v[152:155], v[202:205], v[90:93]
	v_mfma_f32_16x16x32_bf16 v[78:81], v[130:133], v[210:213], v[78:81]
	v_mfma_f32_16x16x32_bf16 v[74:77], v[152:155], v[210:213], v[74:77]
	v_mfma_f32_16x16x32_bf16 v[126:129], v[134:137], v[190:193], v[126:129]
	v_mfma_f32_16x16x32_bf16 v[122:125], v[156:159], v[190:193], v[122:125]
	v_mfma_f32_16x16x32_bf16 v[110:113], v[134:137], v[198:201], v[110:113]
	v_mfma_f32_16x16x32_bf16 v[106:109], v[156:159], v[198:201], v[106:109]
	v_mfma_f32_16x16x32_bf16 v[94:97], v[134:137], v[206:209], v[94:97]
	v_mfma_f32_16x16x32_bf16 v[90:93], v[156:159], v[206:209], v[90:93]
	v_mfma_f32_16x16x32_bf16 v[78:81], v[134:137], v[214:217], v[78:81]
	v_mfma_f32_16x16x32_bf16 v[74:77], v[156:159], v[214:217], v[74:77]
	v_mfma_f32_16x16x32_bf16 v[118:121], v[160:163], v[186:189], v[118:121]
	v_mfma_f32_16x16x32_bf16 v[114:117], v[178:181], v[186:189], v[114:117]
	v_mfma_f32_16x16x32_bf16 v[102:105], v[160:163], v[194:197], v[102:105]
	v_mfma_f32_16x16x32_bf16 v[98:101], v[178:181], v[194:197], v[98:101]
	v_mfma_f32_16x16x32_bf16 v[86:89], v[160:163], v[202:205], v[86:89]
	v_mfma_f32_16x16x32_bf16 v[82:85], v[178:181], v[202:205], v[82:85]
	v_mfma_f32_16x16x32_bf16 v[70:73], v[160:163], v[210:213], v[70:73]
	v_mfma_f32_16x16x32_bf16 v[66:69], v[178:181], v[210:213], v[66:69]
	v_mfma_f32_16x16x32_bf16 v[118:121], v[174:177], v[190:193], v[118:121]
	v_mfma_f32_16x16x32_bf16 v[114:117], v[182:185], v[190:193], v[114:117]
	v_mfma_f32_16x16x32_bf16 v[102:105], v[174:177], v[198:201], v[102:105]
	v_mfma_f32_16x16x32_bf16 v[98:101], v[182:185], v[198:201], v[98:101]
	v_mfma_f32_16x16x32_bf16 v[86:89], v[174:177], v[206:209], v[86:89]
	v_mfma_f32_16x16x32_bf16 v[82:85], v[182:185], v[206:209], v[82:85]
	v_mfma_f32_16x16x32_bf16 v[70:73], v[174:177], v[214:217], v[70:73]
	v_mfma_f32_16x16x32_bf16 v[66:69], v[182:185], v[214:217], v[66:69]
	s_barrier
; #define PG8_STAGEA(bufoff, gbase, voff) PG8_STAGE_X(bufoff, gbase, voff, AUXA)
; #define PG8_STAGEB(bufoff, gbase, voff) PG8_STAGE_X(bufoff, gbase, voff, AUXB)
; #define PG8_LDA(dst, b, h) do { _Pragma("unroll") for (int m = 0; m < 4; ++m) _Pragma("unroll") for (int k = 0; k < 2; ++k) dst[m][k] = *(const PG8_LAS bf16x8*)(lds + PG8_SA(b, h) + aoff + m * 2048 + k * 1024); } while (0)
; #define PG8_LDB(dst, b, h) do { _Pragma("unroll") for (int n = 0; n < 2; ++n) _Pragma("unroll") for (int k = 0; k < 2; ++k) dst[n][k] = *(const PG8_LAS bf16x8*)(lds + PG8_SB(b, h) + boff + n * 2048 + k * 1024); } while (0)
; #define PG8_MMA(ai, bj, At, Bt) do { if (GEMM_PRIO_MODE == 0) __builtin_amdgcn_s_setprio(1); PG8_MMA_LOOPS \
;         acc[ai][bj][m][n] = __builtin_amdgcn_mfma_f32_16x16x32_bf16(Bt[n][k], At[m][k], acc[ai][bj][m][n], 0, 0, 0); if (GEMM_PRIO_MODE == 0) __builtin_amdgcn_s_setprio(0); } while (0)
; #define PG8_WAIT_V(n) asm volatile("s_waitcnt vmcnt(" #n ")" ::: "memory")
; #define PG8_WAIT_VR(n, nr, flag) asm volatile("s_cmp_eq_u32 %0, 0\n\ts_cbranch_scc1 .Lpg8s%=\n\ts_waitcnt vmcnt(" #nr ")\n\ts_branch .Lpg8d%=\n.Lpg8s%=:\n\ts_waitcnt vmcnt(" #n ")\n.Lpg8d%=:" :: "s"(flag) : "memory", "scc")
;     ...
;             const bool last = (t == nt - 2);
;             const char* a1 = cA + (size_t)(t + 1) * kstepA;
;             const char* a2 = last ? nA : cA + (size_t)(t + 2) * kstepA; const char* b2 = last ? nB : cB + (size_t)(t + 2) * kstepB;
;             const char* a3 = a2 + kstepA; const char* b3 = b2 + kstepB;
;             if (last && has_next) S.a_ready(nxt);
;             if constexpr (SP2) {
;             PG8_LDB(B0, 0, 0); PG8_LDB(B1, 0, 1); PG8_SCHED; PG8_LDA(At, 0, 0); PG8_STAGEA(PG8_SA(1, 1), a1 + hstepA, voffA);
;     ...
;             const int relax = __builtin_amdgcn_readfirstlane((t == 0 && ui > 0) ? 1 : 0);
;             PG8_WAIT_VR(8, 24, relax); PG8_WAIT_L(0); PG8_BAR; PG8_MMA(0, 0, At, B0); PG8_MMA(0, 1, At, B1); PG8_BAR; PG8_SCHED;
;     ...
;             PG8_WAIT_V(8); PG8_WAIT_L(0); PG8_BAR; PG8_MMA(0, 0, At, B0); PG8_MMA(0, 1, At, B1); PG8_BAR; PG8_SCHED;
;     ...
;             PG8_LDA(At, 1, 1); PG8_STAGEB(PG8_SB(1, 0), b3, voffB); PG8_STAGEB(PG8_SB(1, 1), b3 + hstepB, voffB); PG8_STAGEA(PG8_SA(1, 0), a3, voffA);
;             PG8_WAIT_V(8); PG8_WAIT_L(0); PG8_BAR; PG8_MMA(1, 0, At, B0); PG8_MMA(1, 1, At, B1); PG8_BAR; PG8_SCHED;
	s_setprio 0
	s_add_i32 s14, s18, s42
	v_lshl_add_u64 v[164:165], v[164:165], 0, s[86:87]
	s_mov_b32 m0, s14
	ds_read_b128 v[186:189], v172 offset:49152
	ds_read_b128 v[190:193], v172 offset:50176
	ds_read_b128 v[194:197], v172 offset:51200
	ds_read_b128 v[198:201], v172 offset:52224
	ds_read_b128 v[202:205], v172 offset:53248
	ds_read_b128 v[206:209], v172 offset:54272
	ds_read_b128 v[210:213], v172 offset:55296
	ds_read_b128 v[214:217], v172 offset:56320
	global_load_lds_dwordx4 v[164:165], off
	s_add_i32 m0, s14, 0x2000
	s_add_u32 s10, s10, 0x100080
	v_lshl_add_u64 v[164:165], v[218:219], 0, s[86:87]
	s_addc_u32 s11, s11, 0
	s_add_i32 s14, s19, s42
	global_load_lds_dwordx4 v[164:165], off
	v_lshl_add_u64 v[164:165], s[10:11], 0, v[142:143]
	s_mov_b32 m0, s14
	s_nop 0
	global_load_lds_dwordx4 v[164:165], off
	v_lshl_add_u64 v[164:165], s[10:11], 0, v[138:139]
	s_add_i32 m0, s14, 0x2000
	s_nop 0
	global_load_lds_dwordx4 v[164:165], off
	v_lshl_add_u64 v[164:165], v[220:221], 0, s[86:87]
	s_mov_b32 m0, s73
	s_nop 0
	global_load_lds_dwordx4 v[164:165], off
	v_lshl_add_u64 v[164:165], v[222:223], 0, s[86:87]
	s_mov_b32 m0, s82
	s_nop 0
	global_load_lds_dwordx4 v[164:165], off
	s_waitcnt vmcnt(8)
	s_waitcnt lgkmcnt(0)
	s_nop 0
	s_setprio 1
	s_barrier
	v_mfma_f32_16x16x32_bf16 v[62:65], v[130:133], v[186:189], v[62:65]
	v_mfma_f32_16x16x32_bf16 v[58:61], v[152:155], v[186:189], v[58:61]
	v_mfma_f32_16x16x32_bf16 v[46:49], v[130:133], v[194:197], v[46:49]
	v_mfma_f32_16x16x32_bf16 v[42:45], v[152:155], v[194:197], v[42:45]
	v_mfma_f32_16x16x32_bf16 v[30:33], v[130:133], v[202:205], v[30:33]
	v_mfma_f32_16x16x32_bf16 v[26:29], v[152:155], v[202:205], v[26:29]
	v_mfma_f32_16x16x32_bf16 v[12:15], v[130:133], v[210:213], v[12:15]
	v_mfma_f32_16x16x32_bf16 v[8:11], v[152:155], v[210:213], v[8:11]
	v_mfma_f32_16x16x32_bf16 v[62:65], v[134:137], v[190:193], v[62:65]
	v_mfma_f32_16x16x32_bf16 v[58:61], v[156:159], v[190:193], v[58:61]
	v_mfma_f32_16x16x32_bf16 v[46:49], v[134:137], v[198:201], v[46:49]
	v_mfma_f32_16x16x32_bf16 v[42:45], v[156:159], v[198:201], v[42:45]
	v_mfma_f32_16x16x32_bf16 v[30:33], v[134:137], v[206:209], v[30:33]
	v_mfma_f32_16x16x32_bf16 v[26:29], v[156:159], v[206:209], v[26:29]
	v_mfma_f32_16x16x32_bf16 v[12:15], v[134:137], v[214:217], v[12:15]
	v_mfma_f32_16x16x32_bf16 v[8:11], v[156:159], v[214:217], v[8:11]
	v_mfma_f32_16x16x32_bf16 v[54:57], v[160:163], v[186:189], v[54:57]
	v_mfma_f32_16x16x32_bf16 v[50:53], v[178:181], v[186:189], v[50:53]
	v_mfma_f32_16x16x32_bf16 v[38:41], v[160:163], v[194:197], v[38:41]
	v_mfma_f32_16x16x32_bf16 v[34:37], v[178:181], v[194:197], v[34:37]
	v_mfma_f32_16x16x32_bf16 v[22:25], v[160:163], v[202:205], v[22:25]
	v_mfma_f32_16x16x32_bf16 v[18:21], v[178:181], v[202:205], v[18:21]
	v_mfma_f32_16x16x32_bf16 v[4:7], v[160:163], v[210:213], v[4:7]
	v_mfma_f32_16x16x32_bf16 v[0:3], v[178:181], v[210:213], v[0:3]
	v_mfma_f32_16x16x32_bf16 v[54:57], v[174:177], v[190:193], v[54:57]
	v_mfma_f32_16x16x32_bf16 v[50:53], v[182:185], v[190:193], v[50:53]
	v_mfma_f32_16x16x32_bf16 v[38:41], v[174:177], v[198:201], v[38:41]
	v_mfma_f32_16x16x32_bf16 v[34:37], v[182:185], v[198:201], v[34:37]
	v_mfma_f32_16x16x32_bf16 v[22:25], v[174:177], v[206:209], v[22:25]
	v_mfma_f32_16x16x32_bf16 v[18:21], v[182:185], v[206:209], v[18:21]
	v_mfma_f32_16x16x32_bf16 v[4:7], v[174:177], v[214:217], v[4:7]
	v_mfma_f32_16x16x32_bf16 v[0:3], v[182:185], v[214:217], v[0:3]
	s_barrier
	s_setprio 0
	s_add_i32 s27, s27, 2
	s_add_u32 s8, s8, 0x100
	s_addc_u32 s9, s9, 0
	s_add_u32 s0, s0, 0x100
	s_addc_u32 s1, s1, 0
	v_add_u32_e32 v226, 0x10000, v167
.LBB0_129:
	s_add_u32 s10, s8, 0xfff00080
	s_addc_u32 s11, s9, -1
	s_add_i32 s18, 0, 0x10000
	s_cmp_eq_u32 s27, 60
	s_cselect_b32 s15, s4, s11
	s_cselect_b32 s14, s5, s10
	s_cselect_b32 s11, s16, s1
	s_cselect_b32 s10, s17, s0
	s_add_i32 s20, 0, 0x14000
	s_waitcnt lgkmcnt(0)
	ds_read_b128 v[130:133], v226
	ds_read_b128 v[134:137], v226 offset:1024
	ds_read_b128 v[152:155], v226 offset:2048
	ds_read_b128 v[156:159], v226 offset:3072
	ds_read_b128 v[160:163], v226 offset:16384
	ds_read_b128 v[174:177], v226 offset:17408
	ds_read_b128 v[178:181], v226 offset:18432
	ds_read_b128 v[182:185], v226 offset:19456
	s_add_i32 m0, s51, 0xc000
	ds_read_b128 v[186:189], v172
	ds_read_b128 v[190:193], v172 offset:1024
	ds_read_b128 v[194:197], v172 offset:2048
	ds_read_b128 v[198:201], v172 offset:3072
	ds_read_b128 v[202:205], v172 offset:4096
	ds_read_b128 v[206:209], v172 offset:5120
	ds_read_b128 v[210:213], v172 offset:6144
	ds_read_b128 v[214:217], v172 offset:7168
	global_load_lds_dwordx4 v148, s[8:9]
	s_add_i32 m0, s51, 0xe000
	s_nop 0
	global_load_lds_dwordx4 v150, s[8:9]
	s_waitcnt vmcnt(8)
	s_waitcnt lgkmcnt(0)
	s_nop 0
	s_setprio 1
	s_barrier
; #define PG8_STAGEA(bufoff, gbase, voff) PG8_STAGE_X(bufoff, gbase, voff, AUXA)
; #define PG8_STAGEB(bufoff, gbase, voff) PG8_STAGE_X(bufoff, gbase, voff, AUXB)
; #define PG8_LDA(dst, b, h) do { _Pragma("unroll") for (int m = 0; m < 4; ++m) _Pragma("unroll") for (int k = 0; k < 2; ++k) dst[m][k] = *(const PG8_LAS bf16x8*)(lds + PG8_SA(b, h) + aoff + m * 2048 + k * 1024); } while (0)
; #define PG8_MMA(ai, bj, At, Bt) do { if (GEMM_PRIO_MODE == 0) __builtin_amdgcn_s_setprio(1); PG8_MMA_LOOPS \
;         acc[ai][bj][m][n] = __builtin_amdgcn_mfma_f32_16x16x32_bf16(Bt[n][k], At[m][k], acc[ai][bj][m][n], 0, 0, 0); if (GEMM_PRIO_MODE == 0) __builtin_amdgcn_s_setprio(0); } while (0)
; #define PG8_WAIT_V(n) asm volatile("s_waitcnt vmcnt(" #n ")" ::: "memory")
; #define PG8_WAIT_VR(n, nr, flag) asm volatile("s_cmp_eq_u32 %0, 0\n\ts_cbranch_scc1 .Lpg8s%=\n\ts_waitcnt vmcnt(" #nr ")\n\ts_branch .Lpg8d%=\n.Lpg8s%=:\n\ts_waitcnt vmcnt(" #n ")\n.Lpg8d%=:" :: "s"(flag) : "memory", "scc")
; #define PG8_WAIT_L(n) asm volatile("s_waitcnt lgkmcnt(" #n ")" ::: "memory")
; #define PG8_BAR __builtin_amdgcn_s_barrier()
; #define PG8_SCHED __builtin_amdgcn_sched_barrier(0)
;     ...
;             PG8_WAIT_V(8); PG8_WAIT_L(0); PG8_BAR; PG8_MMA(0, 0, At, B0); PG8_MMA(0, 1, At, B1); PG8_BAR; PG8_SCHED;
;     ...
;             PG8_LDA(At, 0, 1); PG8_STAGEB(PG8_SB(0, 0), b2, voffB); PG8_STAGEB(PG8_SB(0, 1), b2 + hstepB, voffB); PG8_STAGEA(PG8_SA(0, 0), a2, voffA);
;     ...
;             PG8_WAIT_VR(8, 24, relax); PG8_WAIT_L(0); PG8_BAR; PG8_MMA(1, 0, At, B0); PG8_MMA(1, 1, At, B1); PG8_BAR; PG8_SCHED;
;     ...
;             PG8_WAIT_V(8); PG8_WAIT_L(0); PG8_BAR; PG8_MMA(1, 0, At, B0); PG8_MMA(1, 1, At, B1); PG8_BAR; PG8_SCHED;
	v_mfma_f32_16x16x32_bf16 v[126:129], v[130:133], v[186:189], v[126:129]
	v_mfma_f32_16x16x32_bf16 v[122:125], v[152:155], v[186:189], v[122:125]
	v_mfma_f32_16x16x32_bf16 v[110:113], v[130:133], v[194:197], v[110:113]
	v_mfma_f32_16x16x32_bf16 v[106:109], v[152:155], v[194:197], v[106:109]
	v_mfma_f32_16x16x32_bf16 v[94:97], v[130:133], v[202:205], v[94:97]
	v_mfma_f32_16x16x32_bf16 v[90:93], v[152:155], v[202:205], v[90:93]
	v_mfma_f32_16x16x32_bf16 v[78:81], v[130:133], v[210:213], v[78:81]
	v_mfma_f32_16x16x32_bf16 v[74:77], v[152:155], v[210:213], v[74:77]
	v_mfma_f32_16x16x32_bf16 v[126:129], v[134:137], v[190:193], v[126:129]
	v_mfma_f32_16x16x32_bf16 v[122:125], v[156:159], v[190:193], v[122:125]
	v_mfma_f32_16x16x32_bf16 v[110:113], v[134:137], v[198:201], v[110:113]
	v_mfma_f32_16x16x32_bf16 v[106:109], v[156:159], v[198:201], v[106:109]
	v_mfma_f32_16x16x32_bf16 v[94:97], v[134:137], v[206:209], v[94:97]
	v_mfma_f32_16x16x32_bf16 v[90:93], v[156:159], v[206:209], v[90:93]
	v_mfma_f32_16x16x32_bf16 v[78:81], v[134:137], v[214:217], v[78:81]
	v_mfma_f32_16x16x32_bf16 v[74:77], v[156:159], v[214:217], v[74:77]
	v_mfma_f32_16x16x32_bf16 v[118:121], v[160:163], v[186:189], v[118:121]
	v_mfma_f32_16x16x32_bf16 v[114:117], v[178:181], v[186:189], v[114:117]
	v_mfma_f32_16x16x32_bf16 v[102:105], v[160:163], v[194:197], v[102:105]
	v_mfma_f32_16x16x32_bf16 v[98:101], v[178:181], v[194:197], v[98:101]
	v_mfma_f32_16x16x32_bf16 v[86:89], v[160:163], v[202:205], v[86:89]
	v_mfma_f32_16x16x32_bf16 v[82:85], v[178:181], v[202:205], v[82:85]
	v_mfma_f32_16x16x32_bf16 v[70:73], v[160:163], v[210:213], v[70:73]
	v_mfma_f32_16x16x32_bf16 v[66:69], v[178:181], v[210:213], v[66:69]
	v_mfma_f32_16x16x32_bf16 v[118:121], v[174:177], v[190:193], v[118:121]
	v_mfma_f32_16x16x32_bf16 v[114:117], v[182:185], v[190:193], v[114:117]
	v_mfma_f32_16x16x32_bf16 v[102:105], v[174:177], v[198:201], v[102:105]
	v_mfma_f32_16x16x32_bf16 v[98:101], v[182:185], v[198:201], v[98:101]
	v_mfma_f32_16x16x32_bf16 v[86:89], v[174:177], v[206:209], v[86:89]
	v_mfma_f32_16x16x32_bf16 v[82:85], v[182:185], v[206:209], v[82:85]
	v_mfma_f32_16x16x32_bf16 v[70:73], v[174:177], v[214:217], v[70:73]
	v_mfma_f32_16x16x32_bf16 v[66:69], v[182:185], v[214:217], v[66:69]
	s_barrier
	s_setprio 0
	s_add_i32 s18, s18, s42
	s_mov_b32 m0, s18
	ds_read_b128 v[186:189], v172 offset:16384
	ds_read_b128 v[190:193], v172 offset:17408
	ds_read_b128 v[194:197], v172 offset:18432
	ds_read_b128 v[198:201], v172 offset:19456
	ds_read_b128 v[202:205], v172 offset:20480
	ds_read_b128 v[206:209], v172 offset:21504
	ds_read_b128 v[210:213], v172 offset:22528
	ds_read_b128 v[214:217], v172 offset:23552
	s_add_u32 s100, s14, 0x80
	s_addc_u32 s101, s15, 0
	global_load_lds_dwordx4 v142, s[10:11]
	s_add_i32 m0, s18, 0x2000
	s_add_u32 s18, s10, 0x100000
	s_addc_u32 s19, s11, 0
	s_add_i32 s20, s20, s42
	global_load_lds_dwordx4 v138, s[10:11]
	s_mov_b32 m0, s20
	s_nop 0
	global_load_lds_dwordx4 v142, s[18:19]
	s_add_i32 m0, s20, 0x2000
	s_nop 0
	global_load_lds_dwordx4 v138, s[18:19]
	s_mov_b32 m0, s51
	s_nop 0
	global_load_lds_dwordx4 v144, s[14:15]
	s_mov_b32 m0, s68
	s_nop 0
	global_load_lds_dwordx4 v140, s[14:15]
	s_waitcnt vmcnt(8)
	s_waitcnt lgkmcnt(0)
	s_setprio 1
	s_barrier
	v_mfma_f32_16x16x32_bf16 v[62:65], v[130:133], v[186:189], v[62:65]
	v_mfma_f32_16x16x32_bf16 v[58:61], v[152:155], v[186:189], v[58:61]
	v_mfma_f32_16x16x32_bf16 v[46:49], v[130:133], v[194:197], v[46:49]
	v_mfma_f32_16x16x32_bf16 v[42:45], v[152:155], v[194:197], v[42:45]
	v_mfma_f32_16x16x32_bf16 v[30:33], v[130:133], v[202:205], v[30:33]
	v_mfma_f32_16x16x32_bf16 v[26:29], v[152:155], v[202:205], v[26:29]
	v_mfma_f32_16x16x32_bf16 v[12:15], v[130:133], v[210:213], v[12:15]
	v_mfma_f32_16x16x32_bf16 v[8:11], v[152:155], v[210:213], v[8:11]
	v_mfma_f32_16x16x32_bf16 v[62:65], v[134:137], v[190:193], v[62:65]
	v_mfma_f32_16x16x32_bf16 v[58:61], v[156:159], v[190:193], v[58:61]
	v_mfma_f32_16x16x32_bf16 v[46:49], v[134:137], v[198:201], v[46:49]
	v_mfma_f32_16x16x32_bf16 v[42:45], v[156:159], v[198:201], v[42:45]
	v_mfma_f32_16x16x32_bf16 v[30:33], v[134:137], v[206:209], v[30:33]
	v_mfma_f32_16x16x32_bf16 v[26:29], v[156:159], v[206:209], v[26:29]
	v_mfma_f32_16x16x32_bf16 v[12:15], v[134:137], v[214:217], v[12:15]
	v_mfma_f32_16x16x32_bf16 v[8:11], v[156:159], v[214:217], v[8:11]
	v_mfma_f32_16x16x32_bf16 v[54:57], v[160:163], v[186:189], v[54:57]
	v_mfma_f32_16x16x32_bf16 v[50:53], v[178:181], v[186:189], v[50:53]
	v_mfma_f32_16x16x32_bf16 v[38:41], v[160:163], v[194:197], v[38:41]
	v_mfma_f32_16x16x32_bf16 v[34:37], v[178:181], v[194:197], v[34:37]
	v_mfma_f32_16x16x32_bf16 v[22:25], v[160:163], v[202:205], v[22:25]
	v_mfma_f32_16x16x32_bf16 v[18:21], v[178:181], v[202:205], v[18:21]
	v_mfma_f32_16x16x32_bf16 v[4:7], v[160:163], v[210:213], v[4:7]
	v_mfma_f32_16x16x32_bf16 v[0:3], v[178:181], v[210:213], v[0:3]
	v_mfma_f32_16x16x32_bf16 v[54:57], v[174:177], v[190:193], v[54:57]
	v_mfma_f32_16x16x32_bf16 v[50:53], v[182:185], v[190:193], v[50:53]
	v_mfma_f32_16x16x32_bf16 v[38:41], v[174:177], v[198:201], v[38:41]
	v_mfma_f32_16x16x32_bf16 v[34:37], v[182:185], v[198:201], v[34:37]
	v_mfma_f32_16x16x32_bf16 v[22:25], v[174:177], v[206:209], v[22:25]
	v_mfma_f32_16x16x32_bf16 v[18:21], v[182:185], v[206:209], v[18:21]
	v_mfma_f32_16x16x32_bf16 v[4:7], v[174:177], v[214:217], v[4:7]
	v_mfma_f32_16x16x32_bf16 v[0:3], v[182:185], v[214:217], v[0:3]
	s_barrier
; #define PG8_STAGEA(bufoff, gbase, voff) PG8_STAGE_X(bufoff, gbase, voff, AUXA)
; #define PG8_STAGEB(bufoff, gbase, voff) PG8_STAGE_X(bufoff, gbase, voff, AUXB)
; #define PG8_LDA(dst, b, h) do { _Pragma("unroll") for (int m = 0; m < 4; ++m) _Pragma("unroll") for (int k = 0; k < 2; ++k) dst[m][k] = *(const PG8_LAS bf16x8*)(lds + PG8_SA(b, h) + aoff + m * 2048 + k * 1024); } while (0)
; #define PG8_LDB(dst, b, h) do { _Pragma("unroll") for (int n = 0; n < 2; ++n) _Pragma("unroll") for (int k = 0; k < 2; ++k) dst[n][k] = *(const PG8_LAS bf16x8*)(lds + PG8_SB(b, h) + boff + n * 2048 + k * 1024); } while (0)
; #define PG8_MMA(ai, bj, At, Bt) do { if (GEMM_PRIO_MODE == 0) __builtin_amdgcn_s_setprio(1); PG8_MMA_LOOPS \
;         acc[ai][bj][m][n] = __builtin_amdgcn_mfma_f32_16x16x32_bf16(Bt[n][k], At[m][k], acc[ai][bj][m][n], 0, 0, 0); if (GEMM_PRIO_MODE == 0) __builtin_amdgcn_s_setprio(0); } while (0)
; #define PG8_WAIT_V(n) asm volatile("s_waitcnt vmcnt(" #n ")" ::: "memory")
; #define PG8_WAIT_L(n) asm volatile("s_waitcnt lgkmcnt(" #n ")" ::: "memory")
; #define PG8_BAR __builtin_amdgcn_s_barrier()
; #define PG8_SCHED __builtin_amdgcn_sched_barrier(0)
;     ...
;             PG8_LDB(B0, 1, 0); PG8_LDB(B1, 1, 1); PG8_SCHED; PG8_LDA(At, 1, 0); PG8_STAGEA(PG8_SA(0, 1), a2 + hstepA, voffA);
;             PG8_WAIT_V(8); PG8_WAIT_L(0); PG8_BAR; PG8_MMA(0, 0, At, B0); PG8_MMA(0, 1, At, B1); PG8_BAR; PG8_SCHED;
;             PG8_LDA(At, 1, 1); PG8_STAGEB(PG8_SB(1, 0), b3, voffB); PG8_STAGEB(PG8_SB(1, 1), b3 + hstepB, voffB); PG8_STAGEA(PG8_SA(1, 0), a3, voffA);
;             PG8_WAIT_V(8); PG8_WAIT_L(0); PG8_BAR; PG8_MMA(1, 0, At, B0); PG8_MMA(1, 1, At, B1); PG8_BAR; PG8_SCHED;
	s_setprio 0
	s_add_i32 s18, 0, 0x18000
	s_add_i32 s19, 0, 0x1c000
	ds_read_b128 v[130:133], v226 offset:32768
	ds_read_b128 v[134:137], v226 offset:33792
	ds_read_b128 v[152:155], v226 offset:34816
	ds_read_b128 v[156:159], v226 offset:35840
	ds_read_b128 v[160:163], v226 offset:49152
	ds_read_b128 v[174:177], v226 offset:50176
	ds_read_b128 v[178:181], v226 offset:51200
	ds_read_b128 v[182:185], v226 offset:52224
	s_add_u32 s14, s14, 0x100000
	s_addc_u32 s15, s15, 0
	s_mov_b32 m0, s69
	ds_read_b128 v[186:189], v172 offset:32768
	ds_read_b128 v[190:193], v172 offset:33792
	ds_read_b128 v[194:197], v172 offset:34816
	ds_read_b128 v[198:201], v172 offset:35840
	ds_read_b128 v[202:205], v172 offset:36864
	ds_read_b128 v[206:209], v172 offset:37888
	ds_read_b128 v[210:213], v172 offset:38912
	ds_read_b128 v[214:217], v172 offset:39936
	global_load_lds_dwordx4 v144, s[14:15]
	s_mov_b32 m0, s72
	s_nop 0
	global_load_lds_dwordx4 v140, s[14:15]
	s_waitcnt vmcnt(8)
	s_waitcnt lgkmcnt(0)
	s_setprio 1
	s_barrier
	v_mfma_f32_16x16x32_bf16 v[126:129], v[130:133], v[186:189], v[126:129]
	v_mfma_f32_16x16x32_bf16 v[122:125], v[152:155], v[186:189], v[122:125]
	v_mfma_f32_16x16x32_bf16 v[110:113], v[130:133], v[194:197], v[110:113]
	v_mfma_f32_16x16x32_bf16 v[106:109], v[152:155], v[194:197], v[106:109]
	v_mfma_f32_16x16x32_bf16 v[94:97], v[130:133], v[202:205], v[94:97]
	v_mfma_f32_16x16x32_bf16 v[90:93], v[152:155], v[202:205], v[90:93]
	v_mfma_f32_16x16x32_bf16 v[78:81], v[130:133], v[210:213], v[78:81]
	v_mfma_f32_16x16x32_bf16 v[74:77], v[152:155], v[210:213], v[74:77]
	v_mfma_f32_16x16x32_bf16 v[126:129], v[134:137], v[190:193], v[126:129]
	v_mfma_f32_16x16x32_bf16 v[122:125], v[156:159], v[190:193], v[122:125]
	v_mfma_f32_16x16x32_bf16 v[110:113], v[134:137], v[198:201], v[110:113]
	v_mfma_f32_16x16x32_bf16 v[106:109], v[156:159], v[198:201], v[106:109]
	v_mfma_f32_16x16x32_bf16 v[94:97], v[134:137], v[206:209], v[94:97]
	v_mfma_f32_16x16x32_bf16 v[90:93], v[156:159], v[206:209], v[90:93]
	v_mfma_f32_16x16x32_bf16 v[78:81], v[134:137], v[214:217], v[78:81]
	v_mfma_f32_16x16x32_bf16 v[74:77], v[156:159], v[214:217], v[74:77]
	v_mfma_f32_16x16x32_bf16 v[118:121], v[160:163], v[186:189], v[118:121]
	v_mfma_f32_16x16x32_bf16 v[114:117], v[178:181], v[186:189], v[114:117]
	v_mfma_f32_16x16x32_bf16 v[102:105], v[160:163], v[194:197], v[102:105]
	v_mfma_f32_16x16x32_bf16 v[98:101], v[178:181], v[194:197], v[98:101]
	v_mfma_f32_16x16x32_bf16 v[86:89], v[160:163], v[202:205], v[86:89]
	v_mfma_f32_16x16x32_bf16 v[82:85], v[178:181], v[202:205], v[82:85]
	v_mfma_f32_16x16x32_bf16 v[70:73], v[160:163], v[210:213], v[70:73]
	v_mfma_f32_16x16x32_bf16 v[66:69], v[178:181], v[210:213], v[66:69]
	v_mfma_f32_16x16x32_bf16 v[118:121], v[174:177], v[190:193], v[118:121]
	v_mfma_f32_16x16x32_bf16 v[114:117], v[182:185], v[190:193], v[114:117]
	v_mfma_f32_16x16x32_bf16 v[102:105], v[174:177], v[198:201], v[102:105]
	v_mfma_f32_16x16x32_bf16 v[98:101], v[182:185], v[198:201], v[98:101]
	v_mfma_f32_16x16x32_bf16 v[86:89], v[174:177], v[206:209], v[86:89]
	v_mfma_f32_16x16x32_bf16 v[82:85], v[182:185], v[206:209], v[82:85]
	v_mfma_f32_16x16x32_bf16 v[70:73], v[174:177], v[214:217], v[70:73]
	v_mfma_f32_16x16x32_bf16 v[66:69], v[182:185], v[214:217], v[66:69]
	s_barrier
	s_setprio 0
	s_add_i32 s14, s18, s42
	s_mov_b32 m0, s14
	ds_read_b128 v[186:189], v172 offset:49152
	ds_read_b128 v[190:193], v172 offset:50176
	ds_read_b128 v[194:197], v172 offset:51200
	ds_read_b128 v[198:201], v172 offset:52224
	ds_read_b128 v[202:205], v172 offset:53248
	ds_read_b128 v[206:209], v172 offset:54272
	ds_read_b128 v[210:213], v172 offset:55296
	ds_read_b128 v[214:217], v172 offset:56320
	s_add_u32 vcc_lo, s10, 0x80
	s_addc_u32 vcc_hi, s11, 0
	global_load_lds_dwordx4 v142, vcc
	s_add_i32 m0, s14, 0x2000
	s_add_u32 s10, s10, 0x100080
	s_addc_u32 s11, s11, 0
	s_add_i32 s14, s19, s42
	global_load_lds_dwordx4 v138, vcc
	s_mov_b32 m0, s14
	s_nop 0
	global_load_lds_dwordx4 v142, s[10:11]
	s_add_i32 m0, s14, 0x2000
	s_nop 0
	global_load_lds_dwordx4 v138, s[10:11]
	s_mov_b32 m0, s73
	s_nop 0
	global_load_lds_dwordx4 v144, s[100:101]
	s_mov_b32 m0, s82
	s_nop 0
	global_load_lds_dwordx4 v140, s[100:101]
	s_waitcnt vmcnt(8)
	s_waitcnt lgkmcnt(0)
	s_setprio 1
	s_barrier
	v_mfma_f32_16x16x32_bf16 v[62:65], v[130:133], v[186:189], v[62:65]
	v_mfma_f32_16x16x32_bf16 v[58:61], v[152:155], v[186:189], v[58:61]
	v_mfma_f32_16x16x32_bf16 v[46:49], v[130:133], v[194:197], v[46:49]
	v_mfma_f32_16x16x32_bf16 v[42:45], v[152:155], v[194:197], v[42:45]
	v_mfma_f32_16x16x32_bf16 v[30:33], v[130:133], v[202:205], v[30:33]
	v_mfma_f32_16x16x32_bf16 v[26:29], v[152:155], v[202:205], v[26:29]
	v_mfma_f32_16x16x32_bf16 v[12:15], v[130:133], v[210:213], v[12:15]
	v_mfma_f32_16x16x32_bf16 v[8:11], v[152:155], v[210:213], v[8:11]
	v_mfma_f32_16x16x32_bf16 v[62:65], v[134:137], v[190:193], v[62:65]
	v_mfma_f32_16x16x32_bf16 v[58:61], v[156:159], v[190:193], v[58:61]
	v_mfma_f32_16x16x32_bf16 v[46:49], v[134:137], v[198:201], v[46:49]
	v_mfma_f32_16x16x32_bf16 v[42:45], v[156:159], v[198:201], v[42:45]
	v_mfma_f32_16x16x32_bf16 v[30:33], v[134:137], v[206:209], v[30:33]
	v_mfma_f32_16x16x32_bf16 v[26:29], v[156:159], v[206:209], v[26:29]
	v_mfma_f32_16x16x32_bf16 v[12:15], v[134:137], v[214:217], v[12:15]
	v_mfma_f32_16x16x32_bf16 v[8:11], v[156:159], v[214:217], v[8:11]
	v_mfma_f32_16x16x32_bf16 v[54:57], v[160:163], v[186:189], v[54:57]
	v_mfma_f32_16x16x32_bf16 v[50:53], v[178:181], v[186:189], v[50:53]
	v_mfma_f32_16x16x32_bf16 v[38:41], v[160:163], v[194:197], v[38:41]
	v_mfma_f32_16x16x32_bf16 v[34:37], v[178:181], v[194:197], v[34:37]
	v_mfma_f32_16x16x32_bf16 v[22:25], v[160:163], v[202:205], v[22:25]
	v_mfma_f32_16x16x32_bf16 v[18:21], v[178:181], v[202:205], v[18:21]
	v_mfma_f32_16x16x32_bf16 v[4:7], v[160:163], v[210:213], v[4:7]
	v_mfma_f32_16x16x32_bf16 v[0:3], v[178:181], v[210:213], v[0:3]
	v_mfma_f32_16x16x32_bf16 v[54:57], v[174:177], v[190:193], v[54:57]
	v_mfma_f32_16x16x32_bf16 v[50:53], v[182:185], v[190:193], v[50:53]
	v_mfma_f32_16x16x32_bf16 v[38:41], v[174:177], v[198:201], v[38:41]
	v_mfma_f32_16x16x32_bf16 v[34:37], v[182:185], v[198:201], v[34:37]
	v_mfma_f32_16x16x32_bf16 v[22:25], v[174:177], v[206:209], v[22:25]
	v_mfma_f32_16x16x32_bf16 v[18:21], v[182:185], v[206:209], v[18:21]
	v_mfma_f32_16x16x32_bf16 v[4:7], v[174:177], v[214:217], v[4:7]
	v_mfma_f32_16x16x32_bf16 v[0:3], v[182:185], v[214:217], v[0:3]
	s_barrier
	s_setprio 0
	s_add_i32 s27, s27, 2
	s_add_u32 s8, s8, 0x100
	s_addc_u32 s9, s9, 0
	s_add_u32 s0, s0, 0x100
	s_addc_u32 s1, s1, 0
	s_cmp_gt_u32 s27, 61
	s_cbranch_scc0 .LBB0_129
	s_and_b64 vcc, exec, s[24:25]
	s_cbranch_vccz .LBB0_132
	s_barrier

; #define PG8_STAGEA(bufoff, gbase, voff) PG8_STAGE_X(bufoff, gbase, voff, AUXA)
; #define PG8_STR(x) PG8_STR2(x)
;     ...
;         const bool has_next = S.next(ui + 1, nxt);
;         const char* nA = has_next ? (const char*)g.A + (size_t)nxt.pm * tstepA : cA; const char* nB = has_next ? (const char*)g.Bt + (size_t)nxt.pn * tstepB : cB;
;         int t0 = 0;
;         if constexpr (SP2 && GEMM_RELAX == 1) { if (ui > 0) {
;             const char* a1 = cA + kstepA; const char* a2 = cA + 2 * kstepA; const char* b2 = cB + 2 * kstepB; const char* a3 = a2 + kstepA; const char* b3 = b2 + kstepB;
;             PG8_LDB(B0, 0, 0); PG8_LDB(B1, 0, 1); PG8_SCHED; PG8_LDA(At, 0, 0); PG8_STAGEA(PG8_SA(1, 1), a1 + hstepA, voffA);
;             PG8_WAIT_V(24); PG8_WAIT_L(0); PG8_BAR; PG8_MMA(0, 0, At, B0); PG8_MMA(0, 1, At, B1); PG8_BAR; PG8_SCHED;
;             PG8_LDA(At, 0, 1); PG8_STAGEB(PG8_SB(0, 0), b2, voffB); PG8_STAGEB(PG8_SB(0, 1), b2 + hstepB, voffB); PG8_STAGEA(PG8_SA(0, 0), a2, voffA);
;             PG8_WAIT_V(24); PG8_WAIT_L(0); PG8_BAR; PG8_MMA(1, 0, At, B0); PG8_MMA(1, 1, At, B1); PG8_BAR; PG8_SCHED;
;             PG8_LDB(B0, 1, 0); PG8_LDB(B1, 1, 1); PG8_SCHED; PG8_LDA(At, 1, 0); PG8_STAGEA(PG8_SA(0, 1), a2 + hstepA, voffA);
;             PG8_WAIT_V(8); PG8_WAIT_L(0); PG8_BAR; PG8_MMA(0, 0, At, B0); PG8_MMA(0, 1, At, B1); PG8_BAR; PG8_SCHED;
;             PG8_LDA(At, 1, 1); PG8_STAGEB(PG8_SB(1, 0), b3, voffB); PG8_STAGEB(PG8_SB(1, 1), b3 + hstepB, voffB); PG8_STAGEA(PG8_SA(1, 0), a3, voffA);
;             PG8_WAIT_V(8); PG8_WAIT_L(0); PG8_BAR; PG8_MMA(1, 0, At, B0); PG8_MMA(1, 1, At, B1); PG8_BAR; PG8_SCHED;
;             t0 = 2; } }
;     ...
;         asm volatile(".p2align " PG8_STR(GEMM_LOOP_ALIGN) ::: "memory");
;     ...
;         for (int t = t0; t < nt; t += 2) {
;             const bool last = (t == nt - 2);
;             const char* a1 = cA + (size_t)(t + 1) * kstepA;
;             const char* a2 = last ? nA : cA + (size_t)(t + 2) * kstepA; const char* b2 = last ? nB : cB + (size_t)(t + 2) * kstepB;
;             const char* a3 = a2 + kstepA; const char* b3 = b2 + kstepB;
;             if (last && has_next) S.a_ready(nxt);
;             if constexpr (SP2) {
;             PG8_LDB(B0, 0, 0); PG8_LDB(B1, 0, 1); PG8_SCHED; PG8_LDA(At, 0, 0); PG8_STAGEA(PG8_SA(1, 1), a1 + hstepA, voffA);
;     ...
;             const int relax = __builtin_amdgcn_readfirstlane((t == 0 && ui > 0) ? 1 : 0);
.LBB0_557:
	s_ashr_i32 s21, s20, 31
	s_lshl_b64 s[6:7], s[20:21], 21
	s_add_u32 s24, s60, s6
	s_addc_u32 s25, s61, s7
	s_and_b64 s[6:7], s[26:27], exec
	s_cselect_b32 s21, s25, s1
	s_cselect_b32 s82, s24, s0
	s_ashr_i32 s23, s22, 31
	s_lshl_b64 s[6:7], s[22:23], 21
	s_add_u32 s36, s4, s6
	s_addc_u32 s37, s5, s7
	s_and_b64 s[6:7], s[26:27], exec
	s_cselect_b32 s23, s37, s41
	s_cselect_b32 s83, s36, s40
	s_add_u32 s38, s0, 0x100080
	s_addc_u32 s39, s1, 0
	s_add_u32 s0, s40, 0x100
	s_addc_u32 s1, s41, 0
	s_mov_b32 s90, -2
	s_waitcnt lgkmcnt(0)
	s_waitcnt vmcnt(0)
	s_add_u32 s6, s38, 0xfff00080
	s_addc_u32 s7, s39, -1
	s_add_i32 s91, 0, 0x10000
	s_cmp_eq_u32 s90, 60
	s_cselect_b32 s41, s21, s7
	s_cselect_b32 s40, s82, s6
	s_cselect_b32 s17, s23, s1
	s_cselect_b32 s16, s83, s0
	s_add_i32 s94, 0, 0x14000
	v_add_u32_e32 v152, s91, v157
	v_add_u32_e32 v174, s94, v157
	ds_read_b128 v[130:133], v152
	ds_read_b128 v[134:137], v152 offset:1024
	ds_read_b128 v[148:151], v152 offset:2048
	ds_read_b128 v[152:155], v152 offset:3072
	ds_read_b128 v[162:165], v174
	ds_read_b128 v[166:169], v174 offset:1024
	ds_read_b128 v[170:173], v174 offset:2048
	ds_read_b128 v[174:177], v174 offset:3072
	v_lshl_add_u64 v[210:211], s[38:39], 0, v[144:145]
	s_add_i32 m0, s13, 0xc000
	ds_read_b128 v[178:181], v161
	ds_read_b128 v[182:185], v161 offset:1024
	ds_read_b128 v[186:189], v161 offset:2048
	ds_read_b128 v[190:193], v161 offset:3072
	ds_read_b128 v[194:197], v161 offset:4096
	ds_read_b128 v[198:201], v161 offset:5120
	ds_read_b128 v[202:205], v161 offset:6144
	ds_read_b128 v[206:209], v161 offset:7168
	global_load_lds_dwordx4 v[210:211], off
	v_lshl_add_u64 v[210:211], s[38:39], 0, v[146:147]
	s_add_i32 m0, s13, 0xe000
	s_nop 0
	global_load_lds_dwordx4 v[210:211], off
	s_waitcnt vmcnt(8)
	s_waitcnt lgkmcnt(0)
	s_setprio 1
	s_barrier
	v_mfma_f32_16x16x32_bf16 v[126:129], v[130:133], v[178:181], 0
	v_mfma_f32_16x16x32_bf16 v[122:125], v[148:151], v[178:181], 0
	v_mfma_f32_16x16x32_bf16 v[110:113], v[130:133], v[186:189], 0
	v_mfma_f32_16x16x32_bf16 v[106:109], v[148:151], v[186:189], 0
	v_mfma_f32_16x16x32_bf16 v[94:97], v[130:133], v[194:197], 0
	v_mfma_f32_16x16x32_bf16 v[90:93], v[148:151], v[194:197], 0
	v_mfma_f32_16x16x32_bf16 v[78:81], v[130:133], v[202:205], 0
	v_mfma_f32_16x16x32_bf16 v[74:77], v[148:151], v[202:205], 0
	v_mfma_f32_16x16x32_bf16 v[126:129], v[134:137], v[182:185], v[126:129]
	v_mfma_f32_16x16x32_bf16 v[122:125], v[152:155], v[182:185], v[122:125]
	v_mfma_f32_16x16x32_bf16 v[110:113], v[134:137], v[190:193], v[110:113]
	v_mfma_f32_16x16x32_bf16 v[106:109], v[152:155], v[190:193], v[106:109]
	v_mfma_f32_16x16x32_bf16 v[94:97], v[134:137], v[198:201], v[94:97]
	v_mfma_f32_16x16x32_bf16 v[90:93], v[152:155], v[198:201], v[90:93]
	v_mfma_f32_16x16x32_bf16 v[78:81], v[134:137], v[206:209], v[78:81]
	v_mfma_f32_16x16x32_bf16 v[74:77], v[152:155], v[206:209], v[74:77]
	v_mfma_f32_16x16x32_bf16 v[118:121], v[162:165], v[178:181], 0
	v_mfma_f32_16x16x32_bf16 v[114:117], v[170:173], v[178:181], 0
	v_mfma_f32_16x16x32_bf16 v[102:105], v[162:165], v[186:189], 0
	v_mfma_f32_16x16x32_bf16 v[98:101], v[170:173], v[186:189], 0
	v_mfma_f32_16x16x32_bf16 v[86:89], v[162:165], v[194:197], 0
	v_mfma_f32_16x16x32_bf16 v[82:85], v[170:173], v[194:197], 0
	v_mfma_f32_16x16x32_bf16 v[70:73], v[162:165], v[202:205], 0
	v_mfma_f32_16x16x32_bf16 v[66:69], v[170:173], v[202:205], 0
	v_mfma_f32_16x16x32_bf16 v[118:121], v[166:169], v[182:185], v[118:121]
	v_mfma_f32_16x16x32_bf16 v[114:117], v[174:177], v[182:185], v[114:117]
	v_mfma_f32_16x16x32_bf16 v[102:105], v[166:169], v[190:193], v[102:105]
	v_mfma_f32_16x16x32_bf16 v[98:101], v[174:177], v[190:193], v[98:101]
	v_mfma_f32_16x16x32_bf16 v[86:89], v[166:169], v[198:201], v[86:89]
	v_mfma_f32_16x16x32_bf16 v[82:85], v[174:177], v[198:201], v[82:85]
	v_mfma_f32_16x16x32_bf16 v[70:73], v[166:169], v[206:209], v[70:73]
	v_mfma_f32_16x16x32_bf16 v[66:69], v[174:177], v[206:209], v[66:69]
	s_barrier
	s_setprio 0
	s_add_i32 s6, s91, s12
	v_lshl_add_u64 v[210:211], s[16:17], 0, v[16:17]
	s_mov_b32 m0, s6
	ds_read_b128 v[178:181], v161 offset:16384
	ds_read_b128 v[182:185], v161 offset:17408
	ds_read_b128 v[186:189], v161 offset:18432
	ds_read_b128 v[190:193], v161 offset:19456
	ds_read_b128 v[194:197], v161 offset:20480
	ds_read_b128 v[198:201], v161 offset:21504
	ds_read_b128 v[202:205], v161 offset:22528
	ds_read_b128 v[206:209], v161 offset:23552
	global_load_lds_dwordx4 v[210:211], off
	s_add_i32 m0, s6, 0x2000
	s_add_u32 s6, s16, 0x100000
	v_lshl_add_u64 v[212:213], s[16:17], 0, v[138:139]
	s_addc_u32 s7, s17, 0
	s_add_i32 s91, s94, s12
	global_load_lds_dwordx4 v[212:213], off
	v_lshl_add_u64 v[214:215], s[6:7], 0, v[16:17]
	s_mov_b32 m0, s91
	v_lshl_add_u64 v[216:217], s[40:41], 0, v[140:141]
	global_load_lds_dwordx4 v[214:215], off
	v_lshl_add_u64 v[214:215], s[6:7], 0, v[138:139]
	s_add_i32 m0, s91, 0x2000
	s_nop 0
	global_load_lds_dwordx4 v[214:215], off
	v_lshl_add_u64 v[214:215], s[40:41], 0, v[142:143]
	s_mov_b32 m0, s13
	s_nop 0
	global_load_lds_dwordx4 v[214:215], off
	s_mov_b32 m0, s42
	s_nop 0
	global_load_lds_dwordx4 v[216:217], off
	s_waitcnt vmcnt(8)
	s_waitcnt lgkmcnt(0)
	s_setprio 1
	s_barrier
; #define PG8_STAGEA(bufoff, gbase, voff) PG8_STAGE_X(bufoff, gbase, voff, AUXA)
; #define PG8_LDA(dst, b, h) do { _Pragma("unroll") for (int m = 0; m < 4; ++m) _Pragma("unroll") for (int k = 0; k < 2; ++k) dst[m][k] = *(const PG8_LAS bf16x8*)(lds + PG8_SA(b, h) + aoff + m * 2048 + k * 1024); } while (0)
; #define PG8_LDB(dst, b, h) do { _Pragma("unroll") for (int n = 0; n < 2; ++n) _Pragma("unroll") for (int k = 0; k < 2; ++k) dst[n][k] = *(const PG8_LAS bf16x8*)(lds + PG8_SB(b, h) + boff + n * 2048 + k * 1024); } while (0)
; #define PG8_MMA(ai, bj, At, Bt) do { if (GEMM_PRIO_MODE == 0) __builtin_amdgcn_s_setprio(1); PG8_MMA_LOOPS \
;         acc[ai][bj][m][n] = __builtin_amdgcn_mfma_f32_16x16x32_bf16(Bt[n][k], At[m][k], acc[ai][bj][m][n], 0, 0, 0); if (GEMM_PRIO_MODE == 0) __builtin_amdgcn_s_setprio(0); } while (0)
; #define PG8_WAIT_V(n) asm volatile("s_waitcnt vmcnt(" #n ")" ::: "memory")
; #define PG8_WAIT_L(n) asm volatile("s_waitcnt lgkmcnt(" #n ")" ::: "memory")
; #define PG8_BAR __builtin_amdgcn_s_barrier()
; #define PG8_SCHED __builtin_amdgcn_sched_barrier(0)
;     ...
;             PG8_WAIT_V(8); PG8_WAIT_L(0); PG8_BAR; PG8_MMA(1, 0, At, B0); PG8_MMA(1, 1, At, B1); PG8_BAR; PG8_SCHED;
;     ...
;             PG8_LDB(B0, 1, 0); PG8_LDB(B1, 1, 1); PG8_SCHED; PG8_LDA(At, 1, 0); PG8_STAGEA(PG8_SA(0, 1), a2 + hstepA, voffA);
;             PG8_WAIT_V(8); PG8_WAIT_L(0); PG8_BAR; PG8_MMA(0, 0, At, B0); PG8_MMA(0, 1, At, B1); PG8_BAR; PG8_SCHED;
	v_mfma_f32_16x16x32_bf16 v[62:65], v[130:133], v[178:181], 0
	v_mfma_f32_16x16x32_bf16 v[58:61], v[148:151], v[178:181], 0
	v_mfma_f32_16x16x32_bf16 v[46:49], v[130:133], v[186:189], 0
	v_mfma_f32_16x16x32_bf16 v[42:45], v[148:151], v[186:189], 0
	v_mfma_f32_16x16x32_bf16 v[30:33], v[130:133], v[194:197], 0
	v_mfma_f32_16x16x32_bf16 v[26:29], v[148:151], v[194:197], 0
	v_mfma_f32_16x16x32_bf16 v[12:15], v[130:133], v[202:205], 0
	v_mfma_f32_16x16x32_bf16 v[8:11], v[148:151], v[202:205], 0
	v_mfma_f32_16x16x32_bf16 v[62:65], v[134:137], v[182:185], v[62:65]
	v_mfma_f32_16x16x32_bf16 v[58:61], v[152:155], v[182:185], v[58:61]
	v_mfma_f32_16x16x32_bf16 v[46:49], v[134:137], v[190:193], v[46:49]
	v_mfma_f32_16x16x32_bf16 v[42:45], v[152:155], v[190:193], v[42:45]
	v_mfma_f32_16x16x32_bf16 v[30:33], v[134:137], v[198:201], v[30:33]
	v_mfma_f32_16x16x32_bf16 v[26:29], v[152:155], v[198:201], v[26:29]
	v_mfma_f32_16x16x32_bf16 v[12:15], v[134:137], v[206:209], v[12:15]
	v_mfma_f32_16x16x32_bf16 v[8:11], v[152:155], v[206:209], v[8:11]
	v_mfma_f32_16x16x32_bf16 v[54:57], v[162:165], v[178:181], 0
	v_mfma_f32_16x16x32_bf16 v[50:53], v[170:173], v[178:181], 0
	v_mfma_f32_16x16x32_bf16 v[38:41], v[162:165], v[186:189], 0
	v_mfma_f32_16x16x32_bf16 v[34:37], v[170:173], v[186:189], 0
	v_mfma_f32_16x16x32_bf16 v[22:25], v[162:165], v[194:197], 0
	v_mfma_f32_16x16x32_bf16 v[18:21], v[170:173], v[194:197], 0
	v_mfma_f32_16x16x32_bf16 v[4:7], v[162:165], v[202:205], 0
	v_mfma_f32_16x16x32_bf16 v[0:3], v[170:173], v[202:205], 0
	v_mfma_f32_16x16x32_bf16 v[54:57], v[166:169], v[182:185], v[54:57]
	v_mfma_f32_16x16x32_bf16 v[50:53], v[174:177], v[182:185], v[50:53]
	v_mfma_f32_16x16x32_bf16 v[38:41], v[166:169], v[190:193], v[38:41]
	v_mfma_f32_16x16x32_bf16 v[34:37], v[174:177], v[190:193], v[34:37]
	v_mfma_f32_16x16x32_bf16 v[22:25], v[166:169], v[198:201], v[22:25]
	v_mfma_f32_16x16x32_bf16 v[18:21], v[174:177], v[198:201], v[18:21]
	v_mfma_f32_16x16x32_bf16 v[4:7], v[166:169], v[206:209], v[4:7]
	v_mfma_f32_16x16x32_bf16 v[0:3], v[174:177], v[206:209], v[0:3]
	s_barrier
	s_setprio 0
	s_add_i32 s91, 0, 0x18000
	s_add_i32 s94, 0, 0x1c000
	v_add_u32_e32 v152, s91, v157
	v_add_u32_e32 v174, s94, v157
	ds_read_b128 v[130:133], v152
	ds_read_b128 v[134:137], v152 offset:1024
	ds_read_b128 v[148:151], v152 offset:2048
	ds_read_b128 v[152:155], v152 offset:3072
	ds_read_b128 v[162:165], v174
	ds_read_b128 v[166:169], v174 offset:1024
	ds_read_b128 v[170:173], v174 offset:2048
	ds_read_b128 v[174:177], v174 offset:3072
	s_add_u32 s6, s40, 0x100000
	s_addc_u32 s7, s41, 0
	s_mov_b32 m0, s43
	v_lshl_add_u64 v[218:219], s[6:7], 0, v[142:143]
	ds_read_b128 v[178:181], v161 offset:32768
	ds_read_b128 v[182:185], v161 offset:33792
	ds_read_b128 v[186:189], v161 offset:34816
	ds_read_b128 v[190:193], v161 offset:35840
	ds_read_b128 v[194:197], v161 offset:36864
	ds_read_b128 v[198:201], v161 offset:37888
	ds_read_b128 v[202:205], v161 offset:38912
	ds_read_b128 v[206:209], v161 offset:39936
	global_load_lds_dwordx4 v[218:219], off
	v_lshl_add_u64 v[218:219], s[6:7], 0, v[140:141]
	s_mov_b32 m0, s50
	s_nop 0
	global_load_lds_dwordx4 v[218:219], off
	s_waitcnt vmcnt(8)
	s_waitcnt lgkmcnt(0)
	s_nop 0
	s_nop 0
	s_setprio 1
	s_barrier
	v_mfma_f32_16x16x32_bf16 v[126:129], v[130:133], v[178:181], v[126:129]
	v_mfma_f32_16x16x32_bf16 v[122:125], v[148:151], v[178:181], v[122:125]
	v_mfma_f32_16x16x32_bf16 v[110:113], v[130:133], v[186:189], v[110:113]
	v_mfma_f32_16x16x32_bf16 v[106:109], v[148:151], v[186:189], v[106:109]
	v_mfma_f32_16x16x32_bf16 v[94:97], v[130:133], v[194:197], v[94:97]
	v_mfma_f32_16x16x32_bf16 v[90:93], v[148:151], v[194:197], v[90:93]
	v_mfma_f32_16x16x32_bf16 v[78:81], v[130:133], v[202:205], v[78:81]
	v_mfma_f32_16x16x32_bf16 v[74:77], v[148:151], v[202:205], v[74:77]
	v_mfma_f32_16x16x32_bf16 v[126:129], v[134:137], v[182:185], v[126:129]
	v_mfma_f32_16x16x32_bf16 v[122:125], v[152:155], v[182:185], v[122:125]
	v_mfma_f32_16x16x32_bf16 v[110:113], v[134:137], v[190:193], v[110:113]
	v_mfma_f32_16x16x32_bf16 v[106:109], v[152:155], v[190:193], v[106:109]
	v_mfma_f32_16x16x32_bf16 v[94:97], v[134:137], v[198:201], v[94:97]
	v_mfma_f32_16x16x32_bf16 v[90:93], v[152:155], v[198:201], v[90:93]
	v_mfma_f32_16x16x32_bf16 v[78:81], v[134:137], v[206:209], v[78:81]
	v_mfma_f32_16x16x32_bf16 v[74:77], v[152:155], v[206:209], v[74:77]
	v_mfma_f32_16x16x32_bf16 v[118:121], v[162:165], v[178:181], v[118:121]
	v_mfma_f32_16x16x32_bf16 v[114:117], v[170:173], v[178:181], v[114:117]
	v_mfma_f32_16x16x32_bf16 v[102:105], v[162:165], v[186:189], v[102:105]
	v_mfma_f32_16x16x32_bf16 v[98:101], v[170:173], v[186:189], v[98:101]
	v_mfma_f32_16x16x32_bf16 v[86:89], v[162:165], v[194:197], v[86:89]
	v_mfma_f32_16x16x32_bf16 v[82:85], v[170:173], v[194:197], v[82:85]
	v_mfma_f32_16x16x32_bf16 v[70:73], v[162:165], v[202:205], v[70:73]
	v_mfma_f32_16x16x32_bf16 v[66:69], v[170:173], v[202:205], v[66:69]
	v_mfma_f32_16x16x32_bf16 v[118:121], v[166:169], v[182:185], v[118:121]
	v_mfma_f32_16x16x32_bf16 v[114:117], v[174:177], v[182:185], v[114:117]
	v_mfma_f32_16x16x32_bf16 v[102:105], v[166:169], v[190:193], v[102:105]
	v_mfma_f32_16x16x32_bf16 v[98:101], v[174:177], v[190:193], v[98:101]
	v_mfma_f32_16x16x32_bf16 v[86:89], v[166:169], v[198:201], v[86:89]
	v_mfma_f32_16x16x32_bf16 v[82:85], v[174:177], v[198:201], v[82:85]
	v_mfma_f32_16x16x32_bf16 v[70:73], v[166:169], v[206:209], v[70:73]
	v_mfma_f32_16x16x32_bf16 v[66:69], v[174:177], v[206:209], v[66:69]
	s_barrier
; #define PG8_STAGEA(bufoff, gbase, voff) PG8_STAGE_X(bufoff, gbase, voff, AUXA)
; #define PG8_STAGEB(bufoff, gbase, voff) PG8_STAGE_X(bufoff, gbase, voff, AUXB)
; #define PG8_LDA(dst, b, h) do { _Pragma("unroll") for (int m = 0; m < 4; ++m) _Pragma("unroll") for (int k = 0; k < 2; ++k) dst[m][k] = *(const PG8_LAS bf16x8*)(lds + PG8_SA(b, h) + aoff + m * 2048 + k * 1024); } while (0)
; #define PG8_WAIT_V(n) asm volatile("s_waitcnt vmcnt(" #n ")" ::: "memory")
; #define PG8_WAIT_L(n) asm volatile("s_waitcnt lgkmcnt(" #n ")" ::: "memory")
;     ...
;         for (int t = t0; t < nt; t += 2) {
;             const bool last = (t == nt - 2);
;             const char* a1 = cA + (size_t)(t + 1) * kstepA;
;             const char* a2 = last ? nA : cA + (size_t)(t + 2) * kstepA; const char* b2 = last ? nB : cB + (size_t)(t + 2) * kstepB;
;             const char* a3 = a2 + kstepA; const char* b3 = b2 + kstepB;
;             if (last && has_next) S.a_ready(nxt);
;             if constexpr (SP2) {
;             PG8_LDB(B0, 0, 0); PG8_LDB(B1, 0, 1); PG8_SCHED; PG8_LDA(At, 0, 0); PG8_STAGEA(PG8_SA(1, 1), a1 + hstepA, voffA);
;     ...
;             const int relax = __builtin_amdgcn_readfirstlane((t == 0 && ui > 0) ? 1 : 0);
;             PG8_WAIT_VR(8, 24, relax); PG8_WAIT_L(0); PG8_BAR; PG8_MMA(0, 0, At, B0); PG8_MMA(0, 1, At, B1); PG8_BAR; PG8_SCHED;
;     ...
;             PG8_WAIT_V(8); PG8_WAIT_L(0); PG8_BAR; PG8_MMA(0, 0, At, B0); PG8_MMA(0, 1, At, B1); PG8_BAR; PG8_SCHED;
;     ...
;             PG8_LDA(At, 0, 1); PG8_STAGEB(PG8_SB(0, 0), b2, voffB); PG8_STAGEB(PG8_SB(0, 1), b2 + hstepB, voffB); PG8_STAGEA(PG8_SA(0, 0), a2, voffA);
;     ...
;             PG8_WAIT_VR(8, 24, relax); PG8_WAIT_L(0); PG8_BAR; PG8_MMA(1, 0, At, B0); PG8_MMA(1, 1, At, B1); PG8_BAR; PG8_SCHED;
;     ...
;             PG8_WAIT_V(8); PG8_WAIT_L(0); PG8_BAR; PG8_MMA(1, 0, At, B0); PG8_MMA(1, 1, At, B1); PG8_BAR; PG8_SCHED;
;     ...
;             PG8_LDB(B0, 1, 0); PG8_LDB(B1, 1, 1); PG8_SCHED; PG8_LDA(At, 1, 0); PG8_STAGEA(PG8_SA(0, 1), a2 + hstepA, voffA);
;             PG8_WAIT_V(8); PG8_WAIT_L(0); PG8_BAR; PG8_MMA(0, 0, At, B0); PG8_MMA(0, 1, At, B1); PG8_BAR; PG8_SCHED;
;             PG8_LDA(At, 1, 1); PG8_STAGEB(PG8_SB(1, 0), b3, voffB); PG8_STAGEB(PG8_SB(1, 1), b3 + hstepB, voffB); PG8_STAGEA(PG8_SA(1, 0), a3, voffA);
;             PG8_WAIT_V(8); PG8_WAIT_L(0); PG8_BAR; PG8_MMA(1, 0, At, B0); PG8_MMA(1, 1, At, B1); PG8_BAR; PG8_SCHED;
	s_setprio 0
	s_add_i32 s6, s91, s12
	v_lshl_add_u64 v[210:211], v[210:211], 0, s[86:87]
	s_mov_b32 m0, s6
	ds_read_b128 v[178:181], v161 offset:49152
	ds_read_b128 v[182:185], v161 offset:50176
	ds_read_b128 v[186:189], v161 offset:51200
	ds_read_b128 v[190:193], v161 offset:52224
	ds_read_b128 v[194:197], v161 offset:53248
	ds_read_b128 v[198:201], v161 offset:54272
	ds_read_b128 v[202:205], v161 offset:55296
	ds_read_b128 v[206:209], v161 offset:56320
	global_load_lds_dwordx4 v[210:211], off
	s_add_i32 m0, s6, 0x2000
	s_add_u32 s6, s16, 0x100080
	v_lshl_add_u64 v[210:211], v[212:213], 0, s[86:87]
	s_addc_u32 s7, s17, 0
	s_add_i32 s16, s94, s12
	global_load_lds_dwordx4 v[210:211], off
	v_lshl_add_u64 v[210:211], s[6:7], 0, v[16:17]
	s_mov_b32 m0, s16
	s_nop 0
	global_load_lds_dwordx4 v[210:211], off
	v_lshl_add_u64 v[210:211], s[6:7], 0, v[138:139]
	s_add_i32 m0, s16, 0x2000
	s_nop 0
	global_load_lds_dwordx4 v[210:211], off
	v_lshl_add_u64 v[210:211], v[214:215], 0, s[86:87]
	s_mov_b32 m0, s68
	s_nop 0
	global_load_lds_dwordx4 v[210:211], off
	v_lshl_add_u64 v[210:211], v[216:217], 0, s[86:87]
	s_mov_b32 m0, s69
	s_nop 0
	global_load_lds_dwordx4 v[210:211], off
	s_waitcnt vmcnt(8)
	s_waitcnt lgkmcnt(0)
	s_nop 0
	s_setprio 1
	s_barrier
	v_mfma_f32_16x16x32_bf16 v[62:65], v[130:133], v[178:181], v[62:65]
	v_mfma_f32_16x16x32_bf16 v[58:61], v[148:151], v[178:181], v[58:61]
	v_mfma_f32_16x16x32_bf16 v[46:49], v[130:133], v[186:189], v[46:49]
	v_mfma_f32_16x16x32_bf16 v[42:45], v[148:151], v[186:189], v[42:45]
	v_mfma_f32_16x16x32_bf16 v[30:33], v[130:133], v[194:197], v[30:33]
	v_mfma_f32_16x16x32_bf16 v[26:29], v[148:151], v[194:197], v[26:29]
	v_mfma_f32_16x16x32_bf16 v[12:15], v[130:133], v[202:205], v[12:15]
	v_mfma_f32_16x16x32_bf16 v[8:11], v[148:151], v[202:205], v[8:11]
	v_mfma_f32_16x16x32_bf16 v[62:65], v[134:137], v[182:185], v[62:65]
	v_mfma_f32_16x16x32_bf16 v[58:61], v[152:155], v[182:185], v[58:61]
	v_mfma_f32_16x16x32_bf16 v[46:49], v[134:137], v[190:193], v[46:49]
	v_mfma_f32_16x16x32_bf16 v[42:45], v[152:155], v[190:193], v[42:45]
	v_mfma_f32_16x16x32_bf16 v[30:33], v[134:137], v[198:201], v[30:33]
	v_mfma_f32_16x16x32_bf16 v[26:29], v[152:155], v[198:201], v[26:29]
	v_mfma_f32_16x16x32_bf16 v[12:15], v[134:137], v[206:209], v[12:15]
	v_mfma_f32_16x16x32_bf16 v[8:11], v[152:155], v[206:209], v[8:11]
	v_mfma_f32_16x16x32_bf16 v[54:57], v[162:165], v[178:181], v[54:57]
	v_mfma_f32_16x16x32_bf16 v[50:53], v[170:173], v[178:181], v[50:53]
	v_mfma_f32_16x16x32_bf16 v[38:41], v[162:165], v[186:189], v[38:41]
	v_mfma_f32_16x16x32_bf16 v[34:37], v[170:173], v[186:189], v[34:37]
	v_mfma_f32_16x16x32_bf16 v[22:25], v[162:165], v[194:197], v[22:25]
	v_mfma_f32_16x16x32_bf16 v[18:21], v[170:173], v[194:197], v[18:21]
	v_mfma_f32_16x16x32_bf16 v[4:7], v[162:165], v[202:205], v[4:7]
	v_mfma_f32_16x16x32_bf16 v[0:3], v[170:173], v[202:205], v[0:3]
	v_mfma_f32_16x16x32_bf16 v[54:57], v[166:169], v[182:185], v[54:57]
	v_mfma_f32_16x16x32_bf16 v[50:53], v[174:177], v[182:185], v[50:53]
	v_mfma_f32_16x16x32_bf16 v[38:41], v[166:169], v[190:193], v[38:41]
	v_mfma_f32_16x16x32_bf16 v[34:37], v[174:177], v[190:193], v[34:37]
	v_mfma_f32_16x16x32_bf16 v[22:25], v[166:169], v[198:201], v[22:25]
	v_mfma_f32_16x16x32_bf16 v[18:21], v[174:177], v[198:201], v[18:21]
	v_mfma_f32_16x16x32_bf16 v[4:7], v[166:169], v[206:209], v[4:7]
	v_mfma_f32_16x16x32_bf16 v[0:3], v[174:177], v[206:209], v[0:3]
	s_barrier
	s_setprio 0
	s_add_i32 s90, s90, 2
	s_add_u32 s38, s38, 0x100
	s_addc_u32 s39, s39, 0
	s_add_u32 s0, s0, 0x100
	s_addc_u32 s1, s1, 0
	v_add_u32_e32 v220, 0x10000, v157
.LBB0_558:
	s_add_u32 s6, s38, 0xfff00080
	s_addc_u32 s7, s39, -1
	s_add_i32 s91, 0, 0x10000
	s_cmp_eq_u32 s90, 60
	s_cselect_b32 s41, s21, s7
	s_cselect_b32 s40, s82, s6
	s_cselect_b32 s17, s23, s1
	s_cselect_b32 s16, s83, s0
	s_add_i32 s94, 0, 0x14000
	ds_read_b128 v[130:133], v220
	ds_read_b128 v[134:137], v220 offset:1024
	ds_read_b128 v[148:151], v220 offset:2048
	ds_read_b128 v[152:155], v220 offset:3072
	ds_read_b128 v[162:165], v220 offset:16384
	ds_read_b128 v[166:169], v220 offset:17408
	ds_read_b128 v[170:173], v220 offset:18432
	ds_read_b128 v[174:177], v220 offset:19456
	s_add_i32 m0, s13, 0xc000
	ds_read_b128 v[178:181], v161
	ds_read_b128 v[182:185], v161 offset:1024
	ds_read_b128 v[186:189], v161 offset:2048
	ds_read_b128 v[190:193], v161 offset:3072
	ds_read_b128 v[194:197], v161 offset:4096
	ds_read_b128 v[198:201], v161 offset:5120
	ds_read_b128 v[202:205], v161 offset:6144
	ds_read_b128 v[206:209], v161 offset:7168
	global_load_lds_dwordx4 v144, s[38:39]
	s_add_i32 m0, s13, 0xe000
	s_nop 0
	global_load_lds_dwordx4 v146, s[38:39]
	s_waitcnt vmcnt(8)
	s_waitcnt lgkmcnt(0)
	s_setprio 1
	s_barrier
; #define PG8_STAGEA(bufoff, gbase, voff) PG8_STAGE_X(bufoff, gbase, voff, AUXA)
; #define PG8_STAGEB(bufoff, gbase, voff) PG8_STAGE_X(bufoff, gbase, voff, AUXB)
; #define PG8_LDA(dst, b, h) do { _Pragma("unroll") for (int m = 0; m < 4; ++m) _Pragma("unroll") for (int k = 0; k < 2; ++k) dst[m][k] = *(const PG8_LAS bf16x8*)(lds + PG8_SA(b, h) + aoff + m * 2048 + k * 1024); } while (0)
; #define PG8_MMA(ai, bj, At, Bt) do { if (GEMM_PRIO_MODE == 0) __builtin_amdgcn_s_setprio(1); PG8_MMA_LOOPS \
;         acc[ai][bj][m][n] = __builtin_amdgcn_mfma_f32_16x16x32_bf16(Bt[n][k], At[m][k], acc[ai][bj][m][n], 0, 0, 0); if (GEMM_PRIO_MODE == 0) __builtin_amdgcn_s_setprio(0); } while (0)
; #define PG8_WAIT_V(n) asm volatile("s_waitcnt vmcnt(" #n ")" ::: "memory")
; #define PG8_WAIT_VR(n, nr, flag) asm volatile("s_cmp_eq_u32 %0, 0\n\ts_cbranch_scc1 .Lpg8s%=\n\ts_waitcnt vmcnt(" #nr ")\n\ts_branch .Lpg8d%=\n.Lpg8s%=:\n\ts_waitcnt vmcnt(" #n ")\n.Lpg8d%=:" :: "s"(flag) : "memory", "scc")
; #define PG8_WAIT_L(n) asm volatile("s_waitcnt lgkmcnt(" #n ")" ::: "memory")
; #define PG8_BAR __builtin_amdgcn_s_barrier()
; #define PG8_SCHED __builtin_amdgcn_sched_barrier(0)
;     ...
;             PG8_WAIT_V(8); PG8_WAIT_L(0); PG8_BAR; PG8_MMA(0, 0, At, B0); PG8_MMA(0, 1, At, B1); PG8_BAR; PG8_SCHED;
;     ...
;             PG8_LDA(At, 0, 1); PG8_STAGEB(PG8_SB(0, 0), b2, voffB); PG8_STAGEB(PG8_SB(0, 1), b2 + hstepB, voffB); PG8_STAGEA(PG8_SA(0, 0), a2, voffA);
;     ...
;             PG8_WAIT_VR(8, 24, relax); PG8_WAIT_L(0); PG8_BAR; PG8_MMA(1, 0, At, B0); PG8_MMA(1, 1, At, B1); PG8_BAR; PG8_SCHED;
;     ...
;             PG8_WAIT_V(8); PG8_WAIT_L(0); PG8_BAR; PG8_MMA(1, 0, At, B0); PG8_MMA(1, 1, At, B1); PG8_BAR; PG8_SCHED;
	v_mfma_f32_16x16x32_bf16 v[126:129], v[130:133], v[178:181], v[126:129]
	v_mfma_f32_16x16x32_bf16 v[122:125], v[148:151], v[178:181], v[122:125]
	v_mfma_f32_16x16x32_bf16 v[110:113], v[130:133], v[186:189], v[110:113]
	v_mfma_f32_16x16x32_bf16 v[106:109], v[148:151], v[186:189], v[106:109]
	v_mfma_f32_16x16x32_bf16 v[94:97], v[130:133], v[194:197], v[94:97]
	v_mfma_f32_16x16x32_bf16 v[90:93], v[148:151], v[194:197], v[90:93]
	v_mfma_f32_16x16x32_bf16 v[78:81], v[130:133], v[202:205], v[78:81]
	v_mfma_f32_16x16x32_bf16 v[74:77], v[148:151], v[202:205], v[74:77]
	v_mfma_f32_16x16x32_bf16 v[126:129], v[134:137], v[182:185], v[126:129]
	v_mfma_f32_16x16x32_bf16 v[122:125], v[152:155], v[182:185], v[122:125]
	v_mfma_f32_16x16x32_bf16 v[110:113], v[134:137], v[190:193], v[110:113]
	v_mfma_f32_16x16x32_bf16 v[106:109], v[152:155], v[190:193], v[106:109]
	v_mfma_f32_16x16x32_bf16 v[94:97], v[134:137], v[198:201], v[94:97]
	v_mfma_f32_16x16x32_bf16 v[90:93], v[152:155], v[198:201], v[90:93]
	v_mfma_f32_16x16x32_bf16 v[78:81], v[134:137], v[206:209], v[78:81]
	v_mfma_f32_16x16x32_bf16 v[74:77], v[152:155], v[206:209], v[74:77]
	v_mfma_f32_16x16x32_bf16 v[118:121], v[162:165], v[178:181], v[118:121]
	v_mfma_f32_16x16x32_bf16 v[114:117], v[170:173], v[178:181], v[114:117]
	v_mfma_f32_16x16x32_bf16 v[102:105], v[162:165], v[186:189], v[102:105]
	v_mfma_f32_16x16x32_bf16 v[98:101], v[170:173], v[186:189], v[98:101]
	v_mfma_f32_16x16x32_bf16 v[86:89], v[162:165], v[194:197], v[86:89]
	v_mfma_f32_16x16x32_bf16 v[82:85], v[170:173], v[194:197], v[82:85]
	v_mfma_f32_16x16x32_bf16 v[70:73], v[162:165], v[202:205], v[70:73]
	v_mfma_f32_16x16x32_bf16 v[66:69], v[170:173], v[202:205], v[66:69]
	v_mfma_f32_16x16x32_bf16 v[118:121], v[166:169], v[182:185], v[118:121]
	v_mfma_f32_16x16x32_bf16 v[114:117], v[174:177], v[182:185], v[114:117]
	v_mfma_f32_16x16x32_bf16 v[102:105], v[166:169], v[190:193], v[102:105]
	v_mfma_f32_16x16x32_bf16 v[98:101], v[174:177], v[190:193], v[98:101]
	v_mfma_f32_16x16x32_bf16 v[86:89], v[166:169], v[198:201], v[86:89]
	v_mfma_f32_16x16x32_bf16 v[82:85], v[174:177], v[198:201], v[82:85]
	v_mfma_f32_16x16x32_bf16 v[70:73], v[166:169], v[206:209], v[70:73]
	v_mfma_f32_16x16x32_bf16 v[66:69], v[174:177], v[206:209], v[66:69]
	s_barrier
	s_setprio 0
	s_add_i32 s6, s91, s12
	s_mov_b32 m0, s6
	ds_read_b128 v[178:181], v161 offset:16384
	ds_read_b128 v[182:185], v161 offset:17408
	ds_read_b128 v[186:189], v161 offset:18432
	ds_read_b128 v[190:193], v161 offset:19456
	ds_read_b128 v[194:197], v161 offset:20480
	ds_read_b128 v[198:201], v161 offset:21504
	ds_read_b128 v[202:205], v161 offset:22528
	ds_read_b128 v[206:209], v161 offset:23552
	global_load_lds_dwordx4 v16, s[16:17]
	s_add_i32 m0, s6, 0x2000
	s_add_u32 s6, s16, 0x100000
	s_addc_u32 s7, s17, 0
	s_add_i32 s91, s94, s12
	global_load_lds_dwordx4 v138, s[16:17]
	s_mov_b32 m0, s91
	s_nop 0
	global_load_lds_dwordx4 v16, s[6:7]
	s_add_i32 m0, s91, 0x2000
	s_nop 0
	global_load_lds_dwordx4 v138, s[6:7]
	s_mov_b32 m0, s13
	s_nop 0
	global_load_lds_dwordx4 v142, s[40:41]
	s_mov_b32 m0, s42
	s_nop 0
	global_load_lds_dwordx4 v140, s[40:41]
	s_waitcnt vmcnt(8)
	s_waitcnt lgkmcnt(0)
	s_nop 0
	s_setprio 1
	s_barrier
	v_mfma_f32_16x16x32_bf16 v[62:65], v[130:133], v[178:181], v[62:65]
	v_mfma_f32_16x16x32_bf16 v[58:61], v[148:151], v[178:181], v[58:61]
	v_mfma_f32_16x16x32_bf16 v[46:49], v[130:133], v[186:189], v[46:49]
	v_mfma_f32_16x16x32_bf16 v[42:45], v[148:151], v[186:189], v[42:45]
	v_mfma_f32_16x16x32_bf16 v[30:33], v[130:133], v[194:197], v[30:33]
	v_mfma_f32_16x16x32_bf16 v[26:29], v[148:151], v[194:197], v[26:29]
	v_mfma_f32_16x16x32_bf16 v[12:15], v[130:133], v[202:205], v[12:15]
	v_mfma_f32_16x16x32_bf16 v[8:11], v[148:151], v[202:205], v[8:11]
	v_mfma_f32_16x16x32_bf16 v[62:65], v[134:137], v[182:185], v[62:65]
	v_mfma_f32_16x16x32_bf16 v[58:61], v[152:155], v[182:185], v[58:61]
	v_mfma_f32_16x16x32_bf16 v[46:49], v[134:137], v[190:193], v[46:49]
	v_mfma_f32_16x16x32_bf16 v[42:45], v[152:155], v[190:193], v[42:45]
	v_mfma_f32_16x16x32_bf16 v[30:33], v[134:137], v[198:201], v[30:33]
	v_mfma_f32_16x16x32_bf16 v[26:29], v[152:155], v[198:201], v[26:29]
	v_mfma_f32_16x16x32_bf16 v[12:15], v[134:137], v[206:209], v[12:15]
	v_mfma_f32_16x16x32_bf16 v[8:11], v[152:155], v[206:209], v[8:11]
	v_mfma_f32_16x16x32_bf16 v[54:57], v[162:165], v[178:181], v[54:57]
	v_mfma_f32_16x16x32_bf16 v[50:53], v[170:173], v[178:181], v[50:53]
	v_mfma_f32_16x16x32_bf16 v[38:41], v[162:165], v[186:189], v[38:41]
	v_mfma_f32_16x16x32_bf16 v[34:37], v[170:173], v[186:189], v[34:37]
	v_mfma_f32_16x16x32_bf16 v[22:25], v[162:165], v[194:197], v[22:25]
	v_mfma_f32_16x16x32_bf16 v[18:21], v[170:173], v[194:197], v[18:21]
	v_mfma_f32_16x16x32_bf16 v[4:7], v[162:165], v[202:205], v[4:7]
	v_mfma_f32_16x16x32_bf16 v[0:3], v[170:173], v[202:205], v[0:3]
	v_mfma_f32_16x16x32_bf16 v[54:57], v[166:169], v[182:185], v[54:57]
	v_mfma_f32_16x16x32_bf16 v[50:53], v[174:177], v[182:185], v[50:53]
	v_mfma_f32_16x16x32_bf16 v[38:41], v[166:169], v[190:193], v[38:41]
	v_mfma_f32_16x16x32_bf16 v[34:37], v[174:177], v[190:193], v[34:37]
	v_mfma_f32_16x16x32_bf16 v[22:25], v[166:169], v[198:201], v[22:25]
	v_mfma_f32_16x16x32_bf16 v[18:21], v[174:177], v[198:201], v[18:21]
	v_mfma_f32_16x16x32_bf16 v[4:7], v[166:169], v[206:209], v[4:7]
	v_mfma_f32_16x16x32_bf16 v[0:3], v[174:177], v[206:209], v[0:3]
	s_barrier
; #define PG8_STAGEA(bufoff, gbase, voff) PG8_STAGE_X(bufoff, gbase, voff, AUXA)
; #define PG8_STAGEB(bufoff, gbase, voff) PG8_STAGE_X(bufoff, gbase, voff, AUXB)
; #define PG8_LDA(dst, b, h) do { _Pragma("unroll") for (int m = 0; m < 4; ++m) _Pragma("unroll") for (int k = 0; k < 2; ++k) dst[m][k] = *(const PG8_LAS bf16x8*)(lds + PG8_SA(b, h) + aoff + m * 2048 + k * 1024); } while (0)
; #define PG8_LDB(dst, b, h) do { _Pragma("unroll") for (int n = 0; n < 2; ++n) _Pragma("unroll") for (int k = 0; k < 2; ++k) dst[n][k] = *(const PG8_LAS bf16x8*)(lds + PG8_SB(b, h) + boff + n * 2048 + k * 1024); } while (0)
; #define PG8_MMA(ai, bj, At, Bt) do { if (GEMM_PRIO_MODE == 0) __builtin_amdgcn_s_setprio(1); PG8_MMA_LOOPS \
;         acc[ai][bj][m][n] = __builtin_amdgcn_mfma_f32_16x16x32_bf16(Bt[n][k], At[m][k], acc[ai][bj][m][n], 0, 0, 0); if (GEMM_PRIO_MODE == 0) __builtin_amdgcn_s_setprio(0); } while (0)
; #define PG8_WAIT_V(n) asm volatile("s_waitcnt vmcnt(" #n ")" ::: "memory")
; #define PG8_WAIT_L(n) asm volatile("s_waitcnt lgkmcnt(" #n ")" ::: "memory")
; #define PG8_BAR __builtin_amdgcn_s_barrier()
; #define PG8_SCHED __builtin_amdgcn_sched_barrier(0)
;     ...
;             PG8_LDB(B0, 1, 0); PG8_LDB(B1, 1, 1); PG8_SCHED; PG8_LDA(At, 1, 0); PG8_STAGEA(PG8_SA(0, 1), a2 + hstepA, voffA);
;             PG8_WAIT_V(8); PG8_WAIT_L(0); PG8_BAR; PG8_MMA(0, 0, At, B0); PG8_MMA(0, 1, At, B1); PG8_BAR; PG8_SCHED;
;             PG8_LDA(At, 1, 1); PG8_STAGEB(PG8_SB(1, 0), b3, voffB); PG8_STAGEB(PG8_SB(1, 1), b3 + hstepB, voffB); PG8_STAGEA(PG8_SA(1, 0), a3, voffA);
;             PG8_WAIT_V(8); PG8_WAIT_L(0); PG8_BAR; PG8_MMA(1, 0, At, B0); PG8_MMA(1, 1, At, B1); PG8_BAR; PG8_SCHED;
	s_setprio 0
	s_add_i32 s91, 0, 0x18000
	s_add_i32 s94, 0, 0x1c000
	ds_read_b128 v[130:133], v220 offset:32768
	ds_read_b128 v[134:137], v220 offset:33792
	ds_read_b128 v[148:151], v220 offset:34816
	ds_read_b128 v[152:155], v220 offset:35840
	ds_read_b128 v[162:165], v220 offset:49152
	ds_read_b128 v[166:169], v220 offset:50176
	ds_read_b128 v[170:173], v220 offset:51200
	ds_read_b128 v[174:177], v220 offset:52224
	s_add_u32 s6, s40, 0x100000
	s_addc_u32 s7, s41, 0
	s_mov_b32 m0, s43
	ds_read_b128 v[178:181], v161 offset:32768
	ds_read_b128 v[182:185], v161 offset:33792
	ds_read_b128 v[186:189], v161 offset:34816
	ds_read_b128 v[190:193], v161 offset:35840
	ds_read_b128 v[194:197], v161 offset:36864
	ds_read_b128 v[198:201], v161 offset:37888
	ds_read_b128 v[202:205], v161 offset:38912
	ds_read_b128 v[206:209], v161 offset:39936
	global_load_lds_dwordx4 v142, s[6:7]
	s_mov_b32 m0, s50
	s_nop 0
	global_load_lds_dwordx4 v140, s[6:7]
	s_waitcnt vmcnt(8)
	s_waitcnt lgkmcnt(0)
	s_setprio 1
	s_barrier
	v_mfma_f32_16x16x32_bf16 v[126:129], v[130:133], v[178:181], v[126:129]
	v_mfma_f32_16x16x32_bf16 v[122:125], v[148:151], v[178:181], v[122:125]
	v_mfma_f32_16x16x32_bf16 v[110:113], v[130:133], v[186:189], v[110:113]
	v_mfma_f32_16x16x32_bf16 v[106:109], v[148:151], v[186:189], v[106:109]
	v_mfma_f32_16x16x32_bf16 v[94:97], v[130:133], v[194:197], v[94:97]
	v_mfma_f32_16x16x32_bf16 v[90:93], v[148:151], v[194:197], v[90:93]
	v_mfma_f32_16x16x32_bf16 v[78:81], v[130:133], v[202:205], v[78:81]
	v_mfma_f32_16x16x32_bf16 v[74:77], v[148:151], v[202:205], v[74:77]
	v_mfma_f32_16x16x32_bf16 v[126:129], v[134:137], v[182:185], v[126:129]
	v_mfma_f32_16x16x32_bf16 v[122:125], v[152:155], v[182:185], v[122:125]
	v_mfma_f32_16x16x32_bf16 v[110:113], v[134:137], v[190:193], v[110:113]
	v_mfma_f32_16x16x32_bf16 v[106:109], v[152:155], v[190:193], v[106:109]
	v_mfma_f32_16x16x32_bf16 v[94:97], v[134:137], v[198:201], v[94:97]
	v_mfma_f32_16x16x32_bf16 v[90:93], v[152:155], v[198:201], v[90:93]
	v_mfma_f32_16x16x32_bf16 v[78:81], v[134:137], v[206:209], v[78:81]
	v_mfma_f32_16x16x32_bf16 v[74:77], v[152:155], v[206:209], v[74:77]
	v_mfma_f32_16x16x32_bf16 v[118:121], v[162:165], v[178:181], v[118:121]
	v_mfma_f32_16x16x32_bf16 v[114:117], v[170:173], v[178:181], v[114:117]
	v_mfma_f32_16x16x32_bf16 v[102:105], v[162:165], v[186:189], v[102:105]
	v_mfma_f32_16x16x32_bf16 v[98:101], v[170:173], v[186:189], v[98:101]
	v_mfma_f32_16x16x32_bf16 v[86:89], v[162:165], v[194:197], v[86:89]
	v_mfma_f32_16x16x32_bf16 v[82:85], v[170:173], v[194:197], v[82:85]
	v_mfma_f32_16x16x32_bf16 v[70:73], v[162:165], v[202:205], v[70:73]
	v_mfma_f32_16x16x32_bf16 v[66:69], v[170:173], v[202:205], v[66:69]
	v_mfma_f32_16x16x32_bf16 v[118:121], v[166:169], v[182:185], v[118:121]
	v_mfma_f32_16x16x32_bf16 v[114:117], v[174:177], v[182:185], v[114:117]
	v_mfma_f32_16x16x32_bf16 v[102:105], v[166:169], v[190:193], v[102:105]
	v_mfma_f32_16x16x32_bf16 v[98:101], v[174:177], v[190:193], v[98:101]
	v_mfma_f32_16x16x32_bf16 v[86:89], v[166:169], v[198:201], v[86:89]
	v_mfma_f32_16x16x32_bf16 v[82:85], v[174:177], v[198:201], v[82:85]
	v_mfma_f32_16x16x32_bf16 v[70:73], v[166:169], v[206:209], v[70:73]
	v_mfma_f32_16x16x32_bf16 v[66:69], v[174:177], v[206:209], v[66:69]
	s_barrier
	s_setprio 0
	s_add_i32 s6, s91, s12
	s_mov_b32 m0, s6
	ds_read_b128 v[178:181], v161 offset:49152
	ds_read_b128 v[182:185], v161 offset:50176
	ds_read_b128 v[186:189], v161 offset:51200
	ds_read_b128 v[190:193], v161 offset:52224
	ds_read_b128 v[194:197], v161 offset:53248
	ds_read_b128 v[198:201], v161 offset:54272
	ds_read_b128 v[202:205], v161 offset:55296
	ds_read_b128 v[206:209], v161 offset:56320
	s_add_u32 s100, s16, 0x80
	s_addc_u32 s101, s17, 0
	global_load_lds_dwordx4 v16, s[100:101]
	s_add_i32 m0, s6, 0x2000
	s_add_u32 s6, s16, 0x100080
	s_addc_u32 s7, s17, 0
	s_add_i32 s16, s94, s12
	global_load_lds_dwordx4 v138, s[100:101]
	s_mov_b32 m0, s16
	s_nop 0
	global_load_lds_dwordx4 v16, s[6:7]
	s_add_i32 m0, s16, 0x2000
	s_nop 0
	global_load_lds_dwordx4 v138, s[6:7]
	s_mov_b32 m0, s68
	s_nop 0
	s_add_u32 vcc_lo, s40, 0x80
	s_addc_u32 vcc_hi, s41, 0
	global_load_lds_dwordx4 v142, vcc
	s_mov_b32 m0, s69
	s_nop 0
	global_load_lds_dwordx4 v140, vcc
	s_waitcnt vmcnt(8)
	s_waitcnt lgkmcnt(0)
	s_nop 0
	s_setprio 1
	s_barrier
	v_mfma_f32_16x16x32_bf16 v[62:65], v[130:133], v[178:181], v[62:65]
	v_mfma_f32_16x16x32_bf16 v[58:61], v[148:151], v[178:181], v[58:61]
	v_mfma_f32_16x16x32_bf16 v[46:49], v[130:133], v[186:189], v[46:49]
	v_mfma_f32_16x16x32_bf16 v[42:45], v[148:151], v[186:189], v[42:45]
	v_mfma_f32_16x16x32_bf16 v[30:33], v[130:133], v[194:197], v[30:33]
	v_mfma_f32_16x16x32_bf16 v[26:29], v[148:151], v[194:197], v[26:29]
	v_mfma_f32_16x16x32_bf16 v[12:15], v[130:133], v[202:205], v[12:15]
	v_mfma_f32_16x16x32_bf16 v[8:11], v[148:151], v[202:205], v[8:11]
	v_mfma_f32_16x16x32_bf16 v[62:65], v[134:137], v[182:185], v[62:65]
	v_mfma_f32_16x16x32_bf16 v[58:61], v[152:155], v[182:185], v[58:61]
	v_mfma_f32_16x16x32_bf16 v[46:49], v[134:137], v[190:193], v[46:49]
	v_mfma_f32_16x16x32_bf16 v[42:45], v[152:155], v[190:193], v[42:45]
	v_mfma_f32_16x16x32_bf16 v[30:33], v[134:137], v[198:201], v[30:33]
	v_mfma_f32_16x16x32_bf16 v[26:29], v[152:155], v[198:201], v[26:29]
	v_mfma_f32_16x16x32_bf16 v[12:15], v[134:137], v[206:209], v[12:15]
	v_mfma_f32_16x16x32_bf16 v[8:11], v[152:155], v[206:209], v[8:11]
	v_mfma_f32_16x16x32_bf16 v[54:57], v[162:165], v[178:181], v[54:57]
	v_mfma_f32_16x16x32_bf16 v[50:53], v[170:173], v[178:181], v[50:53]
	v_mfma_f32_16x16x32_bf16 v[38:41], v[162:165], v[186:189], v[38:41]
	v_mfma_f32_16x16x32_bf16 v[34:37], v[170:173], v[186:189], v[34:37]
	v_mfma_f32_16x16x32_bf16 v[22:25], v[162:165], v[194:197], v[22:25]
	v_mfma_f32_16x16x32_bf16 v[18:21], v[170:173], v[194:197], v[18:21]
	v_mfma_f32_16x16x32_bf16 v[4:7], v[162:165], v[202:205], v[4:7]
	v_mfma_f32_16x16x32_bf16 v[0:3], v[170:173], v[202:205], v[0:3]
	v_mfma_f32_16x16x32_bf16 v[54:57], v[166:169], v[182:185], v[54:57]
	v_mfma_f32_16x16x32_bf16 v[50:53], v[174:177], v[182:185], v[50:53]
	v_mfma_f32_16x16x32_bf16 v[38:41], v[166:169], v[190:193], v[38:41]
	v_mfma_f32_16x16x32_bf16 v[34:37], v[174:177], v[190:193], v[34:37]
	v_mfma_f32_16x16x32_bf16 v[22:25], v[166:169], v[198:201], v[22:25]
	v_mfma_f32_16x16x32_bf16 v[18:21], v[174:177], v[198:201], v[18:21]
	v_mfma_f32_16x16x32_bf16 v[4:7], v[166:169], v[206:209], v[4:7]
	v_mfma_f32_16x16x32_bf16 v[0:3], v[174:177], v[206:209], v[0:3]
	s_barrier
	s_setprio 0
	s_add_i32 s90, s90, 2
	s_add_u32 s38, s38, 0x100
	s_addc_u32 s39, s39, 0
	s_add_u32 s0, s0, 0x100
	s_addc_u32 s1, s1, 0
	s_cmp_gt_u32 s90, 61
	s_cbranch_scc0 .LBB0_558
	s_and_b64 vcc, exec, s[18:19]
	s_cbranch_vccz .LBB0_561
	s_barrier

; #define PG8_STAGEA(bufoff, gbase, voff) PG8_STAGE_X(bufoff, gbase, voff, AUXA)
; #define PG8_STR(x) PG8_STR2(x)
;     ...
;         const bool has_next = S.next(ui + 1, nxt);
;         const char* nA = has_next ? (const char*)g.A + (size_t)nxt.pm * tstepA : cA; const char* nB = has_next ? (const char*)g.Bt + (size_t)nxt.pn * tstepB : cB;
;         int t0 = 0;
;         if constexpr (SP2 && GEMM_RELAX == 1) { if (ui > 0) {
;             const char* a1 = cA + kstepA; const char* a2 = cA + 2 * kstepA; const char* b2 = cB + 2 * kstepB; const char* a3 = a2 + kstepA; const char* b3 = b2 + kstepB;
;             PG8_LDB(B0, 0, 0); PG8_LDB(B1, 0, 1); PG8_SCHED; PG8_LDA(At, 0, 0); PG8_STAGEA(PG8_SA(1, 1), a1 + hstepA, voffA);
;             PG8_WAIT_V(24); PG8_WAIT_L(0); PG8_BAR; PG8_MMA(0, 0, At, B0); PG8_MMA(0, 1, At, B1); PG8_BAR; PG8_SCHED;
;             PG8_LDA(At, 0, 1); PG8_STAGEB(PG8_SB(0, 0), b2, voffB); PG8_STAGEB(PG8_SB(0, 1), b2 + hstepB, voffB); PG8_STAGEA(PG8_SA(0, 0), a2, voffA);
;             PG8_WAIT_V(24); PG8_WAIT_L(0); PG8_BAR; PG8_MMA(1, 0, At, B0); PG8_MMA(1, 1, At, B1); PG8_BAR; PG8_SCHED;
;             PG8_LDB(B0, 1, 0); PG8_LDB(B1, 1, 1); PG8_SCHED; PG8_LDA(At, 1, 0); PG8_STAGEA(PG8_SA(0, 1), a2 + hstepA, voffA);
;             PG8_WAIT_V(8); PG8_WAIT_L(0); PG8_BAR; PG8_MMA(0, 0, At, B0); PG8_MMA(0, 1, At, B1); PG8_BAR; PG8_SCHED;
;             PG8_LDA(At, 1, 1); PG8_STAGEB(PG8_SB(1, 0), b3, voffB); PG8_STAGEB(PG8_SB(1, 1), b3 + hstepB, voffB); PG8_STAGEA(PG8_SA(1, 0), a3, voffA);
;             PG8_WAIT_V(8); PG8_WAIT_L(0); PG8_BAR; PG8_MMA(1, 0, At, B0); PG8_MMA(1, 1, At, B1); PG8_BAR; PG8_SCHED;
;             t0 = 2; } }
;     ...
;         asm volatile(".p2align " PG8_STR(GEMM_LOOP_ALIGN) ::: "memory");
;     ...
;         for (int t = t0; t < nt; t += 2) {
;             const bool last = (t == nt - 2);
;             const char* a1 = cA + (size_t)(t + 1) * kstepA;
;             const char* a2 = last ? nA : cA + (size_t)(t + 2) * kstepA; const char* b2 = last ? nB : cB + (size_t)(t + 2) * kstepB;
;             const char* a3 = a2 + kstepA; const char* b3 = b2 + kstepB;
;             if (last && has_next) S.a_ready(nxt);
;             if constexpr (SP2) {
;             PG8_LDB(B0, 0, 0); PG8_LDB(B1, 0, 1); PG8_SCHED; PG8_LDA(At, 0, 0); PG8_STAGEA(PG8_SA(1, 1), a1 + hstepA, voffA);
;     ...
;             const int relax = __builtin_amdgcn_readfirstlane((t == 0 && ui > 0) ? 1 : 0);
.LBB0_711:
	s_ashr_i32 s25, s24, 31
	s_lshl_b64 s[0:1], s[24:25], 21
	s_add_u32 s26, s56, s0
	s_addc_u32 s27, s57, s1
	s_and_b64 s[0:1], s[10:11], exec
	s_cselect_b32 s0, s27, s13
	s_cselect_b32 s1, s26, s12
	s_ashr_i32 s23, s22, 31
	s_lshl_b64 s[6:7], s[22:23], 21
	s_add_u32 s36, s51, s6
	s_addc_u32 s37, s68, s7
	s_and_b64 s[6:7], s[10:11], exec
	s_cselect_b32 s23, s37, s43
	s_cselect_b32 s25, s36, s42
	s_add_u32 s40, s12, 0x100080
	s_addc_u32 s41, s13, 0
	s_add_u32 s12, s42, 0x100
	s_addc_u32 s13, s43, 0
	s_mov_b32 s39, -2
	s_add_u32 s6, s40, 0xfff00080
	s_addc_u32 s7, s41, -1
	s_add_i32 s95, 0, 0x10000
	s_cmp_eq_u32 s39, 60
	s_cselect_b32 s43, s0, s7
	s_cselect_b32 s42, s1, s6
	v_add_u32_e32 v144, s95, v146
	s_cselect_b32 s17, s23, s13
	s_cselect_b32 s16, s25, s12
	s_add_i32 vcc_lo, 0, 0x14000
	ds_read_b128 v[150:153], v144
	ds_read_b128 v[154:157], v144 offset:1024
	ds_read_b128 v[158:161], v144 offset:2048
	ds_read_b128 v[162:165], v144 offset:3072
	v_add_u32_e32 v144, vcc_lo, v146
	ds_read_b128 v[166:169], v144
	ds_read_b128 v[170:173], v144 offset:1024
	ds_read_b128 v[174:177], v144 offset:2048
	ds_read_b128 v[178:181], v144 offset:3072
	v_lshl_add_u64 v[144:145], s[40:41], 0, v[140:141]
	s_add_i32 m0, s69, 0xc000
	ds_read_b128 v[182:185], v148
	ds_read_b128 v[186:189], v148 offset:1024
	ds_read_b128 v[190:193], v148 offset:2048
	ds_read_b128 v[194:197], v148 offset:3072
	ds_read_b128 v[198:201], v148 offset:4096
	ds_read_b128 v[202:205], v148 offset:5120
	ds_read_b128 v[206:209], v148 offset:6144
	ds_read_b128 v[210:213], v148 offset:7168
	global_load_lds_dwordx4 v[144:145], off
	v_lshl_add_u64 v[144:145], s[40:41], 0, v[142:143]
	s_add_i32 m0, s69, 0xe000
	s_nop 0
	global_load_lds_dwordx4 v[144:145], off
	s_waitcnt vmcnt(8)
	s_waitcnt lgkmcnt(0)
	s_nop 0
	s_setprio 1
	s_barrier
	v_mfma_f32_16x16x32_bf16 v[126:129], v[150:153], v[182:185], 0
	v_mfma_f32_16x16x32_bf16 v[122:125], v[158:161], v[182:185], 0
	v_mfma_f32_16x16x32_bf16 v[110:113], v[150:153], v[190:193], 0
	v_mfma_f32_16x16x32_bf16 v[106:109], v[158:161], v[190:193], 0
	v_mfma_f32_16x16x32_bf16 v[94:97], v[150:153], v[198:201], 0
	v_mfma_f32_16x16x32_bf16 v[90:93], v[158:161], v[198:201], 0
	v_mfma_f32_16x16x32_bf16 v[78:81], v[150:153], v[206:209], 0
	v_mfma_f32_16x16x32_bf16 v[74:77], v[158:161], v[206:209], 0
	v_mfma_f32_16x16x32_bf16 v[126:129], v[154:157], v[186:189], v[126:129]
	v_mfma_f32_16x16x32_bf16 v[122:125], v[162:165], v[186:189], v[122:125]
	v_mfma_f32_16x16x32_bf16 v[110:113], v[154:157], v[194:197], v[110:113]
	v_mfma_f32_16x16x32_bf16 v[106:109], v[162:165], v[194:197], v[106:109]
	v_mfma_f32_16x16x32_bf16 v[94:97], v[154:157], v[202:205], v[94:97]
	v_mfma_f32_16x16x32_bf16 v[90:93], v[162:165], v[202:205], v[90:93]
	v_mfma_f32_16x16x32_bf16 v[78:81], v[154:157], v[210:213], v[78:81]
	v_mfma_f32_16x16x32_bf16 v[74:77], v[162:165], v[210:213], v[74:77]
	v_mfma_f32_16x16x32_bf16 v[118:121], v[166:169], v[182:185], 0
	v_mfma_f32_16x16x32_bf16 v[114:117], v[174:177], v[182:185], 0
	v_mfma_f32_16x16x32_bf16 v[102:105], v[166:169], v[190:193], 0
	v_mfma_f32_16x16x32_bf16 v[98:101], v[174:177], v[190:193], 0
	v_mfma_f32_16x16x32_bf16 v[86:89], v[166:169], v[198:201], 0
	v_mfma_f32_16x16x32_bf16 v[82:85], v[174:177], v[198:201], 0
	v_mfma_f32_16x16x32_bf16 v[70:73], v[166:169], v[206:209], 0
	v_mfma_f32_16x16x32_bf16 v[66:69], v[174:177], v[206:209], 0
	v_mfma_f32_16x16x32_bf16 v[118:121], v[170:173], v[186:189], v[118:121]
	v_mfma_f32_16x16x32_bf16 v[114:117], v[178:181], v[186:189], v[114:117]
	v_mfma_f32_16x16x32_bf16 v[102:105], v[170:173], v[194:197], v[102:105]
	v_mfma_f32_16x16x32_bf16 v[98:101], v[178:181], v[194:197], v[98:101]
	v_mfma_f32_16x16x32_bf16 v[86:89], v[170:173], v[202:205], v[86:89]
	v_mfma_f32_16x16x32_bf16 v[82:85], v[178:181], v[202:205], v[82:85]
	v_mfma_f32_16x16x32_bf16 v[70:73], v[170:173], v[210:213], v[70:73]
	v_mfma_f32_16x16x32_bf16 v[66:69], v[178:181], v[210:213], v[66:69]
	s_barrier
	s_setprio 0
	s_add_i32 s6, s95, s50
	v_lshl_add_u64 v[144:145], s[16:17], 0, v[134:135]
	s_mov_b32 m0, s6
	ds_read_b128 v[182:185], v148 offset:16384
	ds_read_b128 v[186:189], v148 offset:17408
	ds_read_b128 v[190:193], v148 offset:18432
	ds_read_b128 v[194:197], v148 offset:19456
	ds_read_b128 v[198:201], v148 offset:20480
	ds_read_b128 v[202:205], v148 offset:21504
	ds_read_b128 v[206:209], v148 offset:22528
	ds_read_b128 v[210:213], v148 offset:23552
	global_load_lds_dwordx4 v[144:145], off
	s_add_i32 m0, s6, 0x2000
	s_add_u32 s6, s16, 0x100000
	v_lshl_add_u64 v[214:215], s[16:17], 0, v[130:131]
	s_addc_u32 s7, s17, 0
	s_add_i32 s95, vcc_lo, s50
	global_load_lds_dwordx4 v[214:215], off
	v_lshl_add_u64 v[216:217], s[6:7], 0, v[134:135]
	s_mov_b32 m0, s95
	v_lshl_add_u64 v[218:219], s[42:43], 0, v[132:133]
	global_load_lds_dwordx4 v[216:217], off
	v_lshl_add_u64 v[216:217], s[6:7], 0, v[130:131]
	s_add_i32 m0, s95, 0x2000
	s_nop 0
	global_load_lds_dwordx4 v[216:217], off
	v_lshl_add_u64 v[216:217], s[42:43], 0, v[136:137]
	s_mov_b32 m0, s69
	s_nop 0
	global_load_lds_dwordx4 v[216:217], off
	s_mov_b32 m0, s72
	s_nop 0
	global_load_lds_dwordx4 v[218:219], off
	s_waitcnt vmcnt(8)
	s_waitcnt lgkmcnt(0)
	s_setprio 1
	s_barrier
; #define PG8_STAGEA(bufoff, gbase, voff) PG8_STAGE_X(bufoff, gbase, voff, AUXA)
; #define PG8_LDA(dst, b, h) do { _Pragma("unroll") for (int m = 0; m < 4; ++m) _Pragma("unroll") for (int k = 0; k < 2; ++k) dst[m][k] = *(const PG8_LAS bf16x8*)(lds + PG8_SA(b, h) + aoff + m * 2048 + k * 1024); } while (0)
; #define PG8_LDB(dst, b, h) do { _Pragma("unroll") for (int n = 0; n < 2; ++n) _Pragma("unroll") for (int k = 0; k < 2; ++k) dst[n][k] = *(const PG8_LAS bf16x8*)(lds + PG8_SB(b, h) + boff + n * 2048 + k * 1024); } while (0)
; #define PG8_MMA(ai, bj, At, Bt) do { if (GEMM_PRIO_MODE == 0) __builtin_amdgcn_s_setprio(1); PG8_MMA_LOOPS \
;         acc[ai][bj][m][n] = __builtin_amdgcn_mfma_f32_16x16x32_bf16(Bt[n][k], At[m][k], acc[ai][bj][m][n], 0, 0, 0); if (GEMM_PRIO_MODE == 0) __builtin_amdgcn_s_setprio(0); } while (0)
; #define PG8_WAIT_V(n) asm volatile("s_waitcnt vmcnt(" #n ")" ::: "memory")
; #define PG8_WAIT_L(n) asm volatile("s_waitcnt lgkmcnt(" #n ")" ::: "memory")
; #define PG8_BAR __builtin_amdgcn_s_barrier()
; #define PG8_SCHED __builtin_amdgcn_sched_barrier(0)
;     ...
;             PG8_WAIT_V(8); PG8_WAIT_L(0); PG8_BAR; PG8_MMA(1, 0, At, B0); PG8_MMA(1, 1, At, B1); PG8_BAR; PG8_SCHED;
;     ...
;             PG8_LDB(B0, 1, 0); PG8_LDB(B1, 1, 1); PG8_SCHED; PG8_LDA(At, 1, 0); PG8_STAGEA(PG8_SA(0, 1), a2 + hstepA, voffA);
;             PG8_WAIT_V(8); PG8_WAIT_L(0); PG8_BAR; PG8_MMA(0, 0, At, B0); PG8_MMA(0, 1, At, B1); PG8_BAR; PG8_SCHED;
	v_mfma_f32_16x16x32_bf16 v[62:65], v[150:153], v[182:185], 0
	v_mfma_f32_16x16x32_bf16 v[58:61], v[158:161], v[182:185], 0
	v_mfma_f32_16x16x32_bf16 v[46:49], v[150:153], v[190:193], 0
	v_mfma_f32_16x16x32_bf16 v[42:45], v[158:161], v[190:193], 0
	v_mfma_f32_16x16x32_bf16 v[30:33], v[150:153], v[198:201], 0
	v_mfma_f32_16x16x32_bf16 v[26:29], v[158:161], v[198:201], 0
	v_mfma_f32_16x16x32_bf16 v[12:15], v[150:153], v[206:209], 0
	v_mfma_f32_16x16x32_bf16 v[8:11], v[158:161], v[206:209], 0
	v_mfma_f32_16x16x32_bf16 v[62:65], v[154:157], v[186:189], v[62:65]
	v_mfma_f32_16x16x32_bf16 v[58:61], v[162:165], v[186:189], v[58:61]
	v_mfma_f32_16x16x32_bf16 v[46:49], v[154:157], v[194:197], v[46:49]
	v_mfma_f32_16x16x32_bf16 v[42:45], v[162:165], v[194:197], v[42:45]
	v_mfma_f32_16x16x32_bf16 v[30:33], v[154:157], v[202:205], v[30:33]
	v_mfma_f32_16x16x32_bf16 v[26:29], v[162:165], v[202:205], v[26:29]
	v_mfma_f32_16x16x32_bf16 v[12:15], v[154:157], v[210:213], v[12:15]
	v_mfma_f32_16x16x32_bf16 v[8:11], v[162:165], v[210:213], v[8:11]
	v_mfma_f32_16x16x32_bf16 v[54:57], v[166:169], v[182:185], 0
	v_mfma_f32_16x16x32_bf16 v[50:53], v[174:177], v[182:185], 0
	v_mfma_f32_16x16x32_bf16 v[38:41], v[166:169], v[190:193], 0
	v_mfma_f32_16x16x32_bf16 v[34:37], v[174:177], v[190:193], 0
	v_mfma_f32_16x16x32_bf16 v[22:25], v[166:169], v[198:201], 0
	v_mfma_f32_16x16x32_bf16 v[18:21], v[174:177], v[198:201], 0
	v_mfma_f32_16x16x32_bf16 v[4:7], v[166:169], v[206:209], 0
	v_mfma_f32_16x16x32_bf16 v[0:3], v[174:177], v[206:209], 0
	v_mfma_f32_16x16x32_bf16 v[54:57], v[170:173], v[186:189], v[54:57]
	v_mfma_f32_16x16x32_bf16 v[50:53], v[178:181], v[186:189], v[50:53]
	v_mfma_f32_16x16x32_bf16 v[38:41], v[170:173], v[194:197], v[38:41]
	v_mfma_f32_16x16x32_bf16 v[34:37], v[178:181], v[194:197], v[34:37]
	v_mfma_f32_16x16x32_bf16 v[22:25], v[170:173], v[202:205], v[22:25]
	v_mfma_f32_16x16x32_bf16 v[18:21], v[178:181], v[202:205], v[18:21]
	v_mfma_f32_16x16x32_bf16 v[4:7], v[170:173], v[210:213], v[4:7]
	v_mfma_f32_16x16x32_bf16 v[0:3], v[178:181], v[210:213], v[0:3]
	s_barrier
	s_setprio 0
	s_add_i32 s95, 0, 0x18000
	v_add_u32_e32 v149, s95, v146
	s_add_i32 vcc_lo, 0, 0x1c000
	ds_read_b128 v[150:153], v149
	ds_read_b128 v[154:157], v149 offset:1024
	ds_read_b128 v[158:161], v149 offset:2048
	ds_read_b128 v[162:165], v149 offset:3072
	v_add_u32_e32 v149, vcc_lo, v146
	ds_read_b128 v[166:169], v149
	ds_read_b128 v[170:173], v149 offset:1024
	ds_read_b128 v[174:177], v149 offset:2048
	ds_read_b128 v[178:181], v149 offset:3072
	s_add_u32 s6, s42, 0x100000
	s_addc_u32 s7, s43, 0
	s_mov_b32 m0, s73
	v_lshl_add_u64 v[220:221], s[6:7], 0, v[136:137]
	ds_read_b128 v[182:185], v148 offset:32768
	ds_read_b128 v[186:189], v148 offset:33792
	ds_read_b128 v[190:193], v148 offset:34816
	ds_read_b128 v[194:197], v148 offset:35840
	ds_read_b128 v[198:201], v148 offset:36864
	ds_read_b128 v[202:205], v148 offset:37888
	ds_read_b128 v[206:209], v148 offset:38912
	ds_read_b128 v[210:213], v148 offset:39936
	global_load_lds_dwordx4 v[220:221], off
	v_lshl_add_u64 v[220:221], s[6:7], 0, v[132:133]
	s_mov_b32 m0, s82
	s_nop 0
	global_load_lds_dwordx4 v[220:221], off
	s_waitcnt vmcnt(8)
	s_waitcnt lgkmcnt(0)
	s_setprio 1
	s_barrier
	v_mfma_f32_16x16x32_bf16 v[126:129], v[150:153], v[182:185], v[126:129]
	v_mfma_f32_16x16x32_bf16 v[122:125], v[158:161], v[182:185], v[122:125]
	v_mfma_f32_16x16x32_bf16 v[110:113], v[150:153], v[190:193], v[110:113]
	v_mfma_f32_16x16x32_bf16 v[106:109], v[158:161], v[190:193], v[106:109]
	v_mfma_f32_16x16x32_bf16 v[94:97], v[150:153], v[198:201], v[94:97]
	v_mfma_f32_16x16x32_bf16 v[90:93], v[158:161], v[198:201], v[90:93]
	v_mfma_f32_16x16x32_bf16 v[78:81], v[150:153], v[206:209], v[78:81]
	v_mfma_f32_16x16x32_bf16 v[74:77], v[158:161], v[206:209], v[74:77]
	v_mfma_f32_16x16x32_bf16 v[126:129], v[154:157], v[186:189], v[126:129]
	v_mfma_f32_16x16x32_bf16 v[122:125], v[162:165], v[186:189], v[122:125]
	v_mfma_f32_16x16x32_bf16 v[110:113], v[154:157], v[194:197], v[110:113]
	v_mfma_f32_16x16x32_bf16 v[106:109], v[162:165], v[194:197], v[106:109]
	v_mfma_f32_16x16x32_bf16 v[94:97], v[154:157], v[202:205], v[94:97]
	v_mfma_f32_16x16x32_bf16 v[90:93], v[162:165], v[202:205], v[90:93]
	v_mfma_f32_16x16x32_bf16 v[78:81], v[154:157], v[210:213], v[78:81]
	v_mfma_f32_16x16x32_bf16 v[74:77], v[162:165], v[210:213], v[74:77]
	v_mfma_f32_16x16x32_bf16 v[118:121], v[166:169], v[182:185], v[118:121]
	v_mfma_f32_16x16x32_bf16 v[114:117], v[174:177], v[182:185], v[114:117]
	v_mfma_f32_16x16x32_bf16 v[102:105], v[166:169], v[190:193], v[102:105]
	v_mfma_f32_16x16x32_bf16 v[98:101], v[174:177], v[190:193], v[98:101]
	v_mfma_f32_16x16x32_bf16 v[86:89], v[166:169], v[198:201], v[86:89]
	v_mfma_f32_16x16x32_bf16 v[82:85], v[174:177], v[198:201], v[82:85]
	v_mfma_f32_16x16x32_bf16 v[70:73], v[166:169], v[206:209], v[70:73]
	v_mfma_f32_16x16x32_bf16 v[66:69], v[174:177], v[206:209], v[66:69]
	v_mfma_f32_16x16x32_bf16 v[118:121], v[170:173], v[186:189], v[118:121]
	v_mfma_f32_16x16x32_bf16 v[114:117], v[178:181], v[186:189], v[114:117]
	v_mfma_f32_16x16x32_bf16 v[102:105], v[170:173], v[194:197], v[102:105]
	v_mfma_f32_16x16x32_bf16 v[98:101], v[178:181], v[194:197], v[98:101]
	v_mfma_f32_16x16x32_bf16 v[86:89], v[170:173], v[202:205], v[86:89]
	v_mfma_f32_16x16x32_bf16 v[82:85], v[178:181], v[202:205], v[82:85]
	v_mfma_f32_16x16x32_bf16 v[70:73], v[170:173], v[210:213], v[70:73]
	v_mfma_f32_16x16x32_bf16 v[66:69], v[178:181], v[210:213], v[66:69]
	s_barrier
; #define PG8_STAGEA(bufoff, gbase, voff) PG8_STAGE_X(bufoff, gbase, voff, AUXA)
; #define PG8_STAGEB(bufoff, gbase, voff) PG8_STAGE_X(bufoff, gbase, voff, AUXB)
; #define PG8_LDA(dst, b, h) do { _Pragma("unroll") for (int m = 0; m < 4; ++m) _Pragma("unroll") for (int k = 0; k < 2; ++k) dst[m][k] = *(const PG8_LAS bf16x8*)(lds + PG8_SA(b, h) + aoff + m * 2048 + k * 1024); } while (0)
; #define PG8_WAIT_V(n) asm volatile("s_waitcnt vmcnt(" #n ")" ::: "memory")
; #define PG8_WAIT_L(n) asm volatile("s_waitcnt lgkmcnt(" #n ")" ::: "memory")
;     ...
;         for (int t = t0; t < nt; t += 2) {
;             const bool last = (t == nt - 2);
;             const char* a1 = cA + (size_t)(t + 1) * kstepA;
;             const char* a2 = last ? nA : cA + (size_t)(t + 2) * kstepA; const char* b2 = last ? nB : cB + (size_t)(t + 2) * kstepB;
;             const char* a3 = a2 + kstepA; const char* b3 = b2 + kstepB;
;             if (last && has_next) S.a_ready(nxt);
;             if constexpr (SP2) {
;             PG8_LDB(B0, 0, 0); PG8_LDB(B1, 0, 1); PG8_SCHED; PG8_LDA(At, 0, 0); PG8_STAGEA(PG8_SA(1, 1), a1 + hstepA, voffA);
;     ...
;             const int relax = __builtin_amdgcn_readfirstlane((t == 0 && ui > 0) ? 1 : 0);
;             PG8_WAIT_VR(8, 24, relax); PG8_WAIT_L(0); PG8_BAR; PG8_MMA(0, 0, At, B0); PG8_MMA(0, 1, At, B1); PG8_BAR; PG8_SCHED;
;     ...
;             PG8_WAIT_V(8); PG8_WAIT_L(0); PG8_BAR; PG8_MMA(0, 0, At, B0); PG8_MMA(0, 1, At, B1); PG8_BAR; PG8_SCHED;
;     ...
;             PG8_LDA(At, 0, 1); PG8_STAGEB(PG8_SB(0, 0), b2, voffB); PG8_STAGEB(PG8_SB(0, 1), b2 + hstepB, voffB); PG8_STAGEA(PG8_SA(0, 0), a2, voffA);
;     ...
;             PG8_WAIT_VR(8, 24, relax); PG8_WAIT_L(0); PG8_BAR; PG8_MMA(1, 0, At, B0); PG8_MMA(1, 1, At, B1); PG8_BAR; PG8_SCHED;
;     ...
;             PG8_WAIT_V(8); PG8_WAIT_L(0); PG8_BAR; PG8_MMA(1, 0, At, B0); PG8_MMA(1, 1, At, B1); PG8_BAR; PG8_SCHED;
;     ...
;             PG8_LDB(B0, 1, 0); PG8_LDB(B1, 1, 1); PG8_SCHED; PG8_LDA(At, 1, 0); PG8_STAGEA(PG8_SA(0, 1), a2 + hstepA, voffA);
;             PG8_WAIT_V(8); PG8_WAIT_L(0); PG8_BAR; PG8_MMA(0, 0, At, B0); PG8_MMA(0, 1, At, B1); PG8_BAR; PG8_SCHED;
;             PG8_LDA(At, 1, 1); PG8_STAGEB(PG8_SB(1, 0), b3, voffB); PG8_STAGEB(PG8_SB(1, 1), b3 + hstepB, voffB); PG8_STAGEA(PG8_SA(1, 0), a3, voffA);
;             PG8_WAIT_V(8); PG8_WAIT_L(0); PG8_BAR; PG8_MMA(1, 0, At, B0); PG8_MMA(1, 1, At, B1); PG8_BAR; PG8_SCHED;
	s_setprio 0
	s_add_i32 s6, s95, s50
	v_lshl_add_u64 v[144:145], v[144:145], 0, s[86:87]
	s_mov_b32 m0, s6
	ds_read_b128 v[182:185], v148 offset:49152
	ds_read_b128 v[186:189], v148 offset:50176
	ds_read_b128 v[190:193], v148 offset:51200
	ds_read_b128 v[194:197], v148 offset:52224
	ds_read_b128 v[198:201], v148 offset:53248
	ds_read_b128 v[202:205], v148 offset:54272
	ds_read_b128 v[206:209], v148 offset:55296
	ds_read_b128 v[210:213], v148 offset:56320
	global_load_lds_dwordx4 v[144:145], off
	s_add_i32 m0, s6, 0x2000
	s_add_u32 s6, s16, 0x100080
	v_lshl_add_u64 v[144:145], v[214:215], 0, s[86:87]
	s_addc_u32 s7, s17, 0
	s_add_i32 s16, vcc_lo, s50
	global_load_lds_dwordx4 v[144:145], off
	v_lshl_add_u64 v[144:145], s[6:7], 0, v[134:135]
	s_mov_b32 m0, s16
	s_nop 0
	global_load_lds_dwordx4 v[144:145], off
	v_lshl_add_u64 v[144:145], s[6:7], 0, v[130:131]
	s_add_i32 m0, s16, 0x2000
	s_nop 0
	global_load_lds_dwordx4 v[144:145], off
	v_lshl_add_u64 v[144:145], v[216:217], 0, s[86:87]
	s_mov_b32 m0, s83
	s_nop 0
	global_load_lds_dwordx4 v[144:145], off
	v_lshl_add_u64 v[144:145], v[218:219], 0, s[86:87]
	s_mov_b32 m0, s90
	s_nop 0
	global_load_lds_dwordx4 v[144:145], off
	s_waitcnt vmcnt(8)
	s_waitcnt lgkmcnt(0)
	s_nop 0
	s_setprio 1
	s_barrier
	v_mfma_f32_16x16x32_bf16 v[62:65], v[150:153], v[182:185], v[62:65]
	v_mfma_f32_16x16x32_bf16 v[58:61], v[158:161], v[182:185], v[58:61]
	v_mfma_f32_16x16x32_bf16 v[46:49], v[150:153], v[190:193], v[46:49]
	v_mfma_f32_16x16x32_bf16 v[42:45], v[158:161], v[190:193], v[42:45]
	v_mfma_f32_16x16x32_bf16 v[30:33], v[150:153], v[198:201], v[30:33]
	v_mfma_f32_16x16x32_bf16 v[26:29], v[158:161], v[198:201], v[26:29]
	v_mfma_f32_16x16x32_bf16 v[12:15], v[150:153], v[206:209], v[12:15]
	v_mfma_f32_16x16x32_bf16 v[8:11], v[158:161], v[206:209], v[8:11]
	v_mfma_f32_16x16x32_bf16 v[62:65], v[154:157], v[186:189], v[62:65]
	v_mfma_f32_16x16x32_bf16 v[58:61], v[162:165], v[186:189], v[58:61]
	v_mfma_f32_16x16x32_bf16 v[46:49], v[154:157], v[194:197], v[46:49]
	v_mfma_f32_16x16x32_bf16 v[42:45], v[162:165], v[194:197], v[42:45]
	v_mfma_f32_16x16x32_bf16 v[30:33], v[154:157], v[202:205], v[30:33]
	v_mfma_f32_16x16x32_bf16 v[26:29], v[162:165], v[202:205], v[26:29]
	v_mfma_f32_16x16x32_bf16 v[12:15], v[154:157], v[210:213], v[12:15]
	v_mfma_f32_16x16x32_bf16 v[8:11], v[162:165], v[210:213], v[8:11]
	v_mfma_f32_16x16x32_bf16 v[54:57], v[166:169], v[182:185], v[54:57]
	v_mfma_f32_16x16x32_bf16 v[50:53], v[174:177], v[182:185], v[50:53]
	v_mfma_f32_16x16x32_bf16 v[38:41], v[166:169], v[190:193], v[38:41]
	v_mfma_f32_16x16x32_bf16 v[34:37], v[174:177], v[190:193], v[34:37]
	v_mfma_f32_16x16x32_bf16 v[22:25], v[166:169], v[198:201], v[22:25]
	v_mfma_f32_16x16x32_bf16 v[18:21], v[174:177], v[198:201], v[18:21]
	v_mfma_f32_16x16x32_bf16 v[4:7], v[166:169], v[206:209], v[4:7]
	v_mfma_f32_16x16x32_bf16 v[0:3], v[174:177], v[206:209], v[0:3]
	v_mfma_f32_16x16x32_bf16 v[54:57], v[170:173], v[186:189], v[54:57]
	v_mfma_f32_16x16x32_bf16 v[50:53], v[178:181], v[186:189], v[50:53]
	v_mfma_f32_16x16x32_bf16 v[38:41], v[170:173], v[194:197], v[38:41]
	v_mfma_f32_16x16x32_bf16 v[34:37], v[178:181], v[194:197], v[34:37]
	v_mfma_f32_16x16x32_bf16 v[22:25], v[170:173], v[202:205], v[22:25]
	v_mfma_f32_16x16x32_bf16 v[18:21], v[178:181], v[202:205], v[18:21]
	v_mfma_f32_16x16x32_bf16 v[4:7], v[170:173], v[210:213], v[4:7]
	v_mfma_f32_16x16x32_bf16 v[0:3], v[178:181], v[210:213], v[0:3]
	s_barrier
	s_setprio 0
	s_add_i32 s39, s39, 2
	s_add_u32 s40, s40, 0x100
	s_addc_u32 s41, s41, 0
	s_add_u32 s12, s12, 0x100
	s_addc_u32 s13, s13, 0
	v_add_u32_e32 v222, 0x10000, v146
.LBB0_712:
	s_add_u32 s6, s40, 0xfff00080
	s_addc_u32 s7, s41, -1
	s_add_i32 s95, 0, 0x10000
	s_cmp_eq_u32 s39, 60
	s_cselect_b32 s43, s0, s7
	s_cselect_b32 s42, s1, s6
	s_cselect_b32 s17, s23, s13
	s_cselect_b32 s16, s25, s12
	s_add_i32 vcc_lo, 0, 0x14000
	ds_read_b128 v[150:153], v222
	ds_read_b128 v[154:157], v222 offset:1024
	ds_read_b128 v[158:161], v222 offset:2048
	ds_read_b128 v[162:165], v222 offset:3072
	ds_read_b128 v[166:169], v222 offset:16384
	ds_read_b128 v[170:173], v222 offset:17408
	ds_read_b128 v[174:177], v222 offset:18432
	ds_read_b128 v[178:181], v222 offset:19456
	s_add_i32 m0, s69, 0xc000
	ds_read_b128 v[182:185], v148
	ds_read_b128 v[186:189], v148 offset:1024
	ds_read_b128 v[190:193], v148 offset:2048
	ds_read_b128 v[194:197], v148 offset:3072
	ds_read_b128 v[198:201], v148 offset:4096
	ds_read_b128 v[202:205], v148 offset:5120
	ds_read_b128 v[206:209], v148 offset:6144
	ds_read_b128 v[210:213], v148 offset:7168
	global_load_lds_dwordx4 v140, s[40:41]
	s_add_i32 m0, s69, 0xe000
	s_nop 0
	global_load_lds_dwordx4 v142, s[40:41]
	s_waitcnt vmcnt(8)
	s_waitcnt lgkmcnt(0)
	s_nop 0
	s_nop 0
	s_setprio 1
	s_barrier
; #define PG8_STAGEA(bufoff, gbase, voff) PG8_STAGE_X(bufoff, gbase, voff, AUXA)
; #define PG8_STAGEB(bufoff, gbase, voff) PG8_STAGE_X(bufoff, gbase, voff, AUXB)
; #define PG8_LDA(dst, b, h) do { _Pragma("unroll") for (int m = 0; m < 4; ++m) _Pragma("unroll") for (int k = 0; k < 2; ++k) dst[m][k] = *(const PG8_LAS bf16x8*)(lds + PG8_SA(b, h) + aoff + m * 2048 + k * 1024); } while (0)
; #define PG8_MMA(ai, bj, At, Bt) do { if (GEMM_PRIO_MODE == 0) __builtin_amdgcn_s_setprio(1); PG8_MMA_LOOPS \
;         acc[ai][bj][m][n] = __builtin_amdgcn_mfma_f32_16x16x32_bf16(Bt[n][k], At[m][k], acc[ai][bj][m][n], 0, 0, 0); if (GEMM_PRIO_MODE == 0) __builtin_amdgcn_s_setprio(0); } while (0)
; #define PG8_WAIT_V(n) asm volatile("s_waitcnt vmcnt(" #n ")" ::: "memory")
; #define PG8_WAIT_VR(n, nr, flag) asm volatile("s_cmp_eq_u32 %0, 0\n\ts_cbranch_scc1 .Lpg8s%=\n\ts_waitcnt vmcnt(" #nr ")\n\ts_branch .Lpg8d%=\n.Lpg8s%=:\n\ts_waitcnt vmcnt(" #n ")\n.Lpg8d%=:" :: "s"(flag) : "memory", "scc")
; #define PG8_WAIT_L(n) asm volatile("s_waitcnt lgkmcnt(" #n ")" ::: "memory")
; #define PG8_BAR __builtin_amdgcn_s_barrier()
; #define PG8_SCHED __builtin_amdgcn_sched_barrier(0)
;     ...
;             PG8_WAIT_V(8); PG8_WAIT_L(0); PG8_BAR; PG8_MMA(0, 0, At, B0); PG8_MMA(0, 1, At, B1); PG8_BAR; PG8_SCHED;
;     ...
;             PG8_LDA(At, 0, 1); PG8_STAGEB(PG8_SB(0, 0), b2, voffB); PG8_STAGEB(PG8_SB(0, 1), b2 + hstepB, voffB); PG8_STAGEA(PG8_SA(0, 0), a2, voffA);
;     ...
;             PG8_WAIT_VR(8, 24, relax); PG8_WAIT_L(0); PG8_BAR; PG8_MMA(1, 0, At, B0); PG8_MMA(1, 1, At, B1); PG8_BAR; PG8_SCHED;
;     ...
;             PG8_WAIT_V(8); PG8_WAIT_L(0); PG8_BAR; PG8_MMA(1, 0, At, B0); PG8_MMA(1, 1, At, B1); PG8_BAR; PG8_SCHED;
	v_mfma_f32_16x16x32_bf16 v[126:129], v[150:153], v[182:185], v[126:129]
	v_mfma_f32_16x16x32_bf16 v[122:125], v[158:161], v[182:185], v[122:125]
	v_mfma_f32_16x16x32_bf16 v[110:113], v[150:153], v[190:193], v[110:113]
	v_mfma_f32_16x16x32_bf16 v[106:109], v[158:161], v[190:193], v[106:109]
	v_mfma_f32_16x16x32_bf16 v[94:97], v[150:153], v[198:201], v[94:97]
	v_mfma_f32_16x16x32_bf16 v[90:93], v[158:161], v[198:201], v[90:93]
	v_mfma_f32_16x16x32_bf16 v[78:81], v[150:153], v[206:209], v[78:81]
	v_mfma_f32_16x16x32_bf16 v[74:77], v[158:161], v[206:209], v[74:77]
	v_mfma_f32_16x16x32_bf16 v[126:129], v[154:157], v[186:189], v[126:129]
	v_mfma_f32_16x16x32_bf16 v[122:125], v[162:165], v[186:189], v[122:125]
	v_mfma_f32_16x16x32_bf16 v[110:113], v[154:157], v[194:197], v[110:113]
	v_mfma_f32_16x16x32_bf16 v[106:109], v[162:165], v[194:197], v[106:109]
	v_mfma_f32_16x16x32_bf16 v[94:97], v[154:157], v[202:205], v[94:97]
	v_mfma_f32_16x16x32_bf16 v[90:93], v[162:165], v[202:205], v[90:93]
	v_mfma_f32_16x16x32_bf16 v[78:81], v[154:157], v[210:213], v[78:81]
	v_mfma_f32_16x16x32_bf16 v[74:77], v[162:165], v[210:213], v[74:77]
	v_mfma_f32_16x16x32_bf16 v[118:121], v[166:169], v[182:185], v[118:121]
	v_mfma_f32_16x16x32_bf16 v[114:117], v[174:177], v[182:185], v[114:117]
	v_mfma_f32_16x16x32_bf16 v[102:105], v[166:169], v[190:193], v[102:105]
	v_mfma_f32_16x16x32_bf16 v[98:101], v[174:177], v[190:193], v[98:101]
	v_mfma_f32_16x16x32_bf16 v[86:89], v[166:169], v[198:201], v[86:89]
	v_mfma_f32_16x16x32_bf16 v[82:85], v[174:177], v[198:201], v[82:85]
	v_mfma_f32_16x16x32_bf16 v[70:73], v[166:169], v[206:209], v[70:73]
	v_mfma_f32_16x16x32_bf16 v[66:69], v[174:177], v[206:209], v[66:69]
	v_mfma_f32_16x16x32_bf16 v[118:121], v[170:173], v[186:189], v[118:121]
	v_mfma_f32_16x16x32_bf16 v[114:117], v[178:181], v[186:189], v[114:117]
	v_mfma_f32_16x16x32_bf16 v[102:105], v[170:173], v[194:197], v[102:105]
	v_mfma_f32_16x16x32_bf16 v[98:101], v[178:181], v[194:197], v[98:101]
	v_mfma_f32_16x16x32_bf16 v[86:89], v[170:173], v[202:205], v[86:89]
	v_mfma_f32_16x16x32_bf16 v[82:85], v[178:181], v[202:205], v[82:85]
	v_mfma_f32_16x16x32_bf16 v[70:73], v[170:173], v[210:213], v[70:73]
	v_mfma_f32_16x16x32_bf16 v[66:69], v[178:181], v[210:213], v[66:69]
	s_barrier
	s_setprio 0
	s_add_i32 s6, s95, s50
	s_mov_b32 m0, s6
	ds_read_b128 v[182:185], v148 offset:16384
	ds_read_b128 v[186:189], v148 offset:17408
	ds_read_b128 v[190:193], v148 offset:18432
	ds_read_b128 v[194:197], v148 offset:19456
	ds_read_b128 v[198:201], v148 offset:20480
	ds_read_b128 v[202:205], v148 offset:21504
	ds_read_b128 v[206:209], v148 offset:22528
	ds_read_b128 v[210:213], v148 offset:23552
	global_load_lds_dwordx4 v134, s[16:17]
	s_add_i32 m0, s6, 0x2000
	s_add_u32 s6, s16, 0x100000
	s_addc_u32 s7, s17, 0
	s_add_i32 s95, vcc_lo, s50
	global_load_lds_dwordx4 v130, s[16:17]
	s_mov_b32 m0, s95
	s_nop 0
	global_load_lds_dwordx4 v134, s[6:7]
	s_add_i32 m0, s95, 0x2000
	s_nop 0
	global_load_lds_dwordx4 v130, s[6:7]
	s_mov_b32 m0, s69
	s_nop 0
	global_load_lds_dwordx4 v136, s[42:43]
	s_mov_b32 m0, s72
	s_nop 0
	global_load_lds_dwordx4 v132, s[42:43]
	s_waitcnt vmcnt(8)
	s_waitcnt lgkmcnt(0)
	s_nop 0
	s_setprio 1
	s_barrier
	v_mfma_f32_16x16x32_bf16 v[62:65], v[150:153], v[182:185], v[62:65]
	v_mfma_f32_16x16x32_bf16 v[58:61], v[158:161], v[182:185], v[58:61]
	v_mfma_f32_16x16x32_bf16 v[46:49], v[150:153], v[190:193], v[46:49]
	v_mfma_f32_16x16x32_bf16 v[42:45], v[158:161], v[190:193], v[42:45]
	v_mfma_f32_16x16x32_bf16 v[30:33], v[150:153], v[198:201], v[30:33]
	v_mfma_f32_16x16x32_bf16 v[26:29], v[158:161], v[198:201], v[26:29]
	v_mfma_f32_16x16x32_bf16 v[12:15], v[150:153], v[206:209], v[12:15]
	v_mfma_f32_16x16x32_bf16 v[8:11], v[158:161], v[206:209], v[8:11]
	v_mfma_f32_16x16x32_bf16 v[62:65], v[154:157], v[186:189], v[62:65]
	v_mfma_f32_16x16x32_bf16 v[58:61], v[162:165], v[186:189], v[58:61]
	v_mfma_f32_16x16x32_bf16 v[46:49], v[154:157], v[194:197], v[46:49]
	v_mfma_f32_16x16x32_bf16 v[42:45], v[162:165], v[194:197], v[42:45]
	v_mfma_f32_16x16x32_bf16 v[30:33], v[154:157], v[202:205], v[30:33]
	v_mfma_f32_16x16x32_bf16 v[26:29], v[162:165], v[202:205], v[26:29]
	v_mfma_f32_16x16x32_bf16 v[12:15], v[154:157], v[210:213], v[12:15]
	v_mfma_f32_16x16x32_bf16 v[8:11], v[162:165], v[210:213], v[8:11]
	v_mfma_f32_16x16x32_bf16 v[54:57], v[166:169], v[182:185], v[54:57]
	v_mfma_f32_16x16x32_bf16 v[50:53], v[174:177], v[182:185], v[50:53]
	v_mfma_f32_16x16x32_bf16 v[38:41], v[166:169], v[190:193], v[38:41]
	v_mfma_f32_16x16x32_bf16 v[34:37], v[174:177], v[190:193], v[34:37]
	v_mfma_f32_16x16x32_bf16 v[22:25], v[166:169], v[198:201], v[22:25]
	v_mfma_f32_16x16x32_bf16 v[18:21], v[174:177], v[198:201], v[18:21]
	v_mfma_f32_16x16x32_bf16 v[4:7], v[166:169], v[206:209], v[4:7]
	v_mfma_f32_16x16x32_bf16 v[0:3], v[174:177], v[206:209], v[0:3]
	v_mfma_f32_16x16x32_bf16 v[54:57], v[170:173], v[186:189], v[54:57]
	v_mfma_f32_16x16x32_bf16 v[50:53], v[178:181], v[186:189], v[50:53]
	v_mfma_f32_16x16x32_bf16 v[38:41], v[170:173], v[194:197], v[38:41]
	v_mfma_f32_16x16x32_bf16 v[34:37], v[178:181], v[194:197], v[34:37]
	v_mfma_f32_16x16x32_bf16 v[22:25], v[170:173], v[202:205], v[22:25]
	v_mfma_f32_16x16x32_bf16 v[18:21], v[178:181], v[202:205], v[18:21]
	v_mfma_f32_16x16x32_bf16 v[4:7], v[170:173], v[210:213], v[4:7]
	v_mfma_f32_16x16x32_bf16 v[0:3], v[178:181], v[210:213], v[0:3]
	s_barrier
; #define PG8_STAGEA(bufoff, gbase, voff) PG8_STAGE_X(bufoff, gbase, voff, AUXA)
; #define PG8_STAGEB(bufoff, gbase, voff) PG8_STAGE_X(bufoff, gbase, voff, AUXB)
; #define PG8_LDA(dst, b, h) do { _Pragma("unroll") for (int m = 0; m < 4; ++m) _Pragma("unroll") for (int k = 0; k < 2; ++k) dst[m][k] = *(const PG8_LAS bf16x8*)(lds + PG8_SA(b, h) + aoff + m * 2048 + k * 1024); } while (0)
; #define PG8_LDB(dst, b, h) do { _Pragma("unroll") for (int n = 0; n < 2; ++n) _Pragma("unroll") for (int k = 0; k < 2; ++k) dst[n][k] = *(const PG8_LAS bf16x8*)(lds + PG8_SB(b, h) + boff + n * 2048 + k * 1024); } while (0)
; #define PG8_MMA(ai, bj, At, Bt) do { if (GEMM_PRIO_MODE == 0) __builtin_amdgcn_s_setprio(1); PG8_MMA_LOOPS \
;         acc[ai][bj][m][n] = __builtin_amdgcn_mfma_f32_16x16x32_bf16(Bt[n][k], At[m][k], acc[ai][bj][m][n], 0, 0, 0); if (GEMM_PRIO_MODE == 0) __builtin_amdgcn_s_setprio(0); } while (0)
; #define PG8_WAIT_V(n) asm volatile("s_waitcnt vmcnt(" #n ")" ::: "memory")
; #define PG8_WAIT_L(n) asm volatile("s_waitcnt lgkmcnt(" #n ")" ::: "memory")
; #define PG8_BAR __builtin_amdgcn_s_barrier()
; #define PG8_SCHED __builtin_amdgcn_sched_barrier(0)
;     ...
;             PG8_LDB(B0, 1, 0); PG8_LDB(B1, 1, 1); PG8_SCHED; PG8_LDA(At, 1, 0); PG8_STAGEA(PG8_SA(0, 1), a2 + hstepA, voffA);
;             PG8_WAIT_V(8); PG8_WAIT_L(0); PG8_BAR; PG8_MMA(0, 0, At, B0); PG8_MMA(0, 1, At, B1); PG8_BAR; PG8_SCHED;
;             PG8_LDA(At, 1, 1); PG8_STAGEB(PG8_SB(1, 0), b3, voffB); PG8_STAGEB(PG8_SB(1, 1), b3 + hstepB, voffB); PG8_STAGEA(PG8_SA(1, 0), a3, voffA);
;             PG8_WAIT_V(8); PG8_WAIT_L(0); PG8_BAR; PG8_MMA(1, 0, At, B0); PG8_MMA(1, 1, At, B1); PG8_BAR; PG8_SCHED;
	s_setprio 0
	s_add_i32 s95, 0, 0x18000
	s_add_i32 vcc_lo, 0, 0x1c000
	ds_read_b128 v[150:153], v222 offset:32768
	ds_read_b128 v[154:157], v222 offset:33792
	ds_read_b128 v[158:161], v222 offset:34816
	ds_read_b128 v[162:165], v222 offset:35840
	ds_read_b128 v[166:169], v222 offset:49152
	ds_read_b128 v[170:173], v222 offset:50176
	ds_read_b128 v[174:177], v222 offset:51200
	ds_read_b128 v[178:181], v222 offset:52224
	s_add_u32 s6, s42, 0x100000
	s_addc_u32 s7, s43, 0
	s_mov_b32 m0, s73
	ds_read_b128 v[182:185], v148 offset:32768
	ds_read_b128 v[186:189], v148 offset:33792
	ds_read_b128 v[190:193], v148 offset:34816
	ds_read_b128 v[194:197], v148 offset:35840
	ds_read_b128 v[198:201], v148 offset:36864
	ds_read_b128 v[202:205], v148 offset:37888
	ds_read_b128 v[206:209], v148 offset:38912
	ds_read_b128 v[210:213], v148 offset:39936
	global_load_lds_dwordx4 v136, s[6:7]
	s_mov_b32 m0, s82
	s_nop 0
	global_load_lds_dwordx4 v132, s[6:7]
	s_waitcnt vmcnt(8)
	s_waitcnt lgkmcnt(0)
	s_setprio 1
	s_barrier
	v_mfma_f32_16x16x32_bf16 v[126:129], v[150:153], v[182:185], v[126:129]
	v_mfma_f32_16x16x32_bf16 v[122:125], v[158:161], v[182:185], v[122:125]
	v_mfma_f32_16x16x32_bf16 v[110:113], v[150:153], v[190:193], v[110:113]
	v_mfma_f32_16x16x32_bf16 v[106:109], v[158:161], v[190:193], v[106:109]
	v_mfma_f32_16x16x32_bf16 v[94:97], v[150:153], v[198:201], v[94:97]
	v_mfma_f32_16x16x32_bf16 v[90:93], v[158:161], v[198:201], v[90:93]
	v_mfma_f32_16x16x32_bf16 v[78:81], v[150:153], v[206:209], v[78:81]
	v_mfma_f32_16x16x32_bf16 v[74:77], v[158:161], v[206:209], v[74:77]
	v_mfma_f32_16x16x32_bf16 v[126:129], v[154:157], v[186:189], v[126:129]
	v_mfma_f32_16x16x32_bf16 v[122:125], v[162:165], v[186:189], v[122:125]
	v_mfma_f32_16x16x32_bf16 v[110:113], v[154:157], v[194:197], v[110:113]
	v_mfma_f32_16x16x32_bf16 v[106:109], v[162:165], v[194:197], v[106:109]
	v_mfma_f32_16x16x32_bf16 v[94:97], v[154:157], v[202:205], v[94:97]
	v_mfma_f32_16x16x32_bf16 v[90:93], v[162:165], v[202:205], v[90:93]
	v_mfma_f32_16x16x32_bf16 v[78:81], v[154:157], v[210:213], v[78:81]
	v_mfma_f32_16x16x32_bf16 v[74:77], v[162:165], v[210:213], v[74:77]
	v_mfma_f32_16x16x32_bf16 v[118:121], v[166:169], v[182:185], v[118:121]
	v_mfma_f32_16x16x32_bf16 v[114:117], v[174:177], v[182:185], v[114:117]
	v_mfma_f32_16x16x32_bf16 v[102:105], v[166:169], v[190:193], v[102:105]
	v_mfma_f32_16x16x32_bf16 v[98:101], v[174:177], v[190:193], v[98:101]
	v_mfma_f32_16x16x32_bf16 v[86:89], v[166:169], v[198:201], v[86:89]
	v_mfma_f32_16x16x32_bf16 v[82:85], v[174:177], v[198:201], v[82:85]
	v_mfma_f32_16x16x32_bf16 v[70:73], v[166:169], v[206:209], v[70:73]
	v_mfma_f32_16x16x32_bf16 v[66:69], v[174:177], v[206:209], v[66:69]
	v_mfma_f32_16x16x32_bf16 v[118:121], v[170:173], v[186:189], v[118:121]
	v_mfma_f32_16x16x32_bf16 v[114:117], v[178:181], v[186:189], v[114:117]
	v_mfma_f32_16x16x32_bf16 v[102:105], v[170:173], v[194:197], v[102:105]
	v_mfma_f32_16x16x32_bf16 v[98:101], v[178:181], v[194:197], v[98:101]
	v_mfma_f32_16x16x32_bf16 v[86:89], v[170:173], v[202:205], v[86:89]
	v_mfma_f32_16x16x32_bf16 v[82:85], v[178:181], v[202:205], v[82:85]
	v_mfma_f32_16x16x32_bf16 v[70:73], v[170:173], v[210:213], v[70:73]
	v_mfma_f32_16x16x32_bf16 v[66:69], v[178:181], v[210:213], v[66:69]
	s_barrier
	s_setprio 0
	s_add_i32 s6, s95, s50
	s_mov_b32 m0, s6
	ds_read_b128 v[182:185], v148 offset:49152
	ds_read_b128 v[186:189], v148 offset:50176
	ds_read_b128 v[190:193], v148 offset:51200
	ds_read_b128 v[194:197], v148 offset:52224
	ds_read_b128 v[198:201], v148 offset:53248
	ds_read_b128 v[202:205], v148 offset:54272
	ds_read_b128 v[206:209], v148 offset:55296
	ds_read_b128 v[210:213], v148 offset:56320
	s_add_u32 s100, s16, 0x80
	s_addc_u32 s101, s17, 0
	global_load_lds_dwordx4 v134, s[100:101]
	s_add_i32 m0, s6, 0x2000
	s_add_u32 s6, s16, 0x100080
	s_addc_u32 s7, s17, 0
	s_add_i32 s16, vcc_lo, s50
	global_load_lds_dwordx4 v130, s[100:101]
	s_mov_b32 m0, s16
	s_nop 0
	global_load_lds_dwordx4 v134, s[6:7]
	s_add_i32 m0, s16, 0x2000
	s_nop 0
	global_load_lds_dwordx4 v130, s[6:7]
	s_mov_b32 m0, s83
	s_nop 0
	s_add_u32 s100, s42, 0x80
	s_addc_u32 s101, s43, 0
	global_load_lds_dwordx4 v136, s[100:101]
	s_mov_b32 m0, s90
	s_nop 0
	global_load_lds_dwordx4 v132, s[100:101]
	s_waitcnt vmcnt(8)
	s_waitcnt lgkmcnt(0)
	s_nop 0
	s_setprio 1
	s_barrier
	v_mfma_f32_16x16x32_bf16 v[62:65], v[150:153], v[182:185], v[62:65]
	v_mfma_f32_16x16x32_bf16 v[58:61], v[158:161], v[182:185], v[58:61]
	v_mfma_f32_16x16x32_bf16 v[46:49], v[150:153], v[190:193], v[46:49]
	v_mfma_f32_16x16x32_bf16 v[42:45], v[158:161], v[190:193], v[42:45]
	v_mfma_f32_16x16x32_bf16 v[30:33], v[150:153], v[198:201], v[30:33]
	v_mfma_f32_16x16x32_bf16 v[26:29], v[158:161], v[198:201], v[26:29]
	v_mfma_f32_16x16x32_bf16 v[12:15], v[150:153], v[206:209], v[12:15]
	v_mfma_f32_16x16x32_bf16 v[8:11], v[158:161], v[206:209], v[8:11]
	v_mfma_f32_16x16x32_bf16 v[62:65], v[154:157], v[186:189], v[62:65]
	v_mfma_f32_16x16x32_bf16 v[58:61], v[162:165], v[186:189], v[58:61]
	v_mfma_f32_16x16x32_bf16 v[46:49], v[154:157], v[194:197], v[46:49]
	v_mfma_f32_16x16x32_bf16 v[42:45], v[162:165], v[194:197], v[42:45]
	v_mfma_f32_16x16x32_bf16 v[30:33], v[154:157], v[202:205], v[30:33]
	v_mfma_f32_16x16x32_bf16 v[26:29], v[162:165], v[202:205], v[26:29]
	v_mfma_f32_16x16x32_bf16 v[12:15], v[154:157], v[210:213], v[12:15]
	v_mfma_f32_16x16x32_bf16 v[8:11], v[162:165], v[210:213], v[8:11]
	v_mfma_f32_16x16x32_bf16 v[54:57], v[166:169], v[182:185], v[54:57]
	v_mfma_f32_16x16x32_bf16 v[50:53], v[174:177], v[182:185], v[50:53]
	v_mfma_f32_16x16x32_bf16 v[38:41], v[166:169], v[190:193], v[38:41]
	v_mfma_f32_16x16x32_bf16 v[34:37], v[174:177], v[190:193], v[34:37]
	v_mfma_f32_16x16x32_bf16 v[22:25], v[166:169], v[198:201], v[22:25]
	v_mfma_f32_16x16x32_bf16 v[18:21], v[174:177], v[198:201], v[18:21]
	v_mfma_f32_16x16x32_bf16 v[4:7], v[166:169], v[206:209], v[4:7]
	v_mfma_f32_16x16x32_bf16 v[0:3], v[174:177], v[206:209], v[0:3]
	v_mfma_f32_16x16x32_bf16 v[54:57], v[170:173], v[186:189], v[54:57]
	v_mfma_f32_16x16x32_bf16 v[50:53], v[178:181], v[186:189], v[50:53]
	v_mfma_f32_16x16x32_bf16 v[38:41], v[170:173], v[194:197], v[38:41]
	v_mfma_f32_16x16x32_bf16 v[34:37], v[178:181], v[194:197], v[34:37]
	v_mfma_f32_16x16x32_bf16 v[22:25], v[170:173], v[202:205], v[22:25]
	v_mfma_f32_16x16x32_bf16 v[18:21], v[178:181], v[202:205], v[18:21]
	v_mfma_f32_16x16x32_bf16 v[4:7], v[170:173], v[210:213], v[4:7]
	v_mfma_f32_16x16x32_bf16 v[0:3], v[178:181], v[210:213], v[0:3]
	s_barrier
	s_setprio 0
	s_add_i32 s39, s39, 2
	s_add_u32 s40, s40, 0x100
	s_addc_u32 s41, s41, 0
	s_add_u32 s12, s12, 0x100
	s_addc_u32 s13, s13, 0
	s_cmp_gt_u32 s39, 61
	s_cbranch_scc0 .LBB0_712
	s_and_b64 vcc, exec, s[18:19]
	s_cbranch_vccz .LBB0_715
	s_barrier

; #define PG8_STAGEA(bufoff, gbase, voff) PG8_STAGE_X(bufoff, gbase, voff, AUXA)
; #define PG8_STR(x) PG8_STR2(x)
;     ...
;         const bool has_next = S.next(ui + 1, nxt);
;         const char* nA = has_next ? (const char*)g.A + (size_t)nxt.pm * tstepA : cA; const char* nB = has_next ? (const char*)g.Bt + (size_t)nxt.pn * tstepB : cB;
;         int t0 = 0;
;         if constexpr (SP2 && GEMM_RELAX == 1) { if (ui > 0) {
;             const char* a1 = cA + kstepA; const char* a2 = cA + 2 * kstepA; const char* b2 = cB + 2 * kstepB; const char* a3 = a2 + kstepA; const char* b3 = b2 + kstepB;
;             PG8_LDB(B0, 0, 0); PG8_LDB(B1, 0, 1); PG8_SCHED; PG8_LDA(At, 0, 0); PG8_STAGEA(PG8_SA(1, 1), a1 + hstepA, voffA);
;             PG8_WAIT_V(24); PG8_WAIT_L(0); PG8_BAR; PG8_MMA(0, 0, At, B0); PG8_MMA(0, 1, At, B1); PG8_BAR; PG8_SCHED;
;             PG8_LDA(At, 0, 1); PG8_STAGEB(PG8_SB(0, 0), b2, voffB); PG8_STAGEB(PG8_SB(0, 1), b2 + hstepB, voffB); PG8_STAGEA(PG8_SA(0, 0), a2, voffA);
;             PG8_WAIT_V(24); PG8_WAIT_L(0); PG8_BAR; PG8_MMA(1, 0, At, B0); PG8_MMA(1, 1, At, B1); PG8_BAR; PG8_SCHED;
;             PG8_LDB(B0, 1, 0); PG8_LDB(B1, 1, 1); PG8_SCHED; PG8_LDA(At, 1, 0); PG8_STAGEA(PG8_SA(0, 1), a2 + hstepA, voffA);
;             PG8_WAIT_V(8); PG8_WAIT_L(0); PG8_BAR; PG8_MMA(0, 0, At, B0); PG8_MMA(0, 1, At, B1); PG8_BAR; PG8_SCHED;
;             PG8_LDA(At, 1, 1); PG8_STAGEB(PG8_SB(1, 0), b3, voffB); PG8_STAGEB(PG8_SB(1, 1), b3 + hstepB, voffB); PG8_STAGEA(PG8_SA(1, 0), a3, voffA);
;             PG8_WAIT_V(8); PG8_WAIT_L(0); PG8_BAR; PG8_MMA(1, 0, At, B0); PG8_MMA(1, 1, At, B1); PG8_BAR; PG8_SCHED;
;             t0 = 2; } }
;     ...
;         asm volatile(".p2align " PG8_STR(GEMM_LOOP_ALIGN) ::: "memory");
;     ...
;         for (int t = t0; t < nt; t += 2) {
;             const bool last = (t == nt - 2);
;             const char* a1 = cA + (size_t)(t + 1) * kstepA;
;             const char* a2 = last ? nA : cA + (size_t)(t + 2) * kstepA; const char* b2 = last ? nB : cB + (size_t)(t + 2) * kstepB;
;             const char* a3 = a2 + kstepA; const char* b3 = b2 + kstepB;
;             if (last && has_next) S.a_ready(nxt);
;             if constexpr (SP2) {
;             PG8_LDB(B0, 0, 0); PG8_LDB(B1, 0, 1); PG8_SCHED; PG8_LDA(At, 0, 0); PG8_STAGEA(PG8_SA(1, 1), a1 + hstepA, voffA);
;     ...
;             const int relax = __builtin_amdgcn_readfirstlane((t == 0 && ui > 0) ? 1 : 0);
.LBB0_847:
	s_ashr_i32 s11, s10, 31
	s_lshl_b64 s[18:19], s[10:11], 23
	s_add_u32 s18, s62, s18
	s_addc_u32 s19, s63, s19
	s_and_b64 s[22:23], s[20:21], exec
	s_cselect_b32 s11, s19, s1
	s_cselect_b32 s73, s18, s0
	s_ashr_i32 s15, s14, 31
	s_lshl_b64 s[22:23], s[14:15], 23
	s_add_u32 s22, s12, s22
	s_addc_u32 s23, s13, s23
	s_and_b64 s[24:25], s[20:21], exec
	s_cselect_b32 s15, s23, s17
	s_cselect_b32 s78, s22, s16
	s_add_u32 s24, s0, 0xc000
	s_addc_u32 s25, s1, 0
	s_add_u32 s0, s16, 0x10000
	s_addc_u32 s1, s17, 0
	s_mov_b32 s82, -2
	s_waitcnt lgkmcnt(0)
	s_add_u32 s16, s24, 0x4000
	s_addc_u32 s17, s25, 0
	s_cmpk_eq_i32 s82, 0xfc
	s_cselect_b32 s36, s73, s16
	s_cselect_b32 s37, s11, s17
	s_cselect_b32 s16, s78, s0
	s_cselect_b32 s17, s15, s1
	s_add_u32 s26, s36, 0x8000
	s_addc_u32 s27, s37, 0
	s_add_i32 s83, 0, 0x10000
	s_add_i32 s94, 0, 0x14000
	v_add_u32_e32 v152, s83, v157
	v_add_u32_e32 v174, s94, v157
	ds_read_b128 v[130:133], v152
	ds_read_b128 v[134:137], v152 offset:1024
	ds_read_b128 v[148:151], v152 offset:2048
	ds_read_b128 v[152:155], v152 offset:3072
	ds_read_b128 v[162:165], v174
	ds_read_b128 v[166:169], v174 offset:1024
	ds_read_b128 v[170:173], v174 offset:2048
	ds_read_b128 v[174:177], v174 offset:3072
	v_lshl_add_u64 v[210:211], s[24:25], 0, v[144:145]
	s_add_i32 m0, s39, 0xc000
	ds_read_b128 v[178:181], v161
	ds_read_b128 v[182:185], v161 offset:1024
	ds_read_b128 v[186:189], v161 offset:2048
	ds_read_b128 v[190:193], v161 offset:3072
	ds_read_b128 v[194:197], v161 offset:4096
	ds_read_b128 v[198:201], v161 offset:5120
	ds_read_b128 v[202:205], v161 offset:6144
	ds_read_b128 v[206:209], v161 offset:7168
	global_load_lds_dwordx4 v[210:211], off
	v_lshl_add_u64 v[210:211], s[24:25], 0, v[146:147]
	s_add_i32 m0, s39, 0xe000
	s_nop 0
	global_load_lds_dwordx4 v[210:211], off
	s_waitcnt vmcnt(8)
	s_waitcnt lgkmcnt(0)
	s_setprio 1
	s_barrier
	v_mfma_f32_16x16x32_bf16 v[126:129], v[130:133], v[178:181], 0
	v_mfma_f32_16x16x32_bf16 v[122:125], v[148:151], v[178:181], 0
	v_mfma_f32_16x16x32_bf16 v[110:113], v[130:133], v[186:189], 0
	v_mfma_f32_16x16x32_bf16 v[106:109], v[148:151], v[186:189], 0
	v_mfma_f32_16x16x32_bf16 v[94:97], v[130:133], v[194:197], 0
	v_mfma_f32_16x16x32_bf16 v[90:93], v[148:151], v[194:197], 0
	v_mfma_f32_16x16x32_bf16 v[78:81], v[130:133], v[202:205], 0
	v_mfma_f32_16x16x32_bf16 v[74:77], v[148:151], v[202:205], 0
	v_mfma_f32_16x16x32_bf16 v[126:129], v[134:137], v[182:185], v[126:129]
	v_mfma_f32_16x16x32_bf16 v[122:125], v[152:155], v[182:185], v[122:125]
	v_mfma_f32_16x16x32_bf16 v[110:113], v[134:137], v[190:193], v[110:113]
	v_mfma_f32_16x16x32_bf16 v[106:109], v[152:155], v[190:193], v[106:109]
	v_mfma_f32_16x16x32_bf16 v[94:97], v[134:137], v[198:201], v[94:97]
	v_mfma_f32_16x16x32_bf16 v[90:93], v[152:155], v[198:201], v[90:93]
	v_mfma_f32_16x16x32_bf16 v[78:81], v[134:137], v[206:209], v[78:81]
	v_mfma_f32_16x16x32_bf16 v[74:77], v[152:155], v[206:209], v[74:77]
	v_mfma_f32_16x16x32_bf16 v[118:121], v[162:165], v[178:181], 0
	v_mfma_f32_16x16x32_bf16 v[114:117], v[170:173], v[178:181], 0
	v_mfma_f32_16x16x32_bf16 v[102:105], v[162:165], v[186:189], 0
	v_mfma_f32_16x16x32_bf16 v[98:101], v[170:173], v[186:189], 0
	v_mfma_f32_16x16x32_bf16 v[86:89], v[162:165], v[194:197], 0
	v_mfma_f32_16x16x32_bf16 v[82:85], v[170:173], v[194:197], 0
	v_mfma_f32_16x16x32_bf16 v[70:73], v[162:165], v[202:205], 0
	v_mfma_f32_16x16x32_bf16 v[66:69], v[170:173], v[202:205], 0
	v_mfma_f32_16x16x32_bf16 v[118:121], v[166:169], v[182:185], v[118:121]
	v_mfma_f32_16x16x32_bf16 v[114:117], v[174:177], v[182:185], v[114:117]
	v_mfma_f32_16x16x32_bf16 v[102:105], v[166:169], v[190:193], v[102:105]
	v_mfma_f32_16x16x32_bf16 v[98:101], v[174:177], v[190:193], v[98:101]
	v_mfma_f32_16x16x32_bf16 v[86:89], v[166:169], v[198:201], v[86:89]
	v_mfma_f32_16x16x32_bf16 v[82:85], v[174:177], v[198:201], v[82:85]
	v_mfma_f32_16x16x32_bf16 v[70:73], v[166:169], v[206:209], v[70:73]
	v_mfma_f32_16x16x32_bf16 v[66:69], v[174:177], v[206:209], v[66:69]
	s_barrier
	s_setprio 0
	s_add_i32 s83, s83, s38
	v_lshl_add_u64 v[210:211], s[16:17], 0, v[16:17]
	s_mov_b32 m0, s83
	ds_read_b128 v[178:181], v161 offset:16384
	ds_read_b128 v[182:185], v161 offset:17408
	ds_read_b128 v[186:189], v161 offset:18432
	ds_read_b128 v[190:193], v161 offset:19456
	ds_read_b128 v[194:197], v161 offset:20480
	ds_read_b128 v[198:201], v161 offset:21504
	ds_read_b128 v[202:205], v161 offset:22528
	ds_read_b128 v[206:209], v161 offset:23552
	global_load_lds_dwordx4 v[210:211], off
	s_add_i32 m0, s83, 0x2000
	s_add_u32 s90, s16, 0x4000
	v_lshl_add_u64 v[210:211], s[16:17], 0, v[138:139]
	s_addc_u32 s91, s17, 0
	s_add_i32 s83, s94, s38
	global_load_lds_dwordx4 v[210:211], off
	v_lshl_add_u64 v[210:211], s[90:91], 0, v[16:17]
	s_mov_b32 m0, s83
	s_nop 0
	global_load_lds_dwordx4 v[210:211], off
	v_lshl_add_u64 v[210:211], s[90:91], 0, v[138:139]
	s_add_i32 m0, s83, 0x2000
	s_nop 0
	global_load_lds_dwordx4 v[210:211], off
	v_lshl_add_u64 v[210:211], s[36:37], 0, v[142:143]
	s_mov_b32 m0, s39
	s_nop 0
	global_load_lds_dwordx4 v[210:211], off
	v_lshl_add_u64 v[210:211], s[36:37], 0, v[140:141]
	s_mov_b32 m0, s40
	s_nop 0
	global_load_lds_dwordx4 v[210:211], off
	s_waitcnt vmcnt(8)
	s_waitcnt lgkmcnt(0)
	s_nop 0
	s_setprio 1
	s_barrier
; #define PG8_STAGEA(bufoff, gbase, voff) PG8_STAGE_X(bufoff, gbase, voff, AUXA)
; #define PG8_LDA(dst, b, h) do { _Pragma("unroll") for (int m = 0; m < 4; ++m) _Pragma("unroll") for (int k = 0; k < 2; ++k) dst[m][k] = *(const PG8_LAS bf16x8*)(lds + PG8_SA(b, h) + aoff + m * 2048 + k * 1024); } while (0)
; #define PG8_LDB(dst, b, h) do { _Pragma("unroll") for (int n = 0; n < 2; ++n) _Pragma("unroll") for (int k = 0; k < 2; ++k) dst[n][k] = *(const PG8_LAS bf16x8*)(lds + PG8_SB(b, h) + boff + n * 2048 + k * 1024); } while (0)
; #define PG8_MMA(ai, bj, At, Bt) do { if (GEMM_PRIO_MODE == 0) __builtin_amdgcn_s_setprio(1); PG8_MMA_LOOPS \
;         acc[ai][bj][m][n] = __builtin_amdgcn_mfma_f32_16x16x32_bf16(Bt[n][k], At[m][k], acc[ai][bj][m][n], 0, 0, 0); if (GEMM_PRIO_MODE == 0) __builtin_amdgcn_s_setprio(0); } while (0)
; #define PG8_WAIT_V(n) asm volatile("s_waitcnt vmcnt(" #n ")" ::: "memory")
; #define PG8_WAIT_L(n) asm volatile("s_waitcnt lgkmcnt(" #n ")" ::: "memory")
; #define PG8_BAR __builtin_amdgcn_s_barrier()
; #define PG8_SCHED __builtin_amdgcn_sched_barrier(0)
;     ...
;             PG8_WAIT_V(8); PG8_WAIT_L(0); PG8_BAR; PG8_MMA(1, 0, At, B0); PG8_MMA(1, 1, At, B1); PG8_BAR; PG8_SCHED;
;     ...
;             PG8_LDB(B0, 1, 0); PG8_LDB(B1, 1, 1); PG8_SCHED; PG8_LDA(At, 1, 0); PG8_STAGEA(PG8_SA(0, 1), a2 + hstepA, voffA);
;             PG8_WAIT_V(8); PG8_WAIT_L(0); PG8_BAR; PG8_MMA(0, 0, At, B0); PG8_MMA(0, 1, At, B1); PG8_BAR; PG8_SCHED;
	v_mfma_f32_16x16x32_bf16 v[62:65], v[130:133], v[178:181], 0
	v_mfma_f32_16x16x32_bf16 v[58:61], v[148:151], v[178:181], 0
	v_mfma_f32_16x16x32_bf16 v[46:49], v[130:133], v[186:189], 0
	v_mfma_f32_16x16x32_bf16 v[42:45], v[148:151], v[186:189], 0
	v_mfma_f32_16x16x32_bf16 v[30:33], v[130:133], v[194:197], 0
	v_mfma_f32_16x16x32_bf16 v[26:29], v[148:151], v[194:197], 0
	v_mfma_f32_16x16x32_bf16 v[12:15], v[130:133], v[202:205], 0
	v_mfma_f32_16x16x32_bf16 v[8:11], v[148:151], v[202:205], 0
	v_mfma_f32_16x16x32_bf16 v[62:65], v[134:137], v[182:185], v[62:65]
	v_mfma_f32_16x16x32_bf16 v[58:61], v[152:155], v[182:185], v[58:61]
	v_mfma_f32_16x16x32_bf16 v[46:49], v[134:137], v[190:193], v[46:49]
	v_mfma_f32_16x16x32_bf16 v[42:45], v[152:155], v[190:193], v[42:45]
	v_mfma_f32_16x16x32_bf16 v[30:33], v[134:137], v[198:201], v[30:33]
	v_mfma_f32_16x16x32_bf16 v[26:29], v[152:155], v[198:201], v[26:29]
	v_mfma_f32_16x16x32_bf16 v[12:15], v[134:137], v[206:209], v[12:15]
	v_mfma_f32_16x16x32_bf16 v[8:11], v[152:155], v[206:209], v[8:11]
	v_mfma_f32_16x16x32_bf16 v[54:57], v[162:165], v[178:181], 0
	v_mfma_f32_16x16x32_bf16 v[50:53], v[170:173], v[178:181], 0
	v_mfma_f32_16x16x32_bf16 v[38:41], v[162:165], v[186:189], 0
	v_mfma_f32_16x16x32_bf16 v[34:37], v[170:173], v[186:189], 0
	v_mfma_f32_16x16x32_bf16 v[22:25], v[162:165], v[194:197], 0
	v_mfma_f32_16x16x32_bf16 v[18:21], v[170:173], v[194:197], 0
	v_mfma_f32_16x16x32_bf16 v[4:7], v[162:165], v[202:205], 0
	v_mfma_f32_16x16x32_bf16 v[0:3], v[170:173], v[202:205], 0
	v_mfma_f32_16x16x32_bf16 v[54:57], v[166:169], v[182:185], v[54:57]
	v_mfma_f32_16x16x32_bf16 v[50:53], v[174:177], v[182:185], v[50:53]
	v_mfma_f32_16x16x32_bf16 v[38:41], v[166:169], v[190:193], v[38:41]
	v_mfma_f32_16x16x32_bf16 v[34:37], v[174:177], v[190:193], v[34:37]
	v_mfma_f32_16x16x32_bf16 v[22:25], v[166:169], v[198:201], v[22:25]
	v_mfma_f32_16x16x32_bf16 v[18:21], v[174:177], v[198:201], v[18:21]
	v_mfma_f32_16x16x32_bf16 v[4:7], v[166:169], v[206:209], v[4:7]
	v_mfma_f32_16x16x32_bf16 v[0:3], v[174:177], v[206:209], v[0:3]
	s_barrier
	s_setprio 0
	s_add_i32 s83, 0, 0x18000
	s_add_i32 s90, 0, 0x1c000
	v_add_u32_e32 v152, s83, v157
	v_add_u32_e32 v174, s90, v157
	ds_read_b128 v[130:133], v152
	ds_read_b128 v[134:137], v152 offset:1024
	ds_read_b128 v[148:151], v152 offset:2048
	ds_read_b128 v[152:155], v152 offset:3072
	ds_read_b128 v[162:165], v174
	ds_read_b128 v[166:169], v174 offset:1024
	ds_read_b128 v[170:173], v174 offset:2048
	ds_read_b128 v[174:177], v174 offset:3072
	s_add_u32 s36, s36, 0x4000
	s_addc_u32 s37, s37, 0
	s_mov_b32 m0, s41
	v_lshl_add_u64 v[210:211], s[36:37], 0, v[142:143]
	ds_read_b128 v[178:181], v161 offset:32768
	ds_read_b128 v[182:185], v161 offset:33792
	ds_read_b128 v[186:189], v161 offset:34816
	ds_read_b128 v[190:193], v161 offset:35840
	ds_read_b128 v[194:197], v161 offset:36864
	ds_read_b128 v[198:201], v161 offset:37888
	ds_read_b128 v[202:205], v161 offset:38912
	ds_read_b128 v[206:209], v161 offset:39936
	global_load_lds_dwordx4 v[210:211], off
	v_lshl_add_u64 v[210:211], s[36:37], 0, v[140:141]
	s_mov_b32 m0, s42
	s_nop 0
	global_load_lds_dwordx4 v[210:211], off
	s_waitcnt vmcnt(8)
	s_waitcnt lgkmcnt(0)
	s_setprio 1
	s_barrier
	v_mfma_f32_16x16x32_bf16 v[126:129], v[130:133], v[178:181], v[126:129]
	v_mfma_f32_16x16x32_bf16 v[122:125], v[148:151], v[178:181], v[122:125]
	v_mfma_f32_16x16x32_bf16 v[110:113], v[130:133], v[186:189], v[110:113]
	v_mfma_f32_16x16x32_bf16 v[106:109], v[148:151], v[186:189], v[106:109]
	v_mfma_f32_16x16x32_bf16 v[94:97], v[130:133], v[194:197], v[94:97]
	v_mfma_f32_16x16x32_bf16 v[90:93], v[148:151], v[194:197], v[90:93]
	v_mfma_f32_16x16x32_bf16 v[78:81], v[130:133], v[202:205], v[78:81]
	v_mfma_f32_16x16x32_bf16 v[74:77], v[148:151], v[202:205], v[74:77]
	v_mfma_f32_16x16x32_bf16 v[126:129], v[134:137], v[182:185], v[126:129]
	v_mfma_f32_16x16x32_bf16 v[122:125], v[152:155], v[182:185], v[122:125]
	v_mfma_f32_16x16x32_bf16 v[110:113], v[134:137], v[190:193], v[110:113]
	v_mfma_f32_16x16x32_bf16 v[106:109], v[152:155], v[190:193], v[106:109]
	v_mfma_f32_16x16x32_bf16 v[94:97], v[134:137], v[198:201], v[94:97]
	v_mfma_f32_16x16x32_bf16 v[90:93], v[152:155], v[198:201], v[90:93]
	v_mfma_f32_16x16x32_bf16 v[78:81], v[134:137], v[206:209], v[78:81]
	v_mfma_f32_16x16x32_bf16 v[74:77], v[152:155], v[206:209], v[74:77]
	v_mfma_f32_16x16x32_bf16 v[118:121], v[162:165], v[178:181], v[118:121]
	v_mfma_f32_16x16x32_bf16 v[114:117], v[170:173], v[178:181], v[114:117]
	v_mfma_f32_16x16x32_bf16 v[102:105], v[162:165], v[186:189], v[102:105]
	v_mfma_f32_16x16x32_bf16 v[98:101], v[170:173], v[186:189], v[98:101]
	v_mfma_f32_16x16x32_bf16 v[86:89], v[162:165], v[194:197], v[86:89]
	v_mfma_f32_16x16x32_bf16 v[82:85], v[170:173], v[194:197], v[82:85]
	v_mfma_f32_16x16x32_bf16 v[70:73], v[162:165], v[202:205], v[70:73]
	v_mfma_f32_16x16x32_bf16 v[66:69], v[170:173], v[202:205], v[66:69]
	v_mfma_f32_16x16x32_bf16 v[118:121], v[166:169], v[182:185], v[118:121]
	v_mfma_f32_16x16x32_bf16 v[114:117], v[174:177], v[182:185], v[114:117]
	v_mfma_f32_16x16x32_bf16 v[102:105], v[166:169], v[190:193], v[102:105]
	v_mfma_f32_16x16x32_bf16 v[98:101], v[174:177], v[190:193], v[98:101]
	v_mfma_f32_16x16x32_bf16 v[86:89], v[166:169], v[198:201], v[86:89]
	v_mfma_f32_16x16x32_bf16 v[82:85], v[174:177], v[198:201], v[82:85]
	v_mfma_f32_16x16x32_bf16 v[70:73], v[166:169], v[206:209], v[70:73]
	v_mfma_f32_16x16x32_bf16 v[66:69], v[174:177], v[206:209], v[66:69]
	s_barrier
; #define PG8_STAGEA(bufoff, gbase, voff) PG8_STAGE_X(bufoff, gbase, voff, AUXA)
; #define PG8_STAGEB(bufoff, gbase, voff) PG8_STAGE_X(bufoff, gbase, voff, AUXB)
; #define PG8_LDA(dst, b, h) do { _Pragma("unroll") for (int m = 0; m < 4; ++m) _Pragma("unroll") for (int k = 0; k < 2; ++k) dst[m][k] = *(const PG8_LAS bf16x8*)(lds + PG8_SA(b, h) + aoff + m * 2048 + k * 1024); } while (0)
; #define PG8_WAIT_V(n) asm volatile("s_waitcnt vmcnt(" #n ")" ::: "memory")
; #define PG8_WAIT_L(n) asm volatile("s_waitcnt lgkmcnt(" #n ")" ::: "memory")
;     ...
;         for (int t = t0; t < nt; t += 2) {
;             const bool last = (t == nt - 2);
;             const char* a1 = cA + (size_t)(t + 1) * kstepA;
;             const char* a2 = last ? nA : cA + (size_t)(t + 2) * kstepA; const char* b2 = last ? nB : cB + (size_t)(t + 2) * kstepB;
;             const char* a3 = a2 + kstepA; const char* b3 = b2 + kstepB;
;             if (last && has_next) S.a_ready(nxt);
;             if constexpr (SP2) {
;             PG8_LDB(B0, 0, 0); PG8_LDB(B1, 0, 1); PG8_SCHED; PG8_LDA(At, 0, 0); PG8_STAGEA(PG8_SA(1, 1), a1 + hstepA, voffA);
;     ...
;             const int relax = __builtin_amdgcn_readfirstlane((t == 0 && ui > 0) ? 1 : 0);
;             PG8_WAIT_VR(8, 24, relax); PG8_WAIT_L(0); PG8_BAR; PG8_MMA(0, 0, At, B0); PG8_MMA(0, 1, At, B1); PG8_BAR; PG8_SCHED;
;     ...
;             PG8_WAIT_V(8); PG8_WAIT_L(0); PG8_BAR; PG8_MMA(0, 0, At, B0); PG8_MMA(0, 1, At, B1); PG8_BAR; PG8_SCHED;
;     ...
;             PG8_LDA(At, 0, 1); PG8_STAGEB(PG8_SB(0, 0), b2, voffB); PG8_STAGEB(PG8_SB(0, 1), b2 + hstepB, voffB); PG8_STAGEA(PG8_SA(0, 0), a2, voffA);
;     ...
;             PG8_WAIT_VR(8, 24, relax); PG8_WAIT_L(0); PG8_BAR; PG8_MMA(1, 0, At, B0); PG8_MMA(1, 1, At, B1); PG8_BAR; PG8_SCHED;
;     ...
;             PG8_WAIT_V(8); PG8_WAIT_L(0); PG8_BAR; PG8_MMA(1, 0, At, B0); PG8_MMA(1, 1, At, B1); PG8_BAR; PG8_SCHED;
;     ...
;             PG8_LDB(B0, 1, 0); PG8_LDB(B1, 1, 1); PG8_SCHED; PG8_LDA(At, 1, 0); PG8_STAGEA(PG8_SA(0, 1), a2 + hstepA, voffA);
;             PG8_WAIT_V(8); PG8_WAIT_L(0); PG8_BAR; PG8_MMA(0, 0, At, B0); PG8_MMA(0, 1, At, B1); PG8_BAR; PG8_SCHED;
;             PG8_LDA(At, 1, 1); PG8_STAGEB(PG8_SB(1, 0), b3, voffB); PG8_STAGEB(PG8_SB(1, 1), b3 + hstepB, voffB); PG8_STAGEA(PG8_SA(1, 0), a3, voffA);
;             PG8_WAIT_V(8); PG8_WAIT_L(0); PG8_BAR; PG8_MMA(1, 0, At, B0); PG8_MMA(1, 1, At, B1); PG8_BAR; PG8_SCHED;
	s_setprio 0
	s_add_u32 s36, s16, 0x8000
	s_addc_u32 s37, s17, 0
	s_add_i32 s83, s83, s38
	v_lshl_add_u64 v[210:211], s[36:37], 0, v[16:17]
	s_mov_b32 m0, s83
	ds_read_b128 v[178:181], v161 offset:49152
	ds_read_b128 v[182:185], v161 offset:50176
	ds_read_b128 v[186:189], v161 offset:51200
	ds_read_b128 v[190:193], v161 offset:52224
	ds_read_b128 v[194:197], v161 offset:53248
	ds_read_b128 v[198:201], v161 offset:54272
	ds_read_b128 v[202:205], v161 offset:55296
	ds_read_b128 v[206:209], v161 offset:56320
	global_load_lds_dwordx4 v[210:211], off
	s_add_i32 m0, s83, 0x2000
	s_add_u32 s16, s16, 0xc000
	v_lshl_add_u64 v[210:211], s[36:37], 0, v[138:139]
	s_addc_u32 s17, s17, 0
	s_add_i32 s36, s90, s38
	global_load_lds_dwordx4 v[210:211], off
	v_lshl_add_u64 v[210:211], s[16:17], 0, v[16:17]
	s_mov_b32 m0, s36
	s_nop 0
	global_load_lds_dwordx4 v[210:211], off
	v_lshl_add_u64 v[210:211], s[16:17], 0, v[138:139]
	s_add_i32 m0, s36, 0x2000
	s_nop 0
	global_load_lds_dwordx4 v[210:211], off
	v_lshl_add_u64 v[210:211], s[26:27], 0, v[142:143]
	s_mov_b32 m0, s50
	s_nop 0
	global_load_lds_dwordx4 v[210:211], off
	v_lshl_add_u64 v[210:211], s[26:27], 0, v[140:141]
	s_mov_b32 m0, s51
	s_nop 0
	global_load_lds_dwordx4 v[210:211], off
	s_waitcnt vmcnt(8)
	s_waitcnt lgkmcnt(0)
	s_setprio 1
	s_barrier
	v_mfma_f32_16x16x32_bf16 v[62:65], v[130:133], v[178:181], v[62:65]
	v_mfma_f32_16x16x32_bf16 v[58:61], v[148:151], v[178:181], v[58:61]
	v_mfma_f32_16x16x32_bf16 v[46:49], v[130:133], v[186:189], v[46:49]
	v_mfma_f32_16x16x32_bf16 v[42:45], v[148:151], v[186:189], v[42:45]
	v_mfma_f32_16x16x32_bf16 v[30:33], v[130:133], v[194:197], v[30:33]
	v_mfma_f32_16x16x32_bf16 v[26:29], v[148:151], v[194:197], v[26:29]
	v_mfma_f32_16x16x32_bf16 v[12:15], v[130:133], v[202:205], v[12:15]
	v_mfma_f32_16x16x32_bf16 v[8:11], v[148:151], v[202:205], v[8:11]
	v_mfma_f32_16x16x32_bf16 v[62:65], v[134:137], v[182:185], v[62:65]
	v_mfma_f32_16x16x32_bf16 v[58:61], v[152:155], v[182:185], v[58:61]
	v_mfma_f32_16x16x32_bf16 v[46:49], v[134:137], v[190:193], v[46:49]
	v_mfma_f32_16x16x32_bf16 v[42:45], v[152:155], v[190:193], v[42:45]
	v_mfma_f32_16x16x32_bf16 v[30:33], v[134:137], v[198:201], v[30:33]
	v_mfma_f32_16x16x32_bf16 v[26:29], v[152:155], v[198:201], v[26:29]
	v_mfma_f32_16x16x32_bf16 v[12:15], v[134:137], v[206:209], v[12:15]
	v_mfma_f32_16x16x32_bf16 v[8:11], v[152:155], v[206:209], v[8:11]
	v_mfma_f32_16x16x32_bf16 v[54:57], v[162:165], v[178:181], v[54:57]
	v_mfma_f32_16x16x32_bf16 v[50:53], v[170:173], v[178:181], v[50:53]
	v_mfma_f32_16x16x32_bf16 v[38:41], v[162:165], v[186:189], v[38:41]
	v_mfma_f32_16x16x32_bf16 v[34:37], v[170:173], v[186:189], v[34:37]
	v_mfma_f32_16x16x32_bf16 v[22:25], v[162:165], v[194:197], v[22:25]
	v_mfma_f32_16x16x32_bf16 v[18:21], v[170:173], v[194:197], v[18:21]
	v_mfma_f32_16x16x32_bf16 v[4:7], v[162:165], v[202:205], v[4:7]
	v_mfma_f32_16x16x32_bf16 v[0:3], v[170:173], v[202:205], v[0:3]
	v_mfma_f32_16x16x32_bf16 v[54:57], v[166:169], v[182:185], v[54:57]
	v_mfma_f32_16x16x32_bf16 v[50:53], v[174:177], v[182:185], v[50:53]
	v_mfma_f32_16x16x32_bf16 v[38:41], v[166:169], v[190:193], v[38:41]
	v_mfma_f32_16x16x32_bf16 v[34:37], v[174:177], v[190:193], v[34:37]
	v_mfma_f32_16x16x32_bf16 v[22:25], v[166:169], v[198:201], v[22:25]
	v_mfma_f32_16x16x32_bf16 v[18:21], v[174:177], v[198:201], v[18:21]
	v_mfma_f32_16x16x32_bf16 v[4:7], v[166:169], v[206:209], v[4:7]
	v_mfma_f32_16x16x32_bf16 v[0:3], v[174:177], v[206:209], v[0:3]
	s_barrier
	s_setprio 0
	s_add_i32 s82, s82, 2
	s_add_u32 s24, s24, 0x10000
	s_addc_u32 s25, s25, 0
	s_add_u32 s0, s0, 0x10000
	s_addc_u32 s1, s1, 0
	v_add_u32_e32 v212, 0x10000, v157
.LBB0_848:
	s_add_u32 s16, s24, 0x4000
	s_addc_u32 s17, s25, 0
	s_cmpk_eq_i32 s82, 0xfc
	s_cselect_b32 s36, s73, s16
	s_cselect_b32 s37, s11, s17
	s_cselect_b32 s16, s78, s0
	s_cselect_b32 s17, s15, s1
	s_add_u32 s26, s36, 0x8000
	s_addc_u32 s27, s37, 0
	s_add_i32 s83, 0, 0x10000
	s_add_i32 s94, 0, 0x14000
	ds_read_b128 v[130:133], v212
	ds_read_b128 v[134:137], v212 offset:1024
	ds_read_b128 v[148:151], v212 offset:2048
	ds_read_b128 v[152:155], v212 offset:3072
	ds_read_b128 v[162:165], v212 offset:16384
	ds_read_b128 v[166:169], v212 offset:17408
	ds_read_b128 v[170:173], v212 offset:18432
	ds_read_b128 v[174:177], v212 offset:19456
	s_add_i32 m0, s39, 0xc000
	ds_read_b128 v[178:181], v161
	ds_read_b128 v[182:185], v161 offset:1024
	ds_read_b128 v[186:189], v161 offset:2048
	ds_read_b128 v[190:193], v161 offset:3072
	ds_read_b128 v[194:197], v161 offset:4096
	ds_read_b128 v[198:201], v161 offset:5120
	ds_read_b128 v[202:205], v161 offset:6144
	ds_read_b128 v[206:209], v161 offset:7168
	global_load_lds_dwordx4 v144, s[24:25]
	s_add_i32 m0, s39, 0xe000
	s_nop 0
	global_load_lds_dwordx4 v146, s[24:25]
	s_waitcnt vmcnt(8)
	s_waitcnt lgkmcnt(0)
	s_nop 0
	s_setprio 1
	s_barrier
; #define PG8_STAGEA(bufoff, gbase, voff) PG8_STAGE_X(bufoff, gbase, voff, AUXA)
; #define PG8_STAGEB(bufoff, gbase, voff) PG8_STAGE_X(bufoff, gbase, voff, AUXB)
; #define PG8_LDA(dst, b, h) do { _Pragma("unroll") for (int m = 0; m < 4; ++m) _Pragma("unroll") for (int k = 0; k < 2; ++k) dst[m][k] = *(const PG8_LAS bf16x8*)(lds + PG8_SA(b, h) + aoff + m * 2048 + k * 1024); } while (0)
; #define PG8_MMA(ai, bj, At, Bt) do { if (GEMM_PRIO_MODE == 0) __builtin_amdgcn_s_setprio(1); PG8_MMA_LOOPS \
;         acc[ai][bj][m][n] = __builtin_amdgcn_mfma_f32_16x16x32_bf16(Bt[n][k], At[m][k], acc[ai][bj][m][n], 0, 0, 0); if (GEMM_PRIO_MODE == 0) __builtin_amdgcn_s_setprio(0); } while (0)
; #define PG8_WAIT_V(n) asm volatile("s_waitcnt vmcnt(" #n ")" ::: "memory")
; #define PG8_WAIT_VR(n, nr, flag) asm volatile("s_cmp_eq_u32 %0, 0\n\ts_cbranch_scc1 .Lpg8s%=\n\ts_waitcnt vmcnt(" #nr ")\n\ts_branch .Lpg8d%=\n.Lpg8s%=:\n\ts_waitcnt vmcnt(" #n ")\n.Lpg8d%=:" :: "s"(flag) : "memory", "scc")
; #define PG8_WAIT_L(n) asm volatile("s_waitcnt lgkmcnt(" #n ")" ::: "memory")
; #define PG8_BAR __builtin_amdgcn_s_barrier()
; #define PG8_SCHED __builtin_amdgcn_sched_barrier(0)
;     ...
;             PG8_WAIT_V(8); PG8_WAIT_L(0); PG8_BAR; PG8_MMA(0, 0, At, B0); PG8_MMA(0, 1, At, B1); PG8_BAR; PG8_SCHED;
;     ...
;             PG8_LDA(At, 0, 1); PG8_STAGEB(PG8_SB(0, 0), b2, voffB); PG8_STAGEB(PG8_SB(0, 1), b2 + hstepB, voffB); PG8_STAGEA(PG8_SA(0, 0), a2, voffA);
;     ...
;             PG8_WAIT_VR(8, 24, relax); PG8_WAIT_L(0); PG8_BAR; PG8_MMA(1, 0, At, B0); PG8_MMA(1, 1, At, B1); PG8_BAR; PG8_SCHED;
;     ...
;             PG8_WAIT_V(8); PG8_WAIT_L(0); PG8_BAR; PG8_MMA(1, 0, At, B0); PG8_MMA(1, 1, At, B1); PG8_BAR; PG8_SCHED;
	v_mfma_f32_16x16x32_bf16 v[126:129], v[130:133], v[178:181], v[126:129]
	v_mfma_f32_16x16x32_bf16 v[122:125], v[148:151], v[178:181], v[122:125]
	v_mfma_f32_16x16x32_bf16 v[110:113], v[130:133], v[186:189], v[110:113]
	v_mfma_f32_16x16x32_bf16 v[106:109], v[148:151], v[186:189], v[106:109]
	v_mfma_f32_16x16x32_bf16 v[94:97], v[130:133], v[194:197], v[94:97]
	v_mfma_f32_16x16x32_bf16 v[90:93], v[148:151], v[194:197], v[90:93]
	v_mfma_f32_16x16x32_bf16 v[78:81], v[130:133], v[202:205], v[78:81]
	v_mfma_f32_16x16x32_bf16 v[74:77], v[148:151], v[202:205], v[74:77]
	v_mfma_f32_16x16x32_bf16 v[126:129], v[134:137], v[182:185], v[126:129]
	v_mfma_f32_16x16x32_bf16 v[122:125], v[152:155], v[182:185], v[122:125]
	v_mfma_f32_16x16x32_bf16 v[110:113], v[134:137], v[190:193], v[110:113]
	v_mfma_f32_16x16x32_bf16 v[106:109], v[152:155], v[190:193], v[106:109]
	v_mfma_f32_16x16x32_bf16 v[94:97], v[134:137], v[198:201], v[94:97]
	v_mfma_f32_16x16x32_bf16 v[90:93], v[152:155], v[198:201], v[90:93]
	v_mfma_f32_16x16x32_bf16 v[78:81], v[134:137], v[206:209], v[78:81]
	v_mfma_f32_16x16x32_bf16 v[74:77], v[152:155], v[206:209], v[74:77]
	v_mfma_f32_16x16x32_bf16 v[118:121], v[162:165], v[178:181], v[118:121]
	v_mfma_f32_16x16x32_bf16 v[114:117], v[170:173], v[178:181], v[114:117]
	v_mfma_f32_16x16x32_bf16 v[102:105], v[162:165], v[186:189], v[102:105]
	v_mfma_f32_16x16x32_bf16 v[98:101], v[170:173], v[186:189], v[98:101]
	v_mfma_f32_16x16x32_bf16 v[86:89], v[162:165], v[194:197], v[86:89]
	v_mfma_f32_16x16x32_bf16 v[82:85], v[170:173], v[194:197], v[82:85]
	v_mfma_f32_16x16x32_bf16 v[70:73], v[162:165], v[202:205], v[70:73]
	v_mfma_f32_16x16x32_bf16 v[66:69], v[170:173], v[202:205], v[66:69]
	v_mfma_f32_16x16x32_bf16 v[118:121], v[166:169], v[182:185], v[118:121]
	v_mfma_f32_16x16x32_bf16 v[114:117], v[174:177], v[182:185], v[114:117]
	v_mfma_f32_16x16x32_bf16 v[102:105], v[166:169], v[190:193], v[102:105]
	v_mfma_f32_16x16x32_bf16 v[98:101], v[174:177], v[190:193], v[98:101]
	v_mfma_f32_16x16x32_bf16 v[86:89], v[166:169], v[198:201], v[86:89]
	v_mfma_f32_16x16x32_bf16 v[82:85], v[174:177], v[198:201], v[82:85]
	v_mfma_f32_16x16x32_bf16 v[70:73], v[166:169], v[206:209], v[70:73]
	v_mfma_f32_16x16x32_bf16 v[66:69], v[174:177], v[206:209], v[66:69]
	s_barrier
	s_setprio 0
	s_add_i32 s83, s83, s38
	s_mov_b32 m0, s83
	ds_read_b128 v[178:181], v161 offset:16384
	ds_read_b128 v[182:185], v161 offset:17408
	ds_read_b128 v[186:189], v161 offset:18432
	ds_read_b128 v[190:193], v161 offset:19456
	ds_read_b128 v[194:197], v161 offset:20480
	ds_read_b128 v[198:201], v161 offset:21504
	ds_read_b128 v[202:205], v161 offset:22528
	ds_read_b128 v[206:209], v161 offset:23552
	global_load_lds_dwordx4 v16, s[16:17]
	s_add_i32 m0, s83, 0x2000
	s_add_u32 s90, s16, 0x4000
	s_addc_u32 s91, s17, 0
	s_add_i32 s83, s94, s38
	global_load_lds_dwordx4 v138, s[16:17]
	s_mov_b32 m0, s83
	s_nop 0
	global_load_lds_dwordx4 v16, s[90:91]
	s_add_i32 m0, s83, 0x2000
	s_nop 0
	global_load_lds_dwordx4 v138, s[90:91]
	s_mov_b32 m0, s39
	s_nop 0
	global_load_lds_dwordx4 v142, s[36:37]
	s_mov_b32 m0, s40
	s_nop 0
	global_load_lds_dwordx4 v140, s[36:37]
	s_waitcnt vmcnt(8)
	s_waitcnt lgkmcnt(0)
	s_nop 0
	s_setprio 1
	s_barrier
	v_mfma_f32_16x16x32_bf16 v[62:65], v[130:133], v[178:181], v[62:65]
	v_mfma_f32_16x16x32_bf16 v[58:61], v[148:151], v[178:181], v[58:61]
	v_mfma_f32_16x16x32_bf16 v[46:49], v[130:133], v[186:189], v[46:49]
	v_mfma_f32_16x16x32_bf16 v[42:45], v[148:151], v[186:189], v[42:45]
	v_mfma_f32_16x16x32_bf16 v[30:33], v[130:133], v[194:197], v[30:33]
	v_mfma_f32_16x16x32_bf16 v[26:29], v[148:151], v[194:197], v[26:29]
	v_mfma_f32_16x16x32_bf16 v[12:15], v[130:133], v[202:205], v[12:15]
	v_mfma_f32_16x16x32_bf16 v[8:11], v[148:151], v[202:205], v[8:11]
	v_mfma_f32_16x16x32_bf16 v[62:65], v[134:137], v[182:185], v[62:65]
	v_mfma_f32_16x16x32_bf16 v[58:61], v[152:155], v[182:185], v[58:61]
	v_mfma_f32_16x16x32_bf16 v[46:49], v[134:137], v[190:193], v[46:49]
	v_mfma_f32_16x16x32_bf16 v[42:45], v[152:155], v[190:193], v[42:45]
	v_mfma_f32_16x16x32_bf16 v[30:33], v[134:137], v[198:201], v[30:33]
	v_mfma_f32_16x16x32_bf16 v[26:29], v[152:155], v[198:201], v[26:29]
	v_mfma_f32_16x16x32_bf16 v[12:15], v[134:137], v[206:209], v[12:15]
	v_mfma_f32_16x16x32_bf16 v[8:11], v[152:155], v[206:209], v[8:11]
	v_mfma_f32_16x16x32_bf16 v[54:57], v[162:165], v[178:181], v[54:57]
	v_mfma_f32_16x16x32_bf16 v[50:53], v[170:173], v[178:181], v[50:53]
	v_mfma_f32_16x16x32_bf16 v[38:41], v[162:165], v[186:189], v[38:41]
	v_mfma_f32_16x16x32_bf16 v[34:37], v[170:173], v[186:189], v[34:37]
	v_mfma_f32_16x16x32_bf16 v[22:25], v[162:165], v[194:197], v[22:25]
	v_mfma_f32_16x16x32_bf16 v[18:21], v[170:173], v[194:197], v[18:21]
	v_mfma_f32_16x16x32_bf16 v[4:7], v[162:165], v[202:205], v[4:7]
	v_mfma_f32_16x16x32_bf16 v[0:3], v[170:173], v[202:205], v[0:3]
	v_mfma_f32_16x16x32_bf16 v[54:57], v[166:169], v[182:185], v[54:57]
	v_mfma_f32_16x16x32_bf16 v[50:53], v[174:177], v[182:185], v[50:53]
	v_mfma_f32_16x16x32_bf16 v[38:41], v[166:169], v[190:193], v[38:41]
	v_mfma_f32_16x16x32_bf16 v[34:37], v[174:177], v[190:193], v[34:37]
	v_mfma_f32_16x16x32_bf16 v[22:25], v[166:169], v[198:201], v[22:25]
	v_mfma_f32_16x16x32_bf16 v[18:21], v[174:177], v[198:201], v[18:21]
	v_mfma_f32_16x16x32_bf16 v[4:7], v[166:169], v[206:209], v[4:7]
	v_mfma_f32_16x16x32_bf16 v[0:3], v[174:177], v[206:209], v[0:3]
	s_barrier
; #define PG8_STAGEA(bufoff, gbase, voff) PG8_STAGE_X(bufoff, gbase, voff, AUXA)
; #define PG8_STAGEB(bufoff, gbase, voff) PG8_STAGE_X(bufoff, gbase, voff, AUXB)
; #define PG8_LDA(dst, b, h) do { _Pragma("unroll") for (int m = 0; m < 4; ++m) _Pragma("unroll") for (int k = 0; k < 2; ++k) dst[m][k] = *(const PG8_LAS bf16x8*)(lds + PG8_SA(b, h) + aoff + m * 2048 + k * 1024); } while (0)
; #define PG8_LDB(dst, b, h) do { _Pragma("unroll") for (int n = 0; n < 2; ++n) _Pragma("unroll") for (int k = 0; k < 2; ++k) dst[n][k] = *(const PG8_LAS bf16x8*)(lds + PG8_SB(b, h) + boff + n * 2048 + k * 1024); } while (0)
; #define PG8_MMA(ai, bj, At, Bt) do { if (GEMM_PRIO_MODE == 0) __builtin_amdgcn_s_setprio(1); PG8_MMA_LOOPS \
;         acc[ai][bj][m][n] = __builtin_amdgcn_mfma_f32_16x16x32_bf16(Bt[n][k], At[m][k], acc[ai][bj][m][n], 0, 0, 0); if (GEMM_PRIO_MODE == 0) __builtin_amdgcn_s_setprio(0); } while (0)
; #define PG8_WAIT_V(n) asm volatile("s_waitcnt vmcnt(" #n ")" ::: "memory")
; #define PG8_WAIT_L(n) asm volatile("s_waitcnt lgkmcnt(" #n ")" ::: "memory")
; #define PG8_BAR __builtin_amdgcn_s_barrier()
; #define PG8_SCHED __builtin_amdgcn_sched_barrier(0)
;     ...
;             PG8_LDB(B0, 1, 0); PG8_LDB(B1, 1, 1); PG8_SCHED; PG8_LDA(At, 1, 0); PG8_STAGEA(PG8_SA(0, 1), a2 + hstepA, voffA);
;             PG8_WAIT_V(8); PG8_WAIT_L(0); PG8_BAR; PG8_MMA(0, 0, At, B0); PG8_MMA(0, 1, At, B1); PG8_BAR; PG8_SCHED;
;             PG8_LDA(At, 1, 1); PG8_STAGEB(PG8_SB(1, 0), b3, voffB); PG8_STAGEB(PG8_SB(1, 1), b3 + hstepB, voffB); PG8_STAGEA(PG8_SA(1, 0), a3, voffA);
;             PG8_WAIT_V(8); PG8_WAIT_L(0); PG8_BAR; PG8_MMA(1, 0, At, B0); PG8_MMA(1, 1, At, B1); PG8_BAR; PG8_SCHED;
	s_setprio 0
	s_add_i32 s83, 0, 0x18000
	s_add_i32 s90, 0, 0x1c000
	ds_read_b128 v[130:133], v212 offset:32768
	ds_read_b128 v[134:137], v212 offset:33792
	ds_read_b128 v[148:151], v212 offset:34816
	ds_read_b128 v[152:155], v212 offset:35840
	ds_read_b128 v[162:165], v212 offset:49152
	ds_read_b128 v[166:169], v212 offset:50176
	ds_read_b128 v[170:173], v212 offset:51200
	ds_read_b128 v[174:177], v212 offset:52224
	s_add_u32 s36, s36, 0x4000
	s_addc_u32 s37, s37, 0
	s_mov_b32 m0, s41
	ds_read_b128 v[178:181], v161 offset:32768
	ds_read_b128 v[182:185], v161 offset:33792
	ds_read_b128 v[186:189], v161 offset:34816
	ds_read_b128 v[190:193], v161 offset:35840
	ds_read_b128 v[194:197], v161 offset:36864
	ds_read_b128 v[198:201], v161 offset:37888
	ds_read_b128 v[202:205], v161 offset:38912
	ds_read_b128 v[206:209], v161 offset:39936
	global_load_lds_dwordx4 v142, s[36:37]
	s_mov_b32 m0, s42
	s_nop 0
	global_load_lds_dwordx4 v140, s[36:37]
	s_waitcnt vmcnt(8)
	s_waitcnt lgkmcnt(0)
	s_setprio 1
	s_barrier
	v_mfma_f32_16x16x32_bf16 v[126:129], v[130:133], v[178:181], v[126:129]
	v_mfma_f32_16x16x32_bf16 v[122:125], v[148:151], v[178:181], v[122:125]
	v_mfma_f32_16x16x32_bf16 v[110:113], v[130:133], v[186:189], v[110:113]
	v_mfma_f32_16x16x32_bf16 v[106:109], v[148:151], v[186:189], v[106:109]
	v_mfma_f32_16x16x32_bf16 v[94:97], v[130:133], v[194:197], v[94:97]
	v_mfma_f32_16x16x32_bf16 v[90:93], v[148:151], v[194:197], v[90:93]
	v_mfma_f32_16x16x32_bf16 v[78:81], v[130:133], v[202:205], v[78:81]
	v_mfma_f32_16x16x32_bf16 v[74:77], v[148:151], v[202:205], v[74:77]
	v_mfma_f32_16x16x32_bf16 v[126:129], v[134:137], v[182:185], v[126:129]
	v_mfma_f32_16x16x32_bf16 v[122:125], v[152:155], v[182:185], v[122:125]
	v_mfma_f32_16x16x32_bf16 v[110:113], v[134:137], v[190:193], v[110:113]
	v_mfma_f32_16x16x32_bf16 v[106:109], v[152:155], v[190:193], v[106:109]
	v_mfma_f32_16x16x32_bf16 v[94:97], v[134:137], v[198:201], v[94:97]
	v_mfma_f32_16x16x32_bf16 v[90:93], v[152:155], v[198:201], v[90:93]
	v_mfma_f32_16x16x32_bf16 v[78:81], v[134:137], v[206:209], v[78:81]
	v_mfma_f32_16x16x32_bf16 v[74:77], v[152:155], v[206:209], v[74:77]
	v_mfma_f32_16x16x32_bf16 v[118:121], v[162:165], v[178:181], v[118:121]
	v_mfma_f32_16x16x32_bf16 v[114:117], v[170:173], v[178:181], v[114:117]
	v_mfma_f32_16x16x32_bf16 v[102:105], v[162:165], v[186:189], v[102:105]
	v_mfma_f32_16x16x32_bf16 v[98:101], v[170:173], v[186:189], v[98:101]
	v_mfma_f32_16x16x32_bf16 v[86:89], v[162:165], v[194:197], v[86:89]
	v_mfma_f32_16x16x32_bf16 v[82:85], v[170:173], v[194:197], v[82:85]
	v_mfma_f32_16x16x32_bf16 v[70:73], v[162:165], v[202:205], v[70:73]
	v_mfma_f32_16x16x32_bf16 v[66:69], v[170:173], v[202:205], v[66:69]
	v_mfma_f32_16x16x32_bf16 v[118:121], v[166:169], v[182:185], v[118:121]
	v_mfma_f32_16x16x32_bf16 v[114:117], v[174:177], v[182:185], v[114:117]
	v_mfma_f32_16x16x32_bf16 v[102:105], v[166:169], v[190:193], v[102:105]
	v_mfma_f32_16x16x32_bf16 v[98:101], v[174:177], v[190:193], v[98:101]
	v_mfma_f32_16x16x32_bf16 v[86:89], v[166:169], v[198:201], v[86:89]
	v_mfma_f32_16x16x32_bf16 v[82:85], v[174:177], v[198:201], v[82:85]
	v_mfma_f32_16x16x32_bf16 v[70:73], v[166:169], v[206:209], v[70:73]
	v_mfma_f32_16x16x32_bf16 v[66:69], v[174:177], v[206:209], v[66:69]
	s_barrier
	s_setprio 0
	s_add_u32 s36, s16, 0x8000
	s_addc_u32 s37, s17, 0
	s_add_i32 s83, s83, s38
	s_mov_b32 m0, s83
	ds_read_b128 v[178:181], v161 offset:49152
	ds_read_b128 v[182:185], v161 offset:50176
	ds_read_b128 v[186:189], v161 offset:51200
	ds_read_b128 v[190:193], v161 offset:52224
	ds_read_b128 v[194:197], v161 offset:53248
	ds_read_b128 v[198:201], v161 offset:54272
	ds_read_b128 v[202:205], v161 offset:55296
	ds_read_b128 v[206:209], v161 offset:56320
	global_load_lds_dwordx4 v16, s[36:37]
	s_add_i32 m0, s83, 0x2000
	s_add_u32 s16, s16, 0xc000
	s_addc_u32 s17, s17, 0
	global_load_lds_dwordx4 v138, s[36:37]
	s_add_i32 s36, s90, s38
	s_mov_b32 m0, s36
	s_nop 0
	global_load_lds_dwordx4 v16, s[16:17]
	s_add_i32 m0, s36, 0x2000
	s_nop 0
	global_load_lds_dwordx4 v138, s[16:17]
	s_mov_b32 m0, s50
	s_nop 0
	global_load_lds_dwordx4 v142, s[26:27]
	s_mov_b32 m0, s51
	s_nop 0
	global_load_lds_dwordx4 v140, s[26:27]
	s_waitcnt vmcnt(8)
	s_waitcnt lgkmcnt(0)
	s_nop 0
	s_nop 0
	s_setprio 1
	s_barrier
	v_mfma_f32_16x16x32_bf16 v[62:65], v[130:133], v[178:181], v[62:65]
	v_mfma_f32_16x16x32_bf16 v[58:61], v[148:151], v[178:181], v[58:61]
	v_mfma_f32_16x16x32_bf16 v[46:49], v[130:133], v[186:189], v[46:49]
	v_mfma_f32_16x16x32_bf16 v[42:45], v[148:151], v[186:189], v[42:45]
	v_mfma_f32_16x16x32_bf16 v[30:33], v[130:133], v[194:197], v[30:33]
	v_mfma_f32_16x16x32_bf16 v[26:29], v[148:151], v[194:197], v[26:29]
	v_mfma_f32_16x16x32_bf16 v[12:15], v[130:133], v[202:205], v[12:15]
	v_mfma_f32_16x16x32_bf16 v[8:11], v[148:151], v[202:205], v[8:11]
	v_mfma_f32_16x16x32_bf16 v[62:65], v[134:137], v[182:185], v[62:65]
	v_mfma_f32_16x16x32_bf16 v[58:61], v[152:155], v[182:185], v[58:61]
	v_mfma_f32_16x16x32_bf16 v[46:49], v[134:137], v[190:193], v[46:49]
	v_mfma_f32_16x16x32_bf16 v[42:45], v[152:155], v[190:193], v[42:45]
	v_mfma_f32_16x16x32_bf16 v[30:33], v[134:137], v[198:201], v[30:33]
	v_mfma_f32_16x16x32_bf16 v[26:29], v[152:155], v[198:201], v[26:29]
	v_mfma_f32_16x16x32_bf16 v[12:15], v[134:137], v[206:209], v[12:15]
	v_mfma_f32_16x16x32_bf16 v[8:11], v[152:155], v[206:209], v[8:11]
	v_mfma_f32_16x16x32_bf16 v[54:57], v[162:165], v[178:181], v[54:57]
	v_mfma_f32_16x16x32_bf16 v[50:53], v[170:173], v[178:181], v[50:53]
	v_mfma_f32_16x16x32_bf16 v[38:41], v[162:165], v[186:189], v[38:41]
	v_mfma_f32_16x16x32_bf16 v[34:37], v[170:173], v[186:189], v[34:37]
	v_mfma_f32_16x16x32_bf16 v[22:25], v[162:165], v[194:197], v[22:25]
	v_mfma_f32_16x16x32_bf16 v[18:21], v[170:173], v[194:197], v[18:21]
	v_mfma_f32_16x16x32_bf16 v[4:7], v[162:165], v[202:205], v[4:7]
	v_mfma_f32_16x16x32_bf16 v[0:3], v[170:173], v[202:205], v[0:3]
	v_mfma_f32_16x16x32_bf16 v[54:57], v[166:169], v[182:185], v[54:57]
	v_mfma_f32_16x16x32_bf16 v[50:53], v[174:177], v[182:185], v[50:53]
	v_mfma_f32_16x16x32_bf16 v[38:41], v[166:169], v[190:193], v[38:41]
	v_mfma_f32_16x16x32_bf16 v[34:37], v[174:177], v[190:193], v[34:37]
	v_mfma_f32_16x16x32_bf16 v[22:25], v[166:169], v[198:201], v[22:25]
	v_mfma_f32_16x16x32_bf16 v[18:21], v[174:177], v[198:201], v[18:21]
	v_mfma_f32_16x16x32_bf16 v[4:7], v[166:169], v[206:209], v[4:7]
	v_mfma_f32_16x16x32_bf16 v[0:3], v[174:177], v[206:209], v[0:3]
	s_barrier
	s_setprio 0
	s_add_i32 s82, s82, 2
	s_add_u32 s24, s24, 0x10000
	s_addc_u32 s25, s25, 0
	s_add_u32 s0, s0, 0x10000
	s_addc_u32 s1, s1, 0
	s_cmpk_gt_u32 s82, 0xfd
	s_cbranch_scc0 .LBB0_848
	s_and_b64 vcc, exec, s[8:9]
	s_cbranch_vccz .LBB0_851
	s_barrier
